# GEMM residual epilogue (EpiRes) and GLU epilogue de-serialised: the 8 tile loads of each 128-row half hoisted and issued together, counted vmcnt waits instead of a vmcnt(0) drain after every load
# speedup vs baseline: 1.0012x; 1.0012x over previous
; __device__ __forceinline__ unsigned pk2(float lo, float hi) { const f32x2 v = {lo, hi}; return __builtin_bit_cast(unsigned, __builtin_convertvector(v, bf16x2_t)); }
; __device__ __forceinline__ void unpack8(u32x4 w, float* f) { f[0] = bflo(w.x); f[1] = bfhi(w.x); f[2] = bflo(w.y); f[3] = bfhi(w.y); f[4] = bflo(w.z); f[5] = bfhi(w.z); f[6] = bflo(w.w); f[7] = bfhi(w.w); }
;     __device__ __forceinline__ void operator()(const f32x4 (&acc)[2][2][4][2], const Unit& u, int wr, int wc, int fr, int fq) const {
;     ...
;             for (int m = 0; m < 4; ++m) { const int rl = wr * 64 + fr + ai * HALF + m * 16; const size_t row = (size_t)u.pm * BM + rl; float part = 0.f;
; #pragma unroll
;                 for (int bj = 0; bj < 2; ++bj) { const int col = col0 + bj * HALF; const u32x4 yw = *(const u32x4*)(YG + row * 512 + col); float y[8], o[8]; unpack8(yw, y);
;                     const f32x4 v0 = acc[ai][bj][m][0], v1 = acc[ai][bj][m][1];
; #pragma unroll
;                     for (int j = 0; j < 4; ++j) { o[j] = y[j] / (1.0f + __expf(-v0[j])); o[4 + j] = y[4 + j] / (1.0f + __expf(-v1[j])); }
; #pragma unroll
;                     for (int j = 0; j < 8; ++j) part += o[j] * o[j];
;                     u32x4 w; w.x = pk2(o[0], o[1]); w.y = pk2(o[2], o[3]); w.z = pk2(o[4], o[5]); w.w = pk2(o[6], o[7]);
.LBB0_57:
	v_xor_b32_e32 v128, 16, v163
	v_cmp_lt_i32_e32 vcc, v128, v167
	v_lshl_or_b32 v160, s21, 8, v183
	s_ashr_i32 s21, s20, 31
	v_cndmask_b32_e32 v128, v163, v128, vcc
	v_lshlrev_b32_e32 v186, 2, v128
	v_xor_b32_e32 v128, 32, v163
	v_cmp_lt_i32_e32 vcc, v128, v167
	s_lshl_b64 s[18:19], s[20:21], 8
	v_lshlrev_b32_e32 v160, 1, v160
	v_cndmask_b32_e32 v128, v163, v128, vcc
	v_lshlrev_b32_e32 v185, 2, v128
	v_lshl_add_u64 v[128:129], s[18:19], 0, v[140:141]
	v_lshlrev_b64 v[130:131], 10, v[128:129]
	v_lshlrev_b64 v[172:173], 12, v[128:129]
	v_lshl_add_u64 v[128:129], s[4:5], 0, v[130:131]
	v_lshl_add_u64 v[170:171], v[128:129], 0, v[160:161]
	s_movk_i32 s96, 0x4000
	s_mov_b32 s97, 0
	global_load_dwordx4 v[220:223], v[170:171], off
	global_load_dwordx4 v[224:227], v[170:171], off offset:256
	v_lshl_add_u64 v[192:193], v[170:171], 0, s[96:97]
	global_load_dwordx4 v[228:231], v[192:193], off
	global_load_dwordx4 v[232:235], v[192:193], off offset:256
	v_lshl_add_u64 v[192:193], v[192:193], 0, s[96:97]
	global_load_dwordx4 v[236:239], v[192:193], off
	global_load_dwordx4 v[240:243], v[192:193], off offset:256
	v_lshl_add_u64 v[192:193], v[192:193], 0, s[96:97]
	global_load_dwordx4 v[244:247], v[192:193], off
	global_load_dwordx4 v[248:251], v[192:193], off offset:256
	v_mul_f32_e32 v124, 0xbfb8aa3b, v124
	v_mul_f32_e32 v125, 0xbfb8aa3b, v125
	v_exp_f32_e32 v124, v124
	v_exp_f32_e32 v125, v125
	v_mul_f32_e32 v120, 0xbfb8aa3b, v120
	v_mul_f32_e32 v121, 0xbfb8aa3b, v121
	v_exp_f32_e32 v120, v120
	v_pk_add_f32 v[124:125], v[124:125], 1.0 op_sel_hi:[1,0]
	v_exp_f32_e32 v121, v121
	v_mul_f32_e32 v126, 0xbfb8aa3b, v126
	v_mul_f32_e32 v127, 0xbfb8aa3b, v127
	v_exp_f32_e32 v126, v126
	v_pk_add_f32 v[120:121], v[120:121], 1.0 op_sel_hi:[1,0]
	v_exp_f32_e32 v127, v127
	v_mul_f32_e32 v122, 0xbfb8aa3b, v122
	v_mul_f32_e32 v123, 0xbfb8aa3b, v123
	v_exp_f32_e32 v122, v122
	v_pk_add_f32 v[126:127], v[126:127], 1.0 op_sel_hi:[1,0]
	v_exp_f32_e32 v123, v123
	v_mul_f32_e32 v116, 0xbfb8aa3b, v116
	v_mul_f32_e32 v117, 0xbfb8aa3b, v117
	v_exp_f32_e32 v116, v116
	v_pk_add_f32 v[122:123], v[122:123], 1.0 op_sel_hi:[1,0]
	v_exp_f32_e32 v117, v117
	v_mul_f32_e32 v112, 0xbfb8aa3b, v112
	v_mul_f32_e32 v113, 0xbfb8aa3b, v113
	v_exp_f32_e32 v112, v112
	v_pk_add_f32 v[116:117], v[116:117], 1.0 op_sel_hi:[1,0]
	v_exp_f32_e32 v113, v113
	v_mul_f32_e32 v118, 0xbfb8aa3b, v118
	v_mul_f32_e32 v119, 0xbfb8aa3b, v119
	v_exp_f32_e32 v118, v118
	v_pk_add_f32 v[112:113], v[112:113], 1.0 op_sel_hi:[1,0]
	v_exp_f32_e32 v119, v119
	v_mul_f32_e32 v114, 0xbfb8aa3b, v114
	v_mul_f32_e32 v115, 0xbfb8aa3b, v115
	v_exp_f32_e32 v114, v114
	v_pk_add_f32 v[118:119], v[118:119], 1.0 op_sel_hi:[1,0]
	v_exp_f32_e32 v115, v115
	s_waitcnt vmcnt(7)
	v_mov_b32_e32 v128, v220
	v_mov_b32_e32 v129, v221
	v_mov_b32_e32 v130, v222
	v_mov_b32_e32 v131, v223
	v_lshlrev_b32_e32 v168, 16, v128
	v_and_b32_e32 v128, 0xffff0000, v128
	v_div_scale_f32 v169, s[2:3], v125, v125, v128
	v_rcp_f32_e32 v176, v169
	v_pk_add_f32 v[114:115], v[114:115], 1.0 op_sel_hi:[1,0]
	v_fma_f32 v177, -v169, v176, 1.0
	v_fmac_f32_e32 v176, v177, v176
	v_div_scale_f32 v177, vcc, v128, v125, v128
	v_mul_f32_e32 v178, v177, v176
	v_fma_f32 v179, -v169, v178, v177
	v_fmac_f32_e32 v178, v179, v176
	v_fma_f32 v169, -v169, v178, v177
	v_div_fmas_f32 v169, v169, v176, v178
	v_div_fixup_f32 v125, v169, v125, v128
	v_div_scale_f32 v128, s[2:3], v124, v124, v168
	v_rcp_f32_e32 v169, v128
	s_nop 0
	v_fma_f32 v176, -v128, v169, 1.0
	v_fmac_f32_e32 v169, v176, v169
	v_div_scale_f32 v176, vcc, v168, v124, v168
	v_mul_f32_e32 v177, v176, v169
	v_fma_f32 v178, -v128, v177, v176
	v_fmac_f32_e32 v177, v178, v169
	v_fma_f32 v128, -v128, v177, v176
	v_div_fmas_f32 v128, v128, v169, v177
	v_div_fixup_f32 v124, v128, v124, v168
	v_lshlrev_b32_e32 v128, 16, v130
	v_and_b32_e32 v130, 0xffff0000, v130
	v_div_scale_f32 v168, s[2:3], v121, v121, v130
	v_rcp_f32_e32 v169, v168
	v_cvt_pk_bf16_f32 v188, v124, v125
	v_fma_f32 v176, -v168, v169, 1.0
	v_fmac_f32_e32 v169, v176, v169
	v_div_scale_f32 v176, vcc, v130, v121, v130
	v_mul_f32_e32 v177, v176, v169
	v_fma_f32 v178, -v168, v177, v176
	v_fmac_f32_e32 v177, v178, v169
	v_fma_f32 v168, -v168, v177, v176
	v_div_fmas_f32 v168, v168, v169, v177
	v_div_fixup_f32 v121, v168, v121, v130
	v_div_scale_f32 v130, s[2:3], v120, v120, v128
	v_rcp_f32_e32 v168, v130
	s_nop 0
	v_fma_f32 v169, -v130, v168, 1.0
	v_fmac_f32_e32 v168, v169, v168
	v_div_scale_f32 v169, vcc, v128, v120, v128
	v_mul_f32_e32 v176, v169, v168
	v_fma_f32 v177, -v130, v176, v169
	v_fmac_f32_e32 v176, v177, v168
	v_fma_f32 v130, -v130, v176, v169
	v_div_fmas_f32 v130, v130, v168, v176
	v_div_fixup_f32 v120, v130, v120, v128
	v_lshlrev_b32_e32 v128, 16, v129
	v_and_b32_e32 v129, 0xffff0000, v129
	v_div_scale_f32 v130, s[2:3], v127, v127, v129
	v_rcp_f32_e32 v168, v130
	v_cvt_pk_bf16_f32 v190, v120, v121
	v_fma_f32 v169, -v130, v168, 1.0
	v_fmac_f32_e32 v168, v169, v168
	v_div_scale_f32 v169, vcc, v129, v127, v129
	v_mul_f32_e32 v176, v169, v168
	v_fma_f32 v177, -v130, v176, v169
	v_fmac_f32_e32 v176, v177, v168
	v_fma_f32 v130, -v130, v176, v169
	v_div_fmas_f32 v130, v130, v168, v176
	v_div_fixup_f32 v177, v130, v127, v129
	v_div_scale_f32 v127, s[2:3], v126, v126, v128
	v_rcp_f32_e32 v129, v127
	s_nop 0
	v_fma_f32 v130, -v127, v129, 1.0
	v_fmac_f32_e32 v129, v130, v129
	v_div_scale_f32 v130, vcc, v128, v126, v128
	v_mul_f32_e32 v168, v130, v129
	v_fma_f32 v169, -v127, v168, v130
	v_fmac_f32_e32 v168, v169, v129
	v_fma_f32 v127, -v127, v168, v130
	v_div_fmas_f32 v127, v127, v129, v168
	v_div_fixup_f32 v176, v127, v126, v128
	v_and_b32_e32 v127, 0xffff0000, v131
; __device__ __forceinline__ unsigned pk2(float lo, float hi) { const f32x2 v = {lo, hi}; return __builtin_bit_cast(unsigned, __builtin_convertvector(v, bf16x2_t)); }
; __device__ __forceinline__ void unpack8(u32x4 w, float* f) { f[0] = bflo(w.x); f[1] = bfhi(w.x); f[2] = bflo(w.y); f[3] = bfhi(w.y); f[4] = bflo(w.z); f[5] = bfhi(w.z); f[6] = bflo(w.w); f[7] = bfhi(w.w); }
;     __device__ __forceinline__ void operator()(const f32x4 (&acc)[2][2][4][2], const Unit& u, int wr, int wc, int fr, int fq) const {
;     ...
;                 for (int bj = 0; bj < 2; ++bj) { const int col = col0 + bj * HALF; const u32x4 yw = *(const u32x4*)(YG + row * 512 + col); float y[8], o[8]; unpack8(yw, y);
;                     const f32x4 v0 = acc[ai][bj][m][0], v1 = acc[ai][bj][m][1];
; #pragma unroll
;                     for (int j = 0; j < 4; ++j) { o[j] = y[j] / (1.0f + __expf(-v0[j])); o[4 + j] = y[4 + j] / (1.0f + __expf(-v1[j])); }
; #pragma unroll
;                     for (int j = 0; j < 8; ++j) part += o[j] * o[j];
;                     u32x4 w; w.x = pk2(o[0], o[1]); w.y = pk2(o[2], o[3]); w.z = pk2(o[4], o[5]); w.w = pk2(o[6], o[7]);
;                     *(u32x4*)(YC + row * D + col) = w; }
;                 part += __shfl_xor(part, 16); part += __shfl_xor(part, 32);
;                 if (fq == 0) (void)__hip_atomic_fetch_add(rss + rl, part, __ATOMIC_RELAXED, __HIP_MEMORY_SCOPE_WORKGROUP); }
	v_div_scale_f32 v128, s[2:3], v123, v123, v127
	v_rcp_f32_e32 v129, v128
	v_lshlrev_b32_e32 v126, 16, v131
	v_cvt_pk_bf16_f32 v189, v176, v177
	v_fma_f32 v130, -v128, v129, 1.0
	v_fmac_f32_e32 v129, v130, v129
	v_div_scale_f32 v130, vcc, v127, v123, v127
	v_mul_f32_e32 v131, v130, v129
	v_fma_f32 v168, -v128, v131, v130
	v_fmac_f32_e32 v131, v168, v129
	v_fma_f32 v128, -v128, v131, v130
	v_div_fmas_f32 v128, v128, v129, v131
	v_div_fixup_f32 v123, v128, v123, v127
	v_div_scale_f32 v127, s[2:3], v122, v122, v126
	v_rcp_f32_e32 v128, v127
	v_pk_mul_f32 v[168:169], v[124:125], v[124:125]
	v_fma_f32 v129, -v127, v128, 1.0
	v_fmac_f32_e32 v128, v129, v128
	v_div_scale_f32 v129, vcc, v126, v122, v126
	v_mul_f32_e32 v130, v129, v128
	v_fma_f32 v131, -v127, v130, v129
	v_fmac_f32_e32 v130, v131, v128
	v_fma_f32 v127, -v127, v130, v129
	v_div_fmas_f32 v127, v127, v128, v130
	v_div_fixup_f32 v122, v127, v122, v126
	v_pk_mul_f32 v[128:129], v[120:121], v[120:121]
	v_lshl_add_u64 v[120:121], s[94:95], 0, v[172:173]
	v_pk_mul_f32 v[126:127], v[122:123], v[122:123]
	v_cvt_pk_bf16_f32 v191, v122, v123
	v_lshl_add_u64 v[124:125], v[120:121], 0, v[160:161]
	v_pk_mul_f32 v[130:131], v[176:177], v[176:177]
	v_add_f32_e32 v168, v168, v169
	v_add_f32_e32 v130, v130, v168
	v_add_f32_e32 v130, v131, v130
	v_add_f32_e32 v128, v128, v130
	v_add_f32_e32 v128, v129, v128
	v_add_f32_e32 v126, v126, v128
	v_add_f32_e32 v126, v127, v126
	global_store_dwordx4 v[124:125], v[188:191], off
	s_waitcnt vmcnt(7)
	v_mov_b32_e32 v120, v224
	v_mov_b32_e32 v121, v225
	v_mov_b32_e32 v122, v226
	v_mov_b32_e32 v123, v227
	v_lshlrev_b32_e32 v170, 16, v120
	v_and_b32_e32 v120, 0xffff0000, v120
	v_div_scale_f32 v171, s[2:3], v117, v117, v120
	v_rcp_f32_e32 v172, v171
	s_nop 0
	v_fma_f32 v173, -v171, v172, 1.0
	v_fmac_f32_e32 v172, v173, v172
	v_div_scale_f32 v173, vcc, v120, v117, v120
	v_mul_f32_e32 v176, v173, v172
	v_fma_f32 v177, -v171, v176, v173
	v_fmac_f32_e32 v176, v177, v172
	v_fma_f32 v171, -v171, v176, v173
	v_div_fmas_f32 v171, v171, v172, v176
	v_div_fixup_f32 v117, v171, v117, v120
	v_div_scale_f32 v120, s[2:3], v116, v116, v170
	v_rcp_f32_e32 v171, v120
	s_nop 0
	v_fma_f32 v172, -v120, v171, 1.0
	v_fmac_f32_e32 v171, v172, v171
	v_div_scale_f32 v172, vcc, v170, v116, v170
	v_mul_f32_e32 v173, v172, v171
	v_fma_f32 v176, -v120, v173, v172
	v_fmac_f32_e32 v173, v176, v171
	v_fma_f32 v120, -v120, v173, v172
	v_div_fmas_f32 v120, v120, v171, v173
	v_div_fixup_f32 v116, v120, v116, v170
	v_lshlrev_b32_e32 v120, 16, v122
	v_and_b32_e32 v122, 0xffff0000, v122
	v_div_scale_f32 v170, s[2:3], v113, v113, v122
	v_rcp_f32_e32 v171, v170
	s_nop 0
	v_fma_f32 v172, -v170, v171, 1.0
	v_fmac_f32_e32 v171, v172, v171
	v_div_scale_f32 v172, vcc, v122, v113, v122
	v_mul_f32_e32 v173, v172, v171
	v_fma_f32 v176, -v170, v173, v172
	v_fmac_f32_e32 v173, v176, v171
	v_fma_f32 v170, -v170, v173, v172
	v_div_fmas_f32 v170, v170, v171, v173
	v_div_fixup_f32 v113, v170, v113, v122
	v_div_scale_f32 v122, s[2:3], v112, v112, v120
	v_rcp_f32_e32 v170, v122
	s_nop 0
	v_fma_f32 v171, -v122, v170, 1.0
	v_fmac_f32_e32 v170, v171, v170
	v_div_scale_f32 v171, vcc, v120, v112, v120
	v_mul_f32_e32 v172, v171, v170
	v_fma_f32 v173, -v122, v172, v171
	v_fmac_f32_e32 v172, v173, v170
	v_fma_f32 v122, -v122, v172, v171
	v_div_fmas_f32 v122, v122, v170, v172
	v_div_fixup_f32 v112, v122, v112, v120
	v_lshlrev_b32_e32 v120, 16, v121
	v_and_b32_e32 v121, 0xffff0000, v121
	v_div_scale_f32 v122, s[2:3], v119, v119, v121
	v_rcp_f32_e32 v170, v122
	s_nop 0
	v_fma_f32 v171, -v122, v170, 1.0
	v_fmac_f32_e32 v170, v171, v170
	v_div_scale_f32 v171, vcc, v121, v119, v121
	v_mul_f32_e32 v172, v171, v170
	v_fma_f32 v173, -v122, v172, v171
	v_fmac_f32_e32 v172, v173, v170
	v_fma_f32 v122, -v122, v172, v171
	v_div_fmas_f32 v122, v122, v170, v172
	v_div_fixup_f32 v119, v122, v119, v121
	v_div_scale_f32 v121, s[2:3], v118, v118, v120
	v_rcp_f32_e32 v122, v121
	s_nop 0
	v_fma_f32 v170, -v121, v122, 1.0
	v_fmac_f32_e32 v122, v170, v122
	v_div_scale_f32 v170, vcc, v120, v118, v120
	v_mul_f32_e32 v171, v170, v122
	v_fma_f32 v172, -v121, v171, v170
	v_fmac_f32_e32 v171, v172, v122
	v_fma_f32 v121, -v121, v171, v170
	v_div_fmas_f32 v121, v121, v122, v171
	v_div_fixup_f32 v118, v121, v118, v120
	v_and_b32_e32 v121, 0xffff0000, v123
	v_div_scale_f32 v122, s[2:3], v115, v115, v121
	v_lshlrev_b32_e32 v120, 16, v123
	v_rcp_f32_e32 v123, v122
	s_nop 0
	v_fma_f32 v170, -v122, v123, 1.0
	v_fmac_f32_e32 v123, v170, v123
	v_div_scale_f32 v170, vcc, v121, v115, v121
	v_mul_f32_e32 v171, v170, v123
	v_fma_f32 v172, -v122, v171, v170
	v_fmac_f32_e32 v171, v172, v123
	v_fma_f32 v122, -v122, v171, v170
	v_div_fmas_f32 v122, v122, v123, v171
	v_div_fixup_f32 v121, v122, v115, v121
	v_div_scale_f32 v115, s[2:3], v114, v114, v120
	v_rcp_f32_e32 v122, v115
	s_nop 0
	v_fma_f32 v123, -v115, v122, 1.0
	v_fmac_f32_e32 v122, v123, v122
	v_div_scale_f32 v123, vcc, v120, v114, v120
	v_mul_f32_e32 v170, v123, v122
	v_fma_f32 v171, -v115, v170, v123
	v_fmac_f32_e32 v170, v171, v122
	v_fma_f32 v115, -v115, v170, v123
	v_div_fmas_f32 v115, v115, v122, v170
	v_div_fixup_f32 v120, v115, v114, v120
	v_pk_mul_f32 v[114:115], v[116:117], v[116:117]
	v_pk_mul_f32 v[122:123], v[118:119], v[118:119]
	v_add_f32_e32 v114, v114, v126
	v_add_f32_e32 v114, v115, v114
	v_add_f32_e32 v114, v122, v114
	v_pk_mul_f32 v[170:171], v[112:113], v[112:113]
	v_add_f32_e32 v114, v123, v114
	v_add_f32_e32 v114, v170, v114
	v_pk_mul_f32 v[172:173], v[120:121], v[120:121]
	v_add_f32_e32 v114, v171, v114
	v_add_f32_e32 v114, v172, v114
	v_add_f32_e32 v122, v173, v114
	v_cvt_pk_bf16_f32 v114, v116, v117
	v_cvt_pk_bf16_f32 v116, v112, v113
	ds_bpermute_b32 v112, v186, v122
	v_cvt_pk_bf16_f32 v115, v118, v119
	v_cvt_pk_bf16_f32 v117, v120, v121
	global_store_dwordx4 v[124:125], v[114:117], off offset:256
	s_waitcnt lgkmcnt(0)
	v_add_f32_e32 v112, v122, v112
	ds_bpermute_b32 v113, v185, v112
	s_and_saveexec_b64 s[2:3], s[38:39]
	s_cbranch_execz .LBB0_59
	s_waitcnt lgkmcnt(0)
	v_add_f32_e32 v112, v112, v113
	ds_add_f32 v175, v112
; __device__ __forceinline__ unsigned pk2(float lo, float hi) { const f32x2 v = {lo, hi}; return __builtin_bit_cast(unsigned, __builtin_convertvector(v, bf16x2_t)); }
; __device__ __forceinline__ void unpack8(u32x4 w, float* f) { f[0] = bflo(w.x); f[1] = bfhi(w.x); f[2] = bflo(w.y); f[3] = bfhi(w.y); f[4] = bflo(w.z); f[5] = bfhi(w.z); f[6] = bflo(w.w); f[7] = bfhi(w.w); }
;     __device__ __forceinline__ void operator()(const f32x4 (&acc)[2][2][4][2], const Unit& u, int wr, int wc, int fr, int fq) const {
;     ...
;             for (int m = 0; m < 4; ++m) { const int rl = wr * 64 + fr + ai * HALF + m * 16; const size_t row = (size_t)u.pm * BM + rl; float part = 0.f;
; #pragma unroll
;                 for (int bj = 0; bj < 2; ++bj) { const int col = col0 + bj * HALF; const u32x4 yw = *(const u32x4*)(YG + row * 512 + col); float y[8], o[8]; unpack8(yw, y);
;                     const f32x4 v0 = acc[ai][bj][m][0], v1 = acc[ai][bj][m][1];
; #pragma unroll
;                     for (int j = 0; j < 4; ++j) { o[j] = y[j] / (1.0f + __expf(-v0[j])); o[4 + j] = y[4 + j] / (1.0f + __expf(-v1[j])); }
; #pragma unroll
;                     for (int j = 0; j < 8; ++j) part += o[j] * o[j];
;                     u32x4 w; w.x = pk2(o[0], o[1]); w.y = pk2(o[2], o[3]); w.z = pk2(o[4], o[5]); w.w = pk2(o[6], o[7]);
;                     *(u32x4*)(YC + row * D + col) = w; }
.LBB0_59:
	s_or_b64 exec, exec, s[2:3]
	s_waitcnt lgkmcnt(0)
	v_lshl_add_u64 v[112:113], s[18:19], 0, v[142:143]
	v_lshlrev_b64 v[114:115], 10, v[112:113]
	v_lshlrev_b64 v[120:121], 12, v[112:113]
	v_lshl_add_u64 v[112:113], s[4:5], 0, v[114:115]
	v_lshl_add_u64 v[118:119], v[112:113], 0, v[160:161]
	v_mul_f32_e32 v108, 0xbfb8aa3b, v108
	v_mul_f32_e32 v109, 0xbfb8aa3b, v109
	v_exp_f32_e32 v108, v108
	v_exp_f32_e32 v109, v109
	v_mul_f32_e32 v104, 0xbfb8aa3b, v104
	v_mul_f32_e32 v105, 0xbfb8aa3b, v105
	v_exp_f32_e32 v104, v104
	v_pk_add_f32 v[108:109], v[108:109], 1.0 op_sel_hi:[1,0]
	v_exp_f32_e32 v105, v105
	v_mul_f32_e32 v100, 0xbfb8aa3b, v100
	v_mul_f32_e32 v101, 0xbfb8aa3b, v101
	v_exp_f32_e32 v100, v100
	v_pk_add_f32 v[104:105], v[104:105], 1.0 op_sel_hi:[1,0]
	v_exp_f32_e32 v101, v101
	v_mul_f32_e32 v96, 0xbfb8aa3b, v96
	v_mul_f32_e32 v97, 0xbfb8aa3b, v97
	v_exp_f32_e32 v96, v96
	v_pk_add_f32 v[100:101], v[100:101], 1.0 op_sel_hi:[1,0]
	v_exp_f32_e32 v97, v97
	v_mul_f32_e32 v102, 0xbfb8aa3b, v102
	v_mul_f32_e32 v103, 0xbfb8aa3b, v103
	v_exp_f32_e32 v102, v102
	v_pk_add_f32 v[96:97], v[96:97], 1.0 op_sel_hi:[1,0]
	v_exp_f32_e32 v103, v103
	v_mul_f32_e32 v98, 0xbfb8aa3b, v98
	v_mul_f32_e32 v99, 0xbfb8aa3b, v99
	v_exp_f32_e32 v98, v98
	v_pk_add_f32 v[102:103], v[102:103], 1.0 op_sel_hi:[1,0]
	v_exp_f32_e32 v99, v99
	s_waitcnt vmcnt(7)
	v_mov_b32_e32 v112, v228
	v_mov_b32_e32 v113, v229
	v_mov_b32_e32 v114, v230
	v_mov_b32_e32 v115, v231
	v_lshlrev_b32_e32 v116, 16, v112
	v_and_b32_e32 v112, 0xffff0000, v112
	v_div_scale_f32 v117, s[2:3], v109, v109, v112
	v_rcp_f32_e32 v122, v117
	v_pk_add_f32 v[98:99], v[98:99], 1.0 op_sel_hi:[1,0]
	v_fma_f32 v123, -v117, v122, 1.0
	v_fmac_f32_e32 v122, v123, v122
	v_div_scale_f32 v123, vcc, v112, v109, v112
	v_mul_f32_e32 v124, v123, v122
	v_fma_f32 v125, -v117, v124, v123
	v_fmac_f32_e32 v124, v125, v122
	v_fma_f32 v117, -v117, v124, v123
	v_div_fmas_f32 v117, v117, v122, v124
	v_div_fixup_f32 v109, v117, v109, v112
	v_div_scale_f32 v112, s[2:3], v108, v108, v116
	v_rcp_f32_e32 v117, v112
	s_nop 0
	v_fma_f32 v122, -v112, v117, 1.0
	v_fmac_f32_e32 v117, v122, v117
	v_div_scale_f32 v122, vcc, v116, v108, v116
	v_mul_f32_e32 v123, v122, v117
	v_fma_f32 v124, -v112, v123, v122
	v_fmac_f32_e32 v123, v124, v117
	v_fma_f32 v112, -v112, v123, v122
	v_div_fmas_f32 v112, v112, v117, v123
	v_div_fixup_f32 v108, v112, v108, v116
	v_lshlrev_b32_e32 v112, 16, v114
	v_and_b32_e32 v114, 0xffff0000, v114
	v_div_scale_f32 v116, s[2:3], v105, v105, v114
	v_rcp_f32_e32 v117, v116
	s_nop 0
	v_fma_f32 v122, -v116, v117, 1.0
	v_fmac_f32_e32 v117, v122, v117
	v_div_scale_f32 v122, vcc, v114, v105, v114
	v_mul_f32_e32 v123, v122, v117
	v_fma_f32 v124, -v116, v123, v122
	v_fmac_f32_e32 v123, v124, v117
	v_fma_f32 v116, -v116, v123, v122
	v_div_fmas_f32 v116, v116, v117, v123
	v_div_fixup_f32 v123, v116, v105, v114
	v_div_scale_f32 v105, s[2:3], v104, v104, v112
	v_rcp_f32_e32 v114, v105
	s_nop 0
	v_fma_f32 v116, -v105, v114, 1.0
	v_fmac_f32_e32 v114, v116, v114
	v_div_scale_f32 v116, vcc, v112, v104, v112
	v_mul_f32_e32 v117, v116, v114
	v_fma_f32 v122, -v105, v117, v116
	v_fmac_f32_e32 v117, v122, v114
	v_fma_f32 v105, -v105, v117, v116
	v_div_fmas_f32 v105, v105, v114, v117
	v_div_fixup_f32 v122, v105, v104, v112
	v_mul_f32_e32 v105, 0xbfb8aa3b, v106
	v_mul_f32_e32 v104, 0xbfb8aa3b, v110
	v_exp_f32_e32 v106, v105
	v_mul_f32_e32 v105, 0xbfb8aa3b, v111
	v_exp_f32_e32 v104, v104
	v_exp_f32_e32 v105, v105
	v_and_b32_e32 v111, 0xffff0000, v113
	v_lshlrev_b32_e32 v110, 16, v113
	v_pk_add_f32 v[104:105], v[104:105], 1.0 op_sel_hi:[1,0]
	s_nop 0
	v_div_scale_f32 v112, s[2:3], v105, v105, v111
	v_rcp_f32_e32 v113, v112
	s_nop 0
	v_fma_f32 v114, -v112, v113, 1.0
	v_fmac_f32_e32 v113, v114, v113
	v_div_scale_f32 v114, vcc, v111, v105, v111
	v_mul_f32_e32 v116, v114, v113
	v_fma_f32 v117, -v112, v116, v114
	v_fmac_f32_e32 v116, v117, v113
	v_fma_f32 v112, -v112, v116, v114
	v_div_fmas_f32 v112, v112, v113, v116
	v_div_fixup_f32 v125, v112, v105, v111
	v_div_scale_f32 v105, s[2:3], v104, v104, v110
	v_rcp_f32_e32 v111, v105
	v_pk_mul_f32 v[116:117], v[108:109], v[108:109]
	v_fma_f32 v112, -v105, v111, 1.0
	v_fmac_f32_e32 v111, v112, v111
	v_div_scale_f32 v112, vcc, v110, v104, v110
	v_mul_f32_e32 v113, v112, v111
	v_fma_f32 v114, -v105, v113, v112
	v_fmac_f32_e32 v113, v114, v111
	v_fma_f32 v105, -v105, v113, v112
	v_div_fmas_f32 v105, v105, v111, v113
	v_div_fixup_f32 v124, v105, v104, v110
	v_mul_f32_e32 v104, 0xbfb8aa3b, v107
	v_exp_f32_e32 v107, v104
	v_and_b32_e32 v111, 0xffff0000, v115
	v_lshlrev_b32_e32 v110, 16, v115
	v_add_f32_e32 v116, v116, v117
	v_pk_add_f32 v[104:105], v[106:107], 1.0 op_sel_hi:[1,0]
	s_nop 0
	v_div_scale_f32 v106, s[2:3], v105, v105, v111
	v_rcp_f32_e32 v107, v106
	s_nop 0
	v_fma_f32 v112, -v106, v107, 1.0
	v_fmac_f32_e32 v107, v112, v107
	v_div_scale_f32 v112, vcc, v111, v105, v111
	v_mul_f32_e32 v113, v112, v107
	v_fma_f32 v114, -v106, v113, v112
	v_fmac_f32_e32 v113, v114, v107
	v_fma_f32 v106, -v106, v113, v112
	v_div_fmas_f32 v106, v106, v107, v113
	v_div_fixup_f32 v127, v106, v105, v111
	v_div_scale_f32 v105, s[2:3], v104, v104, v110
	v_rcp_f32_e32 v106, v105
	v_pk_mul_f32 v[114:115], v[124:125], v[124:125]
	v_fma_f32 v107, -v105, v106, 1.0
	v_fmac_f32_e32 v106, v107, v106
	v_div_scale_f32 v107, vcc, v110, v104, v110
	v_mul_f32_e32 v111, v107, v106
	v_fma_f32 v112, -v105, v111, v107
	v_fmac_f32_e32 v111, v112, v106
	v_fma_f32 v105, -v105, v111, v107
	v_div_fmas_f32 v105, v105, v106, v111
	v_div_fixup_f32 v126, v105, v104, v110
	v_cvt_pk_bf16_f32 v104, v108, v109
	v_lshl_add_u64 v[108:109], s[94:95], 0, v[120:121]
	v_cvt_pk_bf16_f32 v105, v124, v125
	v_cvt_pk_bf16_f32 v106, v122, v123
	v_cvt_pk_bf16_f32 v107, v126, v127
	v_lshl_add_u64 v[108:109], v[108:109], 0, v[160:161]
	global_store_dwordx4 v[108:109], v[104:107], off
	v_pk_mul_f32 v[112:113], v[122:123], v[122:123]
	v_add_f32_e32 v114, v114, v116
	v_add_f32_e32 v114, v115, v114
	v_add_f32_e32 v112, v112, v114
	v_pk_mul_f32 v[110:111], v[126:127], v[126:127]
	v_add_f32_e32 v112, v113, v112
	v_add_f32_e32 v110, v110, v112
	v_add_f32_e32 v110, v111, v110
	s_waitcnt vmcnt(7)
; __device__ __forceinline__ unsigned pk2(float lo, float hi) { const f32x2 v = {lo, hi}; return __builtin_bit_cast(unsigned, __builtin_convertvector(v, bf16x2_t)); }
; __device__ __forceinline__ void unpack8(u32x4 w, float* f) { f[0] = bflo(w.x); f[1] = bfhi(w.x); f[2] = bflo(w.y); f[3] = bfhi(w.y); f[4] = bflo(w.z); f[5] = bfhi(w.z); f[6] = bflo(w.w); f[7] = bfhi(w.w); }
;     __device__ __forceinline__ void operator()(const f32x4 (&acc)[2][2][4][2], const Unit& u, int wr, int wc, int fr, int fq) const {
;     ...
;                 for (int bj = 0; bj < 2; ++bj) { const int col = col0 + bj * HALF; const u32x4 yw = *(const u32x4*)(YG + row * 512 + col); float y[8], o[8]; unpack8(yw, y);
;                     const f32x4 v0 = acc[ai][bj][m][0], v1 = acc[ai][bj][m][1];
; #pragma unroll
;                     for (int j = 0; j < 4; ++j) { o[j] = y[j] / (1.0f + __expf(-v0[j])); o[4 + j] = y[4 + j] / (1.0f + __expf(-v1[j])); }
; #pragma unroll
;                     for (int j = 0; j < 8; ++j) part += o[j] * o[j];
;                     u32x4 w; w.x = pk2(o[0], o[1]); w.y = pk2(o[2], o[3]); w.z = pk2(o[4], o[5]); w.w = pk2(o[6], o[7]);
;                     *(u32x4*)(YC + row * D + col) = w; }
;                 part += __shfl_xor(part, 16); part += __shfl_xor(part, 32);
;                 if (fq == 0) (void)__hip_atomic_fetch_add(rss + rl, part, __ATOMIC_RELAXED, __HIP_MEMORY_SCOPE_WORKGROUP); }
	v_mov_b32_e32 v104, v232
	v_mov_b32_e32 v105, v233
	v_mov_b32_e32 v106, v234
	v_mov_b32_e32 v107, v235
	v_lshlrev_b32_e32 v118, 16, v104
	v_and_b32_e32 v104, 0xffff0000, v104
	v_div_scale_f32 v119, s[2:3], v101, v101, v104
	v_rcp_f32_e32 v120, v119
	s_nop 0
	v_fma_f32 v121, -v119, v120, 1.0
	v_fmac_f32_e32 v120, v121, v120
	v_div_scale_f32 v121, vcc, v104, v101, v104
	v_mul_f32_e32 v122, v121, v120
	v_fma_f32 v123, -v119, v122, v121
	v_fmac_f32_e32 v122, v123, v120
	v_fma_f32 v119, -v119, v122, v121
	v_div_fmas_f32 v119, v119, v120, v122
	v_div_fixup_f32 v101, v119, v101, v104
	v_div_scale_f32 v104, s[2:3], v100, v100, v118
	v_rcp_f32_e32 v119, v104
	s_nop 0
	v_fma_f32 v120, -v104, v119, 1.0
	v_fmac_f32_e32 v119, v120, v119
	v_div_scale_f32 v120, vcc, v118, v100, v118
	v_mul_f32_e32 v121, v120, v119
	v_fma_f32 v122, -v104, v121, v120
	v_fmac_f32_e32 v121, v122, v119
	v_fma_f32 v104, -v104, v121, v120
	v_div_fmas_f32 v104, v104, v119, v121
	v_div_fixup_f32 v100, v104, v100, v118
	v_lshlrev_b32_e32 v104, 16, v106
	v_and_b32_e32 v106, 0xffff0000, v106
	v_div_scale_f32 v118, s[2:3], v97, v97, v106
	v_rcp_f32_e32 v119, v118
	s_nop 0
	v_fma_f32 v120, -v118, v119, 1.0
	v_fmac_f32_e32 v119, v120, v119
	v_div_scale_f32 v120, vcc, v106, v97, v106
	v_mul_f32_e32 v121, v120, v119
	v_fma_f32 v122, -v118, v121, v120
	v_fmac_f32_e32 v121, v122, v119
	v_fma_f32 v118, -v118, v121, v120
	v_div_fmas_f32 v118, v118, v119, v121
	v_div_fixup_f32 v97, v118, v97, v106
	v_div_scale_f32 v106, s[2:3], v96, v96, v104
	v_rcp_f32_e32 v118, v106
	s_nop 0
	v_fma_f32 v119, -v106, v118, 1.0
	v_fmac_f32_e32 v118, v119, v118
	v_div_scale_f32 v119, vcc, v104, v96, v104
	v_mul_f32_e32 v120, v119, v118
	v_fma_f32 v121, -v106, v120, v119
	v_fmac_f32_e32 v120, v121, v118
	v_fma_f32 v106, -v106, v120, v119
	v_div_fmas_f32 v106, v106, v118, v120
	v_div_fixup_f32 v96, v106, v96, v104
	v_lshlrev_b32_e32 v104, 16, v105
	v_and_b32_e32 v105, 0xffff0000, v105
	v_div_scale_f32 v106, s[2:3], v103, v103, v105
	v_rcp_f32_e32 v118, v106
	s_nop 0
	v_fma_f32 v119, -v106, v118, 1.0
	v_fmac_f32_e32 v118, v119, v118
	v_div_scale_f32 v119, vcc, v105, v103, v105
	v_mul_f32_e32 v120, v119, v118
	v_fma_f32 v121, -v106, v120, v119
	v_fmac_f32_e32 v120, v121, v118
	v_fma_f32 v106, -v106, v120, v119
	v_div_fmas_f32 v106, v106, v118, v120
	v_div_fixup_f32 v103, v106, v103, v105
	v_div_scale_f32 v105, s[2:3], v102, v102, v104
	v_rcp_f32_e32 v106, v105
	s_nop 0
	v_fma_f32 v118, -v105, v106, 1.0
	v_fmac_f32_e32 v106, v118, v106
	v_div_scale_f32 v118, vcc, v104, v102, v104
	v_mul_f32_e32 v119, v118, v106
	v_fma_f32 v120, -v105, v119, v118
	v_fmac_f32_e32 v119, v120, v106
	v_fma_f32 v105, -v105, v119, v118
	v_div_fmas_f32 v105, v105, v106, v119
	v_div_fixup_f32 v102, v105, v102, v104
	v_and_b32_e32 v105, 0xffff0000, v107
	v_div_scale_f32 v106, s[2:3], v99, v99, v105
	v_lshlrev_b32_e32 v104, 16, v107
	v_rcp_f32_e32 v107, v106
	s_nop 0
	v_fma_f32 v118, -v106, v107, 1.0
	v_fmac_f32_e32 v107, v118, v107
	v_div_scale_f32 v118, vcc, v105, v99, v105
	v_mul_f32_e32 v119, v118, v107
	v_fma_f32 v120, -v106, v119, v118
	v_fmac_f32_e32 v119, v120, v107
	v_fma_f32 v106, -v106, v119, v118
	v_div_fmas_f32 v106, v106, v107, v119
	v_div_fixup_f32 v105, v106, v99, v105
	v_div_scale_f32 v99, s[2:3], v98, v98, v104
	v_rcp_f32_e32 v106, v99
	s_nop 0
	v_fma_f32 v107, -v99, v106, 1.0
	v_fmac_f32_e32 v106, v107, v106
	v_div_scale_f32 v107, vcc, v104, v98, v104
	v_mul_f32_e32 v118, v107, v106
	v_fma_f32 v119, -v99, v118, v107
	v_fmac_f32_e32 v118, v119, v106
	v_fma_f32 v99, -v99, v118, v107
	v_div_fmas_f32 v99, v99, v106, v118
	v_div_fixup_f32 v104, v99, v98, v104
	v_pk_mul_f32 v[98:99], v[100:101], v[100:101]
	v_pk_mul_f32 v[106:107], v[102:103], v[102:103]
	v_add_f32_e32 v98, v98, v110
	v_add_f32_e32 v98, v99, v98
	v_add_f32_e32 v98, v106, v98
	v_pk_mul_f32 v[118:119], v[96:97], v[96:97]
	v_add_f32_e32 v98, v107, v98
	v_add_f32_e32 v98, v118, v98
	v_pk_mul_f32 v[120:121], v[104:105], v[104:105]
	v_add_f32_e32 v98, v119, v98
	v_add_f32_e32 v98, v120, v98
	v_add_f32_e32 v106, v121, v98
	v_cvt_pk_bf16_f32 v98, v100, v101
	v_cvt_pk_bf16_f32 v100, v96, v97
	ds_bpermute_b32 v96, v186, v106
	v_cvt_pk_bf16_f32 v99, v102, v103
	v_cvt_pk_bf16_f32 v101, v104, v105
	global_store_dwordx4 v[108:109], v[98:101], off offset:256
	s_waitcnt lgkmcnt(0)
	v_add_f32_e32 v96, v106, v96
	ds_bpermute_b32 v97, v185, v96
	s_and_saveexec_b64 s[2:3], s[38:39]
	s_cbranch_execz .LBB0_61
	s_waitcnt lgkmcnt(0)
	v_add_f32_e32 v96, v96, v97
	ds_add_f32 v214, v96
; __device__ __forceinline__ unsigned pk2(float lo, float hi) { const f32x2 v = {lo, hi}; return __builtin_bit_cast(unsigned, __builtin_convertvector(v, bf16x2_t)); }
; __device__ __forceinline__ void unpack8(u32x4 w, float* f) { f[0] = bflo(w.x); f[1] = bfhi(w.x); f[2] = bflo(w.y); f[3] = bfhi(w.y); f[4] = bflo(w.z); f[5] = bfhi(w.z); f[6] = bflo(w.w); f[7] = bfhi(w.w); }
;     __device__ __forceinline__ void operator()(const f32x4 (&acc)[2][2][4][2], const Unit& u, int wr, int wc, int fr, int fq) const {
;     ...
;             for (int m = 0; m < 4; ++m) { const int rl = wr * 64 + fr + ai * HALF + m * 16; const size_t row = (size_t)u.pm * BM + rl; float part = 0.f;
; #pragma unroll
;                 for (int bj = 0; bj < 2; ++bj) { const int col = col0 + bj * HALF; const u32x4 yw = *(const u32x4*)(YG + row * 512 + col); float y[8], o[8]; unpack8(yw, y);
;                     const f32x4 v0 = acc[ai][bj][m][0], v1 = acc[ai][bj][m][1];
; #pragma unroll
;                     for (int j = 0; j < 4; ++j) { o[j] = y[j] / (1.0f + __expf(-v0[j])); o[4 + j] = y[4 + j] / (1.0f + __expf(-v1[j])); }
; #pragma unroll
;                     for (int j = 0; j < 8; ++j) part += o[j] * o[j];
;                     u32x4 w; w.x = pk2(o[0], o[1]); w.y = pk2(o[2], o[3]); w.z = pk2(o[4], o[5]); w.w = pk2(o[6], o[7]);
;                     *(u32x4*)(YC + row * D + col) = w; }
.LBB0_61:
	s_or_b64 exec, exec, s[2:3]
	s_waitcnt lgkmcnt(0)
	v_lshl_add_u64 v[96:97], s[18:19], 0, v[144:145]
	v_lshlrev_b64 v[98:99], 10, v[96:97]
	v_lshlrev_b64 v[104:105], 12, v[96:97]
	v_lshl_add_u64 v[96:97], s[4:5], 0, v[98:99]
	v_lshl_add_u64 v[102:103], v[96:97], 0, v[160:161]
	v_mul_f32_e32 v92, 0xbfb8aa3b, v92
	v_mul_f32_e32 v93, 0xbfb8aa3b, v93
	v_exp_f32_e32 v92, v92
	v_exp_f32_e32 v93, v93
	v_mul_f32_e32 v88, 0xbfb8aa3b, v88
	v_mul_f32_e32 v89, 0xbfb8aa3b, v89
	v_exp_f32_e32 v88, v88
	v_pk_add_f32 v[92:93], v[92:93], 1.0 op_sel_hi:[1,0]
	v_exp_f32_e32 v89, v89
	v_mul_f32_e32 v84, 0xbfb8aa3b, v84
	v_mul_f32_e32 v85, 0xbfb8aa3b, v85
	v_exp_f32_e32 v84, v84
	v_pk_add_f32 v[88:89], v[88:89], 1.0 op_sel_hi:[1,0]
	v_exp_f32_e32 v85, v85
	v_mul_f32_e32 v80, 0xbfb8aa3b, v80
	v_mul_f32_e32 v81, 0xbfb8aa3b, v81
	v_exp_f32_e32 v80, v80
	v_pk_add_f32 v[84:85], v[84:85], 1.0 op_sel_hi:[1,0]
	v_exp_f32_e32 v81, v81
	v_mul_f32_e32 v86, 0xbfb8aa3b, v86
	v_mul_f32_e32 v87, 0xbfb8aa3b, v87
	v_exp_f32_e32 v86, v86
	v_pk_add_f32 v[80:81], v[80:81], 1.0 op_sel_hi:[1,0]
	v_exp_f32_e32 v87, v87
	v_mul_f32_e32 v82, 0xbfb8aa3b, v82
	v_mul_f32_e32 v83, 0xbfb8aa3b, v83
	v_exp_f32_e32 v82, v82
	v_pk_add_f32 v[86:87], v[86:87], 1.0 op_sel_hi:[1,0]
	v_exp_f32_e32 v83, v83
	s_waitcnt vmcnt(7)
	v_mov_b32_e32 v96, v236
	v_mov_b32_e32 v97, v237
	v_mov_b32_e32 v98, v238
	v_mov_b32_e32 v99, v239
	v_lshlrev_b32_e32 v100, 16, v96
	v_and_b32_e32 v96, 0xffff0000, v96
	v_div_scale_f32 v101, s[2:3], v93, v93, v96
	v_rcp_f32_e32 v106, v101
	v_pk_add_f32 v[82:83], v[82:83], 1.0 op_sel_hi:[1,0]
	v_fma_f32 v107, -v101, v106, 1.0
	v_fmac_f32_e32 v106, v107, v106
	v_div_scale_f32 v107, vcc, v96, v93, v96
	v_mul_f32_e32 v108, v107, v106
	v_fma_f32 v109, -v101, v108, v107
	v_fmac_f32_e32 v108, v109, v106
	v_fma_f32 v101, -v101, v108, v107
	v_div_fmas_f32 v101, v101, v106, v108
	v_div_fixup_f32 v93, v101, v93, v96
	v_div_scale_f32 v96, s[2:3], v92, v92, v100
	v_rcp_f32_e32 v101, v96
	s_nop 0
	v_fma_f32 v106, -v96, v101, 1.0
	v_fmac_f32_e32 v101, v106, v101
	v_div_scale_f32 v106, vcc, v100, v92, v100
	v_mul_f32_e32 v107, v106, v101
	v_fma_f32 v108, -v96, v107, v106
	v_fmac_f32_e32 v107, v108, v101
	v_fma_f32 v96, -v96, v107, v106
	v_div_fmas_f32 v96, v96, v101, v107
	v_div_fixup_f32 v92, v96, v92, v100
	v_lshlrev_b32_e32 v96, 16, v98
	v_and_b32_e32 v98, 0xffff0000, v98
	v_div_scale_f32 v100, s[2:3], v89, v89, v98
	v_rcp_f32_e32 v101, v100
	s_nop 0
	v_fma_f32 v106, -v100, v101, 1.0
	v_fmac_f32_e32 v101, v106, v101
	v_div_scale_f32 v106, vcc, v98, v89, v98
	v_mul_f32_e32 v107, v106, v101
	v_fma_f32 v108, -v100, v107, v106
	v_fmac_f32_e32 v107, v108, v101
	v_fma_f32 v100, -v100, v107, v106
	v_div_fmas_f32 v100, v100, v101, v107
	v_div_fixup_f32 v107, v100, v89, v98
	v_div_scale_f32 v89, s[2:3], v88, v88, v96
	v_rcp_f32_e32 v98, v89
	s_nop 0
	v_fma_f32 v100, -v89, v98, 1.0
	v_fmac_f32_e32 v98, v100, v98
	v_div_scale_f32 v100, vcc, v96, v88, v96
	v_mul_f32_e32 v101, v100, v98
	v_fma_f32 v106, -v89, v101, v100
	v_fmac_f32_e32 v101, v106, v98
	v_fma_f32 v89, -v89, v101, v100
	v_div_fmas_f32 v89, v89, v98, v101
	v_div_fixup_f32 v106, v89, v88, v96
	v_mul_f32_e32 v89, 0xbfb8aa3b, v90
	v_mul_f32_e32 v88, 0xbfb8aa3b, v94
	v_exp_f32_e32 v90, v89
	v_mul_f32_e32 v89, 0xbfb8aa3b, v95
	v_exp_f32_e32 v88, v88
	v_exp_f32_e32 v89, v89
	v_and_b32_e32 v95, 0xffff0000, v97
	v_lshlrev_b32_e32 v94, 16, v97
	v_pk_add_f32 v[88:89], v[88:89], 1.0 op_sel_hi:[1,0]
	s_nop 0
	v_div_scale_f32 v96, s[2:3], v89, v89, v95
	v_rcp_f32_e32 v97, v96
	s_nop 0
	v_fma_f32 v98, -v96, v97, 1.0
	v_fmac_f32_e32 v97, v98, v97
	v_div_scale_f32 v98, vcc, v95, v89, v95
	v_mul_f32_e32 v100, v98, v97
	v_fma_f32 v101, -v96, v100, v98
	v_fmac_f32_e32 v100, v101, v97
	v_fma_f32 v96, -v96, v100, v98
	v_div_fmas_f32 v96, v96, v97, v100
	v_div_fixup_f32 v109, v96, v89, v95
	v_div_scale_f32 v89, s[2:3], v88, v88, v94
	v_rcp_f32_e32 v95, v89
	v_pk_mul_f32 v[100:101], v[92:93], v[92:93]
	v_fma_f32 v96, -v89, v95, 1.0
	v_fmac_f32_e32 v95, v96, v95
	v_div_scale_f32 v96, vcc, v94, v88, v94
	v_mul_f32_e32 v97, v96, v95
	v_fma_f32 v98, -v89, v97, v96
	v_fmac_f32_e32 v97, v98, v95
	v_fma_f32 v89, -v89, v97, v96
	v_div_fmas_f32 v89, v89, v95, v97
	v_div_fixup_f32 v108, v89, v88, v94
	v_mul_f32_e32 v88, 0xbfb8aa3b, v91
	v_exp_f32_e32 v91, v88
	v_and_b32_e32 v95, 0xffff0000, v99
	v_lshlrev_b32_e32 v94, 16, v99
	v_add_f32_e32 v100, v100, v101
	v_pk_add_f32 v[88:89], v[90:91], 1.0 op_sel_hi:[1,0]
	s_nop 0
	v_div_scale_f32 v90, s[2:3], v89, v89, v95
	v_rcp_f32_e32 v91, v90
	s_nop 0
	v_fma_f32 v96, -v90, v91, 1.0
	v_fmac_f32_e32 v91, v96, v91
	v_div_scale_f32 v96, vcc, v95, v89, v95
	v_mul_f32_e32 v97, v96, v91
	v_fma_f32 v98, -v90, v97, v96
	v_fmac_f32_e32 v97, v98, v91
	v_fma_f32 v90, -v90, v97, v96
	v_div_fmas_f32 v90, v90, v91, v97
	v_div_fixup_f32 v111, v90, v89, v95
	v_div_scale_f32 v89, s[2:3], v88, v88, v94
	v_rcp_f32_e32 v90, v89
	v_pk_mul_f32 v[98:99], v[108:109], v[108:109]
	v_fma_f32 v91, -v89, v90, 1.0
	v_fmac_f32_e32 v90, v91, v90
	v_div_scale_f32 v91, vcc, v94, v88, v94
	v_mul_f32_e32 v95, v91, v90
	v_fma_f32 v96, -v89, v95, v91
	v_fmac_f32_e32 v95, v96, v90
	v_fma_f32 v89, -v89, v95, v91
	v_div_fmas_f32 v89, v89, v90, v95
	v_div_fixup_f32 v110, v89, v88, v94
	v_cvt_pk_bf16_f32 v88, v92, v93
	v_lshl_add_u64 v[92:93], s[94:95], 0, v[104:105]
	v_cvt_pk_bf16_f32 v89, v108, v109
	v_cvt_pk_bf16_f32 v90, v106, v107
	v_cvt_pk_bf16_f32 v91, v110, v111
	v_lshl_add_u64 v[92:93], v[92:93], 0, v[160:161]
	global_store_dwordx4 v[92:93], v[88:91], off
	v_pk_mul_f32 v[96:97], v[106:107], v[106:107]
	v_add_f32_e32 v98, v98, v100
	v_add_f32_e32 v98, v99, v98
	v_add_f32_e32 v96, v96, v98
	v_pk_mul_f32 v[94:95], v[110:111], v[110:111]
	v_add_f32_e32 v96, v97, v96
	v_add_f32_e32 v94, v94, v96
	v_add_f32_e32 v94, v95, v94
	s_waitcnt vmcnt(7)
; __device__ __forceinline__ unsigned pk2(float lo, float hi) { const f32x2 v = {lo, hi}; return __builtin_bit_cast(unsigned, __builtin_convertvector(v, bf16x2_t)); }
; __device__ __forceinline__ void unpack8(u32x4 w, float* f) { f[0] = bflo(w.x); f[1] = bfhi(w.x); f[2] = bflo(w.y); f[3] = bfhi(w.y); f[4] = bflo(w.z); f[5] = bfhi(w.z); f[6] = bflo(w.w); f[7] = bfhi(w.w); }
;     __device__ __forceinline__ void operator()(const f32x4 (&acc)[2][2][4][2], const Unit& u, int wr, int wc, int fr, int fq) const {
;     ...
;                 for (int bj = 0; bj < 2; ++bj) { const int col = col0 + bj * HALF; const u32x4 yw = *(const u32x4*)(YG + row * 512 + col); float y[8], o[8]; unpack8(yw, y);
;                     const f32x4 v0 = acc[ai][bj][m][0], v1 = acc[ai][bj][m][1];
; #pragma unroll
;                     for (int j = 0; j < 4; ++j) { o[j] = y[j] / (1.0f + __expf(-v0[j])); o[4 + j] = y[4 + j] / (1.0f + __expf(-v1[j])); }
; #pragma unroll
;                     for (int j = 0; j < 8; ++j) part += o[j] * o[j];
;                     u32x4 w; w.x = pk2(o[0], o[1]); w.y = pk2(o[2], o[3]); w.z = pk2(o[4], o[5]); w.w = pk2(o[6], o[7]);
;                     *(u32x4*)(YC + row * D + col) = w; }
;                 part += __shfl_xor(part, 16); part += __shfl_xor(part, 32);
;                 if (fq == 0) (void)__hip_atomic_fetch_add(rss + rl, part, __ATOMIC_RELAXED, __HIP_MEMORY_SCOPE_WORKGROUP); }
	v_mov_b32_e32 v88, v240
	v_mov_b32_e32 v89, v241
	v_mov_b32_e32 v90, v242
	v_mov_b32_e32 v91, v243
	v_lshlrev_b32_e32 v102, 16, v88
	v_and_b32_e32 v88, 0xffff0000, v88
	v_div_scale_f32 v103, s[2:3], v85, v85, v88
	v_rcp_f32_e32 v104, v103
	s_nop 0
	v_fma_f32 v105, -v103, v104, 1.0
	v_fmac_f32_e32 v104, v105, v104
	v_div_scale_f32 v105, vcc, v88, v85, v88
	v_mul_f32_e32 v106, v105, v104
	v_fma_f32 v107, -v103, v106, v105
	v_fmac_f32_e32 v106, v107, v104
	v_fma_f32 v103, -v103, v106, v105
	v_div_fmas_f32 v103, v103, v104, v106
	v_div_fixup_f32 v85, v103, v85, v88
	v_div_scale_f32 v88, s[2:3], v84, v84, v102
	v_rcp_f32_e32 v103, v88
	s_nop 0
	v_fma_f32 v104, -v88, v103, 1.0
	v_fmac_f32_e32 v103, v104, v103
	v_div_scale_f32 v104, vcc, v102, v84, v102
	v_mul_f32_e32 v105, v104, v103
	v_fma_f32 v106, -v88, v105, v104
	v_fmac_f32_e32 v105, v106, v103
	v_fma_f32 v88, -v88, v105, v104
	v_div_fmas_f32 v88, v88, v103, v105
	v_div_fixup_f32 v84, v88, v84, v102
	v_lshlrev_b32_e32 v88, 16, v90
	v_and_b32_e32 v90, 0xffff0000, v90
	v_div_scale_f32 v102, s[2:3], v81, v81, v90
	v_rcp_f32_e32 v103, v102
	s_nop 0
	v_fma_f32 v104, -v102, v103, 1.0
	v_fmac_f32_e32 v103, v104, v103
	v_div_scale_f32 v104, vcc, v90, v81, v90
	v_mul_f32_e32 v105, v104, v103
	v_fma_f32 v106, -v102, v105, v104
	v_fmac_f32_e32 v105, v106, v103
	v_fma_f32 v102, -v102, v105, v104
	v_div_fmas_f32 v102, v102, v103, v105
	v_div_fixup_f32 v81, v102, v81, v90
	v_div_scale_f32 v90, s[2:3], v80, v80, v88
	v_rcp_f32_e32 v102, v90
	s_nop 0
	v_fma_f32 v103, -v90, v102, 1.0
	v_fmac_f32_e32 v102, v103, v102
	v_div_scale_f32 v103, vcc, v88, v80, v88
	v_mul_f32_e32 v104, v103, v102
	v_fma_f32 v105, -v90, v104, v103
	v_fmac_f32_e32 v104, v105, v102
	v_fma_f32 v90, -v90, v104, v103
	v_div_fmas_f32 v90, v90, v102, v104
	v_div_fixup_f32 v80, v90, v80, v88
	v_lshlrev_b32_e32 v88, 16, v89
	v_and_b32_e32 v89, 0xffff0000, v89
	v_div_scale_f32 v90, s[2:3], v87, v87, v89
	v_rcp_f32_e32 v102, v90
	s_nop 0
	v_fma_f32 v103, -v90, v102, 1.0
	v_fmac_f32_e32 v102, v103, v102
	v_div_scale_f32 v103, vcc, v89, v87, v89
	v_mul_f32_e32 v104, v103, v102
	v_fma_f32 v105, -v90, v104, v103
	v_fmac_f32_e32 v104, v105, v102
	v_fma_f32 v90, -v90, v104, v103
	v_div_fmas_f32 v90, v90, v102, v104
	v_div_fixup_f32 v87, v90, v87, v89
	v_div_scale_f32 v89, s[2:3], v86, v86, v88
	v_rcp_f32_e32 v90, v89
	s_nop 0
	v_fma_f32 v102, -v89, v90, 1.0
	v_fmac_f32_e32 v90, v102, v90
	v_div_scale_f32 v102, vcc, v88, v86, v88
	v_mul_f32_e32 v103, v102, v90
	v_fma_f32 v104, -v89, v103, v102
	v_fmac_f32_e32 v103, v104, v90
	v_fma_f32 v89, -v89, v103, v102
	v_div_fmas_f32 v89, v89, v90, v103
	v_div_fixup_f32 v86, v89, v86, v88
	v_and_b32_e32 v89, 0xffff0000, v91
	v_div_scale_f32 v90, s[2:3], v83, v83, v89
	v_lshlrev_b32_e32 v88, 16, v91
	v_rcp_f32_e32 v91, v90
	s_nop 0
	v_fma_f32 v102, -v90, v91, 1.0
	v_fmac_f32_e32 v91, v102, v91
	v_div_scale_f32 v102, vcc, v89, v83, v89
	v_mul_f32_e32 v103, v102, v91
	v_fma_f32 v104, -v90, v103, v102
	v_fmac_f32_e32 v103, v104, v91
	v_fma_f32 v90, -v90, v103, v102
	v_div_fmas_f32 v90, v90, v91, v103
	v_div_fixup_f32 v89, v90, v83, v89
	v_div_scale_f32 v83, s[2:3], v82, v82, v88
	v_rcp_f32_e32 v90, v83
	s_nop 0
	v_fma_f32 v91, -v83, v90, 1.0
	v_fmac_f32_e32 v90, v91, v90
	v_div_scale_f32 v91, vcc, v88, v82, v88
	v_mul_f32_e32 v102, v91, v90
	v_fma_f32 v103, -v83, v102, v91
	v_fmac_f32_e32 v102, v103, v90
	v_fma_f32 v83, -v83, v102, v91
	v_div_fmas_f32 v83, v83, v90, v102
	v_div_fixup_f32 v88, v83, v82, v88
	v_pk_mul_f32 v[82:83], v[84:85], v[84:85]
	v_pk_mul_f32 v[90:91], v[86:87], v[86:87]
	v_add_f32_e32 v82, v82, v94
	v_add_f32_e32 v82, v83, v82
	v_add_f32_e32 v82, v90, v82
	v_pk_mul_f32 v[102:103], v[80:81], v[80:81]
	v_add_f32_e32 v82, v91, v82
	v_add_f32_e32 v82, v102, v82
	v_pk_mul_f32 v[104:105], v[88:89], v[88:89]
	v_add_f32_e32 v82, v103, v82
	v_add_f32_e32 v82, v104, v82
	v_add_f32_e32 v90, v105, v82
	v_cvt_pk_bf16_f32 v82, v84, v85
	v_cvt_pk_bf16_f32 v84, v80, v81
	ds_bpermute_b32 v80, v186, v90
	v_cvt_pk_bf16_f32 v83, v86, v87
	v_cvt_pk_bf16_f32 v85, v88, v89
	global_store_dwordx4 v[92:93], v[82:85], off offset:256
	s_waitcnt lgkmcnt(0)
	v_add_f32_e32 v80, v90, v80
	ds_bpermute_b32 v81, v185, v80
	s_and_saveexec_b64 s[2:3], s[38:39]
	v_readlane_b32 s25, v254, 48
	s_cbranch_execz .LBB0_63
	s_waitcnt lgkmcnt(0)
	v_add_f32_e32 v80, v80, v81
	ds_add_f32 v217, v80
; __device__ __forceinline__ unsigned pk2(float lo, float hi) { const f32x2 v = {lo, hi}; return __builtin_bit_cast(unsigned, __builtin_convertvector(v, bf16x2_t)); }
; __device__ __forceinline__ void unpack8(u32x4 w, float* f) { f[0] = bflo(w.x); f[1] = bfhi(w.x); f[2] = bflo(w.y); f[3] = bfhi(w.y); f[4] = bflo(w.z); f[5] = bfhi(w.z); f[6] = bflo(w.w); f[7] = bfhi(w.w); }
;     __device__ __forceinline__ void operator()(const f32x4 (&acc)[2][2][4][2], const Unit& u, int wr, int wc, int fr, int fq) const {
;     ...
;             for (int m = 0; m < 4; ++m) { const int rl = wr * 64 + fr + ai * HALF + m * 16; const size_t row = (size_t)u.pm * BM + rl; float part = 0.f;
; #pragma unroll
;                 for (int bj = 0; bj < 2; ++bj) { const int col = col0 + bj * HALF; const u32x4 yw = *(const u32x4*)(YG + row * 512 + col); float y[8], o[8]; unpack8(yw, y);
;                     const f32x4 v0 = acc[ai][bj][m][0], v1 = acc[ai][bj][m][1];
; #pragma unroll
;                     for (int j = 0; j < 4; ++j) { o[j] = y[j] / (1.0f + __expf(-v0[j])); o[4 + j] = y[4 + j] / (1.0f + __expf(-v1[j])); }
; #pragma unroll
;                     for (int j = 0; j < 8; ++j) part += o[j] * o[j];
;                     u32x4 w; w.x = pk2(o[0], o[1]); w.y = pk2(o[2], o[3]); w.z = pk2(o[4], o[5]); w.w = pk2(o[6], o[7]);
;                     *(u32x4*)(YC + row * D + col) = w; }
.LBB0_63:
	s_or_b64 exec, exec, s[2:3]
	s_waitcnt lgkmcnt(0)
	v_lshl_add_u64 v[80:81], s[18:19], 0, v[146:147]
	v_lshlrev_b64 v[82:83], 10, v[80:81]
	v_lshlrev_b64 v[88:89], 12, v[80:81]
	v_lshl_add_u64 v[80:81], s[4:5], 0, v[82:83]
	v_lshl_add_u64 v[86:87], v[80:81], 0, v[160:161]
	v_mul_f32_e32 v76, 0xbfb8aa3b, v76
	v_mul_f32_e32 v77, 0xbfb8aa3b, v77
	v_exp_f32_e32 v76, v76
	v_exp_f32_e32 v77, v77
	v_mul_f32_e32 v72, 0xbfb8aa3b, v72
	v_mul_f32_e32 v73, 0xbfb8aa3b, v73
	v_exp_f32_e32 v72, v72
	v_pk_add_f32 v[76:77], v[76:77], 1.0 op_sel_hi:[1,0]
	v_exp_f32_e32 v73, v73
	v_mul_f32_e32 v68, 0xbfb8aa3b, v68
	v_mul_f32_e32 v69, 0xbfb8aa3b, v69
	v_exp_f32_e32 v68, v68
	v_pk_add_f32 v[72:73], v[72:73], 1.0 op_sel_hi:[1,0]
	v_exp_f32_e32 v69, v69
	v_mul_f32_e32 v64, 0xbfb8aa3b, v64
	v_mul_f32_e32 v65, 0xbfb8aa3b, v65
	v_exp_f32_e32 v64, v64
	v_pk_add_f32 v[68:69], v[68:69], 1.0 op_sel_hi:[1,0]
	v_exp_f32_e32 v65, v65
	v_mul_f32_e32 v70, 0xbfb8aa3b, v70
	v_mul_f32_e32 v71, 0xbfb8aa3b, v71
	v_exp_f32_e32 v70, v70
	v_pk_add_f32 v[64:65], v[64:65], 1.0 op_sel_hi:[1,0]
	v_exp_f32_e32 v71, v71
	v_mul_f32_e32 v66, 0xbfb8aa3b, v66
	v_mul_f32_e32 v67, 0xbfb8aa3b, v67
	v_exp_f32_e32 v66, v66
	v_pk_add_f32 v[70:71], v[70:71], 1.0 op_sel_hi:[1,0]
	v_exp_f32_e32 v67, v67
	s_waitcnt vmcnt(7)
	v_mov_b32_e32 v80, v244
	v_mov_b32_e32 v81, v245
	v_mov_b32_e32 v82, v246
	v_mov_b32_e32 v83, v247
	v_lshlrev_b32_e32 v84, 16, v80
	v_and_b32_e32 v80, 0xffff0000, v80
	v_div_scale_f32 v85, s[2:3], v77, v77, v80
	v_rcp_f32_e32 v90, v85
	v_pk_add_f32 v[66:67], v[66:67], 1.0 op_sel_hi:[1,0]
	v_fma_f32 v91, -v85, v90, 1.0
	v_fmac_f32_e32 v90, v91, v90
	v_div_scale_f32 v91, vcc, v80, v77, v80
	v_mul_f32_e32 v92, v91, v90
	v_fma_f32 v93, -v85, v92, v91
	v_fmac_f32_e32 v92, v93, v90
	v_fma_f32 v85, -v85, v92, v91
	v_div_fmas_f32 v85, v85, v90, v92
	v_div_fixup_f32 v77, v85, v77, v80
	v_div_scale_f32 v80, s[2:3], v76, v76, v84
	v_rcp_f32_e32 v85, v80
	s_nop 0
	v_fma_f32 v90, -v80, v85, 1.0
	v_fmac_f32_e32 v85, v90, v85
	v_div_scale_f32 v90, vcc, v84, v76, v84
	v_mul_f32_e32 v91, v90, v85
	v_fma_f32 v92, -v80, v91, v90
	v_fmac_f32_e32 v91, v92, v85
	v_fma_f32 v80, -v80, v91, v90
	v_div_fmas_f32 v80, v80, v85, v91
	v_div_fixup_f32 v76, v80, v76, v84
	v_lshlrev_b32_e32 v80, 16, v82
	v_and_b32_e32 v82, 0xffff0000, v82
	v_div_scale_f32 v84, s[2:3], v73, v73, v82
	v_rcp_f32_e32 v85, v84
	s_nop 0
	v_fma_f32 v90, -v84, v85, 1.0
	v_fmac_f32_e32 v85, v90, v85
	v_div_scale_f32 v90, vcc, v82, v73, v82
	v_mul_f32_e32 v91, v90, v85
	v_fma_f32 v92, -v84, v91, v90
	v_fmac_f32_e32 v91, v92, v85
	v_fma_f32 v84, -v84, v91, v90
	v_div_fmas_f32 v84, v84, v85, v91
	v_div_fixup_f32 v91, v84, v73, v82
	v_div_scale_f32 v73, s[2:3], v72, v72, v80
	v_rcp_f32_e32 v82, v73
	s_nop 0
	v_fma_f32 v84, -v73, v82, 1.0
	v_fmac_f32_e32 v82, v84, v82
	v_div_scale_f32 v84, vcc, v80, v72, v80
	v_mul_f32_e32 v85, v84, v82
	v_fma_f32 v90, -v73, v85, v84
	v_fmac_f32_e32 v85, v90, v82
	v_fma_f32 v73, -v73, v85, v84
	v_div_fmas_f32 v73, v73, v82, v85
	v_div_fixup_f32 v90, v73, v72, v80
	v_mul_f32_e32 v73, 0xbfb8aa3b, v74
	v_mul_f32_e32 v72, 0xbfb8aa3b, v78
	v_exp_f32_e32 v74, v73
	v_mul_f32_e32 v73, 0xbfb8aa3b, v79
	v_exp_f32_e32 v72, v72
	v_exp_f32_e32 v73, v73
	v_and_b32_e32 v79, 0xffff0000, v81
	v_lshlrev_b32_e32 v78, 16, v81
	v_pk_add_f32 v[72:73], v[72:73], 1.0 op_sel_hi:[1,0]
	s_nop 0
	v_div_scale_f32 v80, s[2:3], v73, v73, v79
	v_rcp_f32_e32 v81, v80
	s_nop 0
	v_fma_f32 v82, -v80, v81, 1.0
	v_fmac_f32_e32 v81, v82, v81
	v_div_scale_f32 v82, vcc, v79, v73, v79
	v_mul_f32_e32 v84, v82, v81
	v_fma_f32 v85, -v80, v84, v82
	v_fmac_f32_e32 v84, v85, v81
	v_fma_f32 v80, -v80, v84, v82
	v_div_fmas_f32 v80, v80, v81, v84
	v_div_fixup_f32 v93, v80, v73, v79
	v_div_scale_f32 v73, s[2:3], v72, v72, v78
	v_rcp_f32_e32 v79, v73
	v_pk_mul_f32 v[84:85], v[76:77], v[76:77]
	v_fma_f32 v80, -v73, v79, 1.0
	v_fmac_f32_e32 v79, v80, v79
	v_div_scale_f32 v80, vcc, v78, v72, v78
	v_mul_f32_e32 v81, v80, v79
	v_fma_f32 v82, -v73, v81, v80
	v_fmac_f32_e32 v81, v82, v79
	v_fma_f32 v73, -v73, v81, v80
	v_div_fmas_f32 v73, v73, v79, v81
	v_div_fixup_f32 v92, v73, v72, v78
	v_mul_f32_e32 v72, 0xbfb8aa3b, v75
	v_exp_f32_e32 v75, v72
	v_and_b32_e32 v79, 0xffff0000, v83
	v_lshlrev_b32_e32 v78, 16, v83
	v_add_f32_e32 v84, v84, v85
	v_pk_add_f32 v[72:73], v[74:75], 1.0 op_sel_hi:[1,0]
	s_nop 0
	v_div_scale_f32 v74, s[2:3], v73, v73, v79
	v_rcp_f32_e32 v75, v74
	s_nop 0
	v_fma_f32 v80, -v74, v75, 1.0
	v_fmac_f32_e32 v75, v80, v75
	v_div_scale_f32 v80, vcc, v79, v73, v79
	v_mul_f32_e32 v81, v80, v75
	v_fma_f32 v82, -v74, v81, v80
	v_fmac_f32_e32 v81, v82, v75
	v_fma_f32 v74, -v74, v81, v80
	v_div_fmas_f32 v74, v74, v75, v81
	v_div_fixup_f32 v95, v74, v73, v79
	v_div_scale_f32 v73, s[2:3], v72, v72, v78
	v_rcp_f32_e32 v74, v73
	v_pk_mul_f32 v[82:83], v[92:93], v[92:93]
	v_fma_f32 v75, -v73, v74, 1.0
	v_fmac_f32_e32 v74, v75, v74
	v_div_scale_f32 v75, vcc, v78, v72, v78
	v_mul_f32_e32 v79, v75, v74
	v_fma_f32 v80, -v73, v79, v75
	v_fmac_f32_e32 v79, v80, v74
	v_fma_f32 v73, -v73, v79, v75
	v_div_fmas_f32 v73, v73, v74, v79
	v_div_fixup_f32 v94, v73, v72, v78
	v_cvt_pk_bf16_f32 v72, v76, v77
	v_lshl_add_u64 v[76:77], s[94:95], 0, v[88:89]
	v_cvt_pk_bf16_f32 v73, v92, v93
	v_cvt_pk_bf16_f32 v74, v90, v91
	v_cvt_pk_bf16_f32 v75, v94, v95
	v_lshl_add_u64 v[76:77], v[76:77], 0, v[160:161]
	global_store_dwordx4 v[76:77], v[72:75], off
	v_pk_mul_f32 v[80:81], v[90:91], v[90:91]
	v_add_f32_e32 v82, v82, v84
	v_add_f32_e32 v82, v83, v82
	v_add_f32_e32 v80, v80, v82
	v_pk_mul_f32 v[78:79], v[94:95], v[94:95]
	v_add_f32_e32 v80, v81, v80
	v_add_f32_e32 v78, v78, v80
	v_add_f32_e32 v78, v79, v78
	s_waitcnt vmcnt(7)
; __device__ __forceinline__ unsigned pk2(float lo, float hi) { const f32x2 v = {lo, hi}; return __builtin_bit_cast(unsigned, __builtin_convertvector(v, bf16x2_t)); }
; __device__ __forceinline__ void unpack8(u32x4 w, float* f) { f[0] = bflo(w.x); f[1] = bfhi(w.x); f[2] = bflo(w.y); f[3] = bfhi(w.y); f[4] = bflo(w.z); f[5] = bfhi(w.z); f[6] = bflo(w.w); f[7] = bfhi(w.w); }
;     __device__ __forceinline__ void operator()(const f32x4 (&acc)[2][2][4][2], const Unit& u, int wr, int wc, int fr, int fq) const {
;     ...
;             for (int m = 0; m < 4; ++m) { const int rl = wr * 64 + fr + ai * HALF + m * 16; const size_t row = (size_t)u.pm * BM + rl; float part = 0.f;
; #pragma unroll
;                 for (int bj = 0; bj < 2; ++bj) { const int col = col0 + bj * HALF; const u32x4 yw = *(const u32x4*)(YG + row * 512 + col); float y[8], o[8]; unpack8(yw, y);
;                     const f32x4 v0 = acc[ai][bj][m][0], v1 = acc[ai][bj][m][1];
; #pragma unroll
;                     for (int j = 0; j < 4; ++j) { o[j] = y[j] / (1.0f + __expf(-v0[j])); o[4 + j] = y[4 + j] / (1.0f + __expf(-v1[j])); }
; #pragma unroll
;                     for (int j = 0; j < 8; ++j) part += o[j] * o[j];
;                     u32x4 w; w.x = pk2(o[0], o[1]); w.y = pk2(o[2], o[3]); w.z = pk2(o[4], o[5]); w.w = pk2(o[6], o[7]);
;                     *(u32x4*)(YC + row * D + col) = w; }
;                 part += __shfl_xor(part, 16); part += __shfl_xor(part, 32);
;                 if (fq == 0) (void)__hip_atomic_fetch_add(rss + rl, part, __ATOMIC_RELAXED, __HIP_MEMORY_SCOPE_WORKGROUP); }
	v_mov_b32_e32 v72, v248
	v_mov_b32_e32 v73, v249
	v_mov_b32_e32 v74, v250
	v_mov_b32_e32 v75, v251
	v_lshlrev_b32_e32 v86, 16, v72
	v_and_b32_e32 v72, 0xffff0000, v72
	v_div_scale_f32 v87, s[2:3], v69, v69, v72
	v_rcp_f32_e32 v88, v87
	s_nop 0
	v_fma_f32 v89, -v87, v88, 1.0
	v_fmac_f32_e32 v88, v89, v88
	v_div_scale_f32 v89, vcc, v72, v69, v72
	v_mul_f32_e32 v90, v89, v88
	v_fma_f32 v91, -v87, v90, v89
	v_fmac_f32_e32 v90, v91, v88
	v_fma_f32 v87, -v87, v90, v89
	v_div_fmas_f32 v87, v87, v88, v90
	v_div_fixup_f32 v69, v87, v69, v72
	v_div_scale_f32 v72, s[2:3], v68, v68, v86
	v_rcp_f32_e32 v87, v72
	s_nop 0
	v_fma_f32 v88, -v72, v87, 1.0
	v_fmac_f32_e32 v87, v88, v87
	v_div_scale_f32 v88, vcc, v86, v68, v86
	v_mul_f32_e32 v89, v88, v87
	v_fma_f32 v90, -v72, v89, v88
	v_fmac_f32_e32 v89, v90, v87
	v_fma_f32 v72, -v72, v89, v88
	v_div_fmas_f32 v72, v72, v87, v89
	v_div_fixup_f32 v68, v72, v68, v86
	v_lshlrev_b32_e32 v72, 16, v74
	v_and_b32_e32 v74, 0xffff0000, v74
	v_div_scale_f32 v86, s[2:3], v65, v65, v74
	v_rcp_f32_e32 v87, v86
	s_nop 0
	v_fma_f32 v88, -v86, v87, 1.0
	v_fmac_f32_e32 v87, v88, v87
	v_div_scale_f32 v88, vcc, v74, v65, v74
	v_mul_f32_e32 v89, v88, v87
	v_fma_f32 v90, -v86, v89, v88
	v_fmac_f32_e32 v89, v90, v87
	v_fma_f32 v86, -v86, v89, v88
	v_div_fmas_f32 v86, v86, v87, v89
	v_div_fixup_f32 v65, v86, v65, v74
	v_div_scale_f32 v74, s[2:3], v64, v64, v72
	v_rcp_f32_e32 v86, v74
	s_nop 0
	v_fma_f32 v87, -v74, v86, 1.0
	v_fmac_f32_e32 v86, v87, v86
	v_div_scale_f32 v87, vcc, v72, v64, v72
	v_mul_f32_e32 v88, v87, v86
	v_fma_f32 v89, -v74, v88, v87
	v_fmac_f32_e32 v88, v89, v86
	v_fma_f32 v74, -v74, v88, v87
	v_div_fmas_f32 v74, v74, v86, v88
	v_div_fixup_f32 v64, v74, v64, v72
	v_lshlrev_b32_e32 v72, 16, v73
	v_and_b32_e32 v73, 0xffff0000, v73
	v_div_scale_f32 v74, s[2:3], v71, v71, v73
	v_rcp_f32_e32 v86, v74
	s_nop 0
	v_fma_f32 v87, -v74, v86, 1.0
	v_fmac_f32_e32 v86, v87, v86
	v_div_scale_f32 v87, vcc, v73, v71, v73
	v_mul_f32_e32 v88, v87, v86
	v_fma_f32 v89, -v74, v88, v87
	v_fmac_f32_e32 v88, v89, v86
	v_fma_f32 v74, -v74, v88, v87
	v_div_fmas_f32 v74, v74, v86, v88
	v_div_fixup_f32 v71, v74, v71, v73
	v_div_scale_f32 v73, s[2:3], v70, v70, v72
	v_rcp_f32_e32 v74, v73
	s_nop 0
	v_fma_f32 v86, -v73, v74, 1.0
	v_fmac_f32_e32 v74, v86, v74
	v_div_scale_f32 v86, vcc, v72, v70, v72
	v_mul_f32_e32 v87, v86, v74
	v_fma_f32 v88, -v73, v87, v86
	v_fmac_f32_e32 v87, v88, v74
	v_fma_f32 v73, -v73, v87, v86
	v_div_fmas_f32 v73, v73, v74, v87
	v_div_fixup_f32 v70, v73, v70, v72
	v_and_b32_e32 v73, 0xffff0000, v75
	v_div_scale_f32 v74, s[2:3], v67, v67, v73
	v_lshlrev_b32_e32 v72, 16, v75
	v_rcp_f32_e32 v75, v74
	s_nop 0
	v_fma_f32 v86, -v74, v75, 1.0
	v_fmac_f32_e32 v75, v86, v75
	v_div_scale_f32 v86, vcc, v73, v67, v73
	v_mul_f32_e32 v87, v86, v75
	v_fma_f32 v88, -v74, v87, v86
	v_fmac_f32_e32 v87, v88, v75
	v_fma_f32 v74, -v74, v87, v86
	v_div_fmas_f32 v74, v74, v75, v87
	v_div_fixup_f32 v73, v74, v67, v73
	v_div_scale_f32 v67, s[2:3], v66, v66, v72
	v_rcp_f32_e32 v74, v67
	s_nop 0
	v_fma_f32 v75, -v67, v74, 1.0
	v_fmac_f32_e32 v74, v75, v74
	v_div_scale_f32 v75, vcc, v72, v66, v72
	v_mul_f32_e32 v86, v75, v74
	v_fma_f32 v87, -v67, v86, v75
	v_fmac_f32_e32 v86, v87, v74
	v_fma_f32 v67, -v67, v86, v75
	v_div_fmas_f32 v67, v67, v74, v86
	v_div_fixup_f32 v72, v67, v66, v72
	v_pk_mul_f32 v[66:67], v[68:69], v[68:69]
	v_pk_mul_f32 v[74:75], v[70:71], v[70:71]
	v_add_f32_e32 v66, v66, v78
	v_add_f32_e32 v66, v67, v66
	v_add_f32_e32 v66, v74, v66
	v_pk_mul_f32 v[86:87], v[64:65], v[64:65]
	v_add_f32_e32 v66, v75, v66
	v_add_f32_e32 v66, v86, v66
	v_pk_mul_f32 v[88:89], v[72:73], v[72:73]
	v_add_f32_e32 v66, v87, v66
	v_add_f32_e32 v66, v88, v66
	v_add_f32_e32 v74, v89, v66
	v_cvt_pk_bf16_f32 v66, v68, v69
	v_cvt_pk_bf16_f32 v68, v64, v65
	ds_bpermute_b32 v64, v186, v74
	v_cvt_pk_bf16_f32 v67, v70, v71
	v_cvt_pk_bf16_f32 v69, v72, v73
	global_store_dwordx4 v[76:77], v[66:69], off offset:256
	s_waitcnt lgkmcnt(0)
	v_add_f32_e32 v64, v74, v64
	ds_bpermute_b32 v65, v185, v64
	s_and_saveexec_b64 s[2:3], s[38:39]
	s_cbranch_execz .LBB0_65
	s_waitcnt lgkmcnt(0)
	v_add_f32_e32 v64, v64, v65
	ds_add_f32 v252, v64
.LBB0_65:
	s_or_b64 exec, exec, s[2:3]
	s_waitcnt lgkmcnt(0)
	v_lshl_add_u64 v[64:65], s[18:19], 0, v[148:149]
	v_lshlrev_b64 v[66:67], 10, v[64:65]
	v_lshlrev_b64 v[72:73], 12, v[64:65]
	v_lshl_add_u64 v[64:65], s[4:5], 0, v[66:67]
	v_lshl_add_u64 v[70:71], v[64:65], 0, v[160:161]
	s_movk_i32 s96, 0x4000
	s_mov_b32 s97, 0
	global_load_dwordx4 v[220:223], v[70:71], off
	global_load_dwordx4 v[224:227], v[70:71], off offset:256
	v_lshl_add_u64 v[192:193], v[70:71], 0, s[96:97]
	global_load_dwordx4 v[228:231], v[192:193], off
	global_load_dwordx4 v[232:235], v[192:193], off offset:256
	v_lshl_add_u64 v[192:193], v[192:193], 0, s[96:97]
	global_load_dwordx4 v[236:239], v[192:193], off
	global_load_dwordx4 v[240:243], v[192:193], off offset:256
	v_lshl_add_u64 v[192:193], v[192:193], 0, s[96:97]
	global_load_dwordx4 v[244:247], v[192:193], off
	global_load_dwordx4 v[248:251], v[192:193], off offset:256
	v_mul_f32_e32 v60, 0xbfb8aa3b, v60
	v_mul_f32_e32 v61, 0xbfb8aa3b, v61
	v_exp_f32_e32 v60, v60
	v_exp_f32_e32 v61, v61
	v_mul_f32_e32 v56, 0xbfb8aa3b, v56
	v_mul_f32_e32 v57, 0xbfb8aa3b, v57
	v_exp_f32_e32 v56, v56
	v_pk_add_f32 v[60:61], v[60:61], 1.0 op_sel_hi:[1,0]
	v_exp_f32_e32 v57, v57
	v_mul_f32_e32 v52, 0xbfb8aa3b, v52
	v_mul_f32_e32 v53, 0xbfb8aa3b, v53
	v_exp_f32_e32 v52, v52
	v_pk_add_f32 v[56:57], v[56:57], 1.0 op_sel_hi:[1,0]
	v_exp_f32_e32 v53, v53
	v_mul_f32_e32 v48, 0xbfb8aa3b, v48
	v_mul_f32_e32 v49, 0xbfb8aa3b, v49
	v_exp_f32_e32 v48, v48
	v_pk_add_f32 v[52:53], v[52:53], 1.0 op_sel_hi:[1,0]
	v_exp_f32_e32 v49, v49
	v_mul_f32_e32 v54, 0xbfb8aa3b, v54
	v_mul_f32_e32 v55, 0xbfb8aa3b, v55
	v_exp_f32_e32 v54, v54
	v_pk_add_f32 v[48:49], v[48:49], 1.0 op_sel_hi:[1,0]
	v_exp_f32_e32 v55, v55
	v_mul_f32_e32 v50, 0xbfb8aa3b, v50
	v_mul_f32_e32 v51, 0xbfb8aa3b, v51
	v_exp_f32_e32 v50, v50
	v_pk_add_f32 v[54:55], v[54:55], 1.0 op_sel_hi:[1,0]
	v_exp_f32_e32 v51, v51
	s_waitcnt vmcnt(7)
; __device__ __forceinline__ unsigned pk2(float lo, float hi) { const f32x2 v = {lo, hi}; return __builtin_bit_cast(unsigned, __builtin_convertvector(v, bf16x2_t)); }
; __device__ __forceinline__ void unpack8(u32x4 w, float* f) { f[0] = bflo(w.x); f[1] = bfhi(w.x); f[2] = bflo(w.y); f[3] = bfhi(w.y); f[4] = bflo(w.z); f[5] = bfhi(w.z); f[6] = bflo(w.w); f[7] = bfhi(w.w); }
;     __device__ __forceinline__ void operator()(const f32x4 (&acc)[2][2][4][2], const Unit& u, int wr, int wc, int fr, int fq) const {
;     ...
;                 for (int bj = 0; bj < 2; ++bj) { const int col = col0 + bj * HALF; const u32x4 yw = *(const u32x4*)(YG + row * 512 + col); float y[8], o[8]; unpack8(yw, y);
;                     const f32x4 v0 = acc[ai][bj][m][0], v1 = acc[ai][bj][m][1];
; #pragma unroll
;                     for (int j = 0; j < 4; ++j) { o[j] = y[j] / (1.0f + __expf(-v0[j])); o[4 + j] = y[4 + j] / (1.0f + __expf(-v1[j])); }
; #pragma unroll
;                     for (int j = 0; j < 8; ++j) part += o[j] * o[j];
;                     u32x4 w; w.x = pk2(o[0], o[1]); w.y = pk2(o[2], o[3]); w.z = pk2(o[4], o[5]); w.w = pk2(o[6], o[7]);
;                     *(u32x4*)(YC + row * D + col) = w; }
	v_mov_b32_e32 v64, v220
	v_mov_b32_e32 v65, v221
	v_mov_b32_e32 v66, v222
	v_mov_b32_e32 v67, v223
	v_lshlrev_b32_e32 v68, 16, v64
	v_and_b32_e32 v64, 0xffff0000, v64
	v_div_scale_f32 v69, s[2:3], v61, v61, v64
	v_rcp_f32_e32 v74, v69
	v_pk_add_f32 v[50:51], v[50:51], 1.0 op_sel_hi:[1,0]
	v_fma_f32 v75, -v69, v74, 1.0
	v_fmac_f32_e32 v74, v75, v74
	v_div_scale_f32 v75, vcc, v64, v61, v64
	v_mul_f32_e32 v76, v75, v74
	v_fma_f32 v77, -v69, v76, v75
	v_fmac_f32_e32 v76, v77, v74
	v_fma_f32 v69, -v69, v76, v75
	v_div_fmas_f32 v69, v69, v74, v76
	v_div_fixup_f32 v61, v69, v61, v64
	v_div_scale_f32 v64, s[2:3], v60, v60, v68
	v_rcp_f32_e32 v69, v64
	s_nop 0
	v_fma_f32 v74, -v64, v69, 1.0
	v_fmac_f32_e32 v69, v74, v69
	v_div_scale_f32 v74, vcc, v68, v60, v68
	v_mul_f32_e32 v75, v74, v69
	v_fma_f32 v76, -v64, v75, v74
	v_fmac_f32_e32 v75, v76, v69
	v_fma_f32 v64, -v64, v75, v74
	v_div_fmas_f32 v64, v64, v69, v75
	v_div_fixup_f32 v60, v64, v60, v68
	v_lshlrev_b32_e32 v64, 16, v66
	v_and_b32_e32 v66, 0xffff0000, v66
	v_div_scale_f32 v68, s[2:3], v57, v57, v66
	v_rcp_f32_e32 v69, v68
	s_nop 0
	v_fma_f32 v74, -v68, v69, 1.0
	v_fmac_f32_e32 v69, v74, v69
	v_div_scale_f32 v74, vcc, v66, v57, v66
	v_mul_f32_e32 v75, v74, v69
	v_fma_f32 v76, -v68, v75, v74
	v_fmac_f32_e32 v75, v76, v69
	v_fma_f32 v68, -v68, v75, v74
	v_div_fmas_f32 v68, v68, v69, v75
	v_div_fixup_f32 v75, v68, v57, v66
	v_div_scale_f32 v57, s[2:3], v56, v56, v64
	v_rcp_f32_e32 v66, v57
	s_nop 0
	v_fma_f32 v68, -v57, v66, 1.0
	v_fmac_f32_e32 v66, v68, v66
	v_div_scale_f32 v68, vcc, v64, v56, v64
	v_mul_f32_e32 v69, v68, v66
	v_fma_f32 v74, -v57, v69, v68
	v_fmac_f32_e32 v69, v74, v66
	v_fma_f32 v57, -v57, v69, v68
	v_div_fmas_f32 v57, v57, v66, v69
	v_div_fixup_f32 v74, v57, v56, v64
	v_mul_f32_e32 v57, 0xbfb8aa3b, v58
	v_mul_f32_e32 v56, 0xbfb8aa3b, v62
	v_exp_f32_e32 v58, v57
	v_mul_f32_e32 v57, 0xbfb8aa3b, v63
	v_exp_f32_e32 v56, v56
	v_exp_f32_e32 v57, v57
	v_and_b32_e32 v63, 0xffff0000, v65
	v_lshlrev_b32_e32 v62, 16, v65
	v_pk_add_f32 v[56:57], v[56:57], 1.0 op_sel_hi:[1,0]
	s_nop 0
	v_div_scale_f32 v64, s[2:3], v57, v57, v63
	v_rcp_f32_e32 v65, v64
	s_nop 0
	v_fma_f32 v66, -v64, v65, 1.0
	v_fmac_f32_e32 v65, v66, v65
	v_div_scale_f32 v66, vcc, v63, v57, v63
	v_mul_f32_e32 v68, v66, v65
	v_fma_f32 v69, -v64, v68, v66
	v_fmac_f32_e32 v68, v69, v65
	v_fma_f32 v64, -v64, v68, v66
	v_div_fmas_f32 v64, v64, v65, v68
	v_div_fixup_f32 v77, v64, v57, v63
	v_div_scale_f32 v57, s[2:3], v56, v56, v62
	v_rcp_f32_e32 v63, v57
	v_pk_mul_f32 v[68:69], v[60:61], v[60:61]
	v_fma_f32 v64, -v57, v63, 1.0
	v_fmac_f32_e32 v63, v64, v63
	v_div_scale_f32 v64, vcc, v62, v56, v62
	v_mul_f32_e32 v65, v64, v63
	v_fma_f32 v66, -v57, v65, v64
	v_fmac_f32_e32 v65, v66, v63
	v_fma_f32 v57, -v57, v65, v64
	v_div_fmas_f32 v57, v57, v63, v65
	v_div_fixup_f32 v76, v57, v56, v62
	v_mul_f32_e32 v56, 0xbfb8aa3b, v59
	v_exp_f32_e32 v59, v56
	v_and_b32_e32 v63, 0xffff0000, v67
	v_lshlrev_b32_e32 v62, 16, v67
	v_add_f32_e32 v68, v68, v69
	v_pk_add_f32 v[56:57], v[58:59], 1.0 op_sel_hi:[1,0]
	s_nop 0
	v_div_scale_f32 v58, s[2:3], v57, v57, v63
	v_rcp_f32_e32 v59, v58
	s_nop 0
	v_fma_f32 v64, -v58, v59, 1.0
	v_fmac_f32_e32 v59, v64, v59
	v_div_scale_f32 v64, vcc, v63, v57, v63
	v_mul_f32_e32 v65, v64, v59
	v_fma_f32 v66, -v58, v65, v64
	v_fmac_f32_e32 v65, v66, v59
	v_fma_f32 v58, -v58, v65, v64
	v_div_fmas_f32 v58, v58, v59, v65
	v_div_fixup_f32 v79, v58, v57, v63
	v_div_scale_f32 v57, s[2:3], v56, v56, v62
	v_rcp_f32_e32 v58, v57
	v_pk_mul_f32 v[66:67], v[76:77], v[76:77]
	v_fma_f32 v59, -v57, v58, 1.0
	v_fmac_f32_e32 v58, v59, v58
	v_div_scale_f32 v59, vcc, v62, v56, v62
	v_mul_f32_e32 v63, v59, v58
	v_fma_f32 v64, -v57, v63, v59
	v_fmac_f32_e32 v63, v64, v58
	v_fma_f32 v57, -v57, v63, v59
	v_div_fmas_f32 v57, v57, v58, v63
	v_div_fixup_f32 v78, v57, v56, v62
	v_cvt_pk_bf16_f32 v56, v60, v61
	v_lshl_add_u64 v[60:61], s[94:95], 0, v[72:73]
	v_cvt_pk_bf16_f32 v57, v76, v77
	v_cvt_pk_bf16_f32 v58, v74, v75
	v_cvt_pk_bf16_f32 v59, v78, v79
	v_lshl_add_u64 v[60:61], v[60:61], 0, v[160:161]
	global_store_dwordx4 v[60:61], v[56:59], off
	v_pk_mul_f32 v[64:65], v[74:75], v[74:75]
	v_add_f32_e32 v66, v66, v68
	v_add_f32_e32 v66, v67, v66
	v_add_f32_e32 v64, v64, v66
	v_pk_mul_f32 v[62:63], v[78:79], v[78:79]
	v_add_f32_e32 v64, v65, v64
	v_add_f32_e32 v62, v62, v64
	v_add_f32_e32 v62, v63, v62
	s_waitcnt vmcnt(7)
; __device__ __forceinline__ unsigned pk2(float lo, float hi) { const f32x2 v = {lo, hi}; return __builtin_bit_cast(unsigned, __builtin_convertvector(v, bf16x2_t)); }
; __device__ __forceinline__ void unpack8(u32x4 w, float* f) { f[0] = bflo(w.x); f[1] = bfhi(w.x); f[2] = bflo(w.y); f[3] = bfhi(w.y); f[4] = bflo(w.z); f[5] = bfhi(w.z); f[6] = bflo(w.w); f[7] = bfhi(w.w); }
;     __device__ __forceinline__ void operator()(const f32x4 (&acc)[2][2][4][2], const Unit& u, int wr, int wc, int fr, int fq) const {
;     ...
;             for (int m = 0; m < 4; ++m) { const int rl = wr * 64 + fr + ai * HALF + m * 16; const size_t row = (size_t)u.pm * BM + rl; float part = 0.f;
; #pragma unroll
;                 for (int bj = 0; bj < 2; ++bj) { const int col = col0 + bj * HALF; const u32x4 yw = *(const u32x4*)(YG + row * 512 + col); float y[8], o[8]; unpack8(yw, y);
;                     const f32x4 v0 = acc[ai][bj][m][0], v1 = acc[ai][bj][m][1];
; #pragma unroll
;                     for (int j = 0; j < 4; ++j) { o[j] = y[j] / (1.0f + __expf(-v0[j])); o[4 + j] = y[4 + j] / (1.0f + __expf(-v1[j])); }
; #pragma unroll
;                     for (int j = 0; j < 8; ++j) part += o[j] * o[j];
;                     u32x4 w; w.x = pk2(o[0], o[1]); w.y = pk2(o[2], o[3]); w.z = pk2(o[4], o[5]); w.w = pk2(o[6], o[7]);
;                     *(u32x4*)(YC + row * D + col) = w; }
;                 part += __shfl_xor(part, 16); part += __shfl_xor(part, 32);
;                 if (fq == 0) (void)__hip_atomic_fetch_add(rss + rl, part, __ATOMIC_RELAXED, __HIP_MEMORY_SCOPE_WORKGROUP); }
	v_mov_b32_e32 v56, v224
	v_mov_b32_e32 v57, v225
	v_mov_b32_e32 v58, v226
	v_mov_b32_e32 v59, v227
	v_lshlrev_b32_e32 v70, 16, v56
	v_and_b32_e32 v56, 0xffff0000, v56
	v_div_scale_f32 v71, s[2:3], v53, v53, v56
	v_rcp_f32_e32 v72, v71
	s_nop 0
	v_fma_f32 v73, -v71, v72, 1.0
	v_fmac_f32_e32 v72, v73, v72
	v_div_scale_f32 v73, vcc, v56, v53, v56
	v_mul_f32_e32 v74, v73, v72
	v_fma_f32 v75, -v71, v74, v73
	v_fmac_f32_e32 v74, v75, v72
	v_fma_f32 v71, -v71, v74, v73
	v_div_fmas_f32 v71, v71, v72, v74
	v_div_fixup_f32 v53, v71, v53, v56
	v_div_scale_f32 v56, s[2:3], v52, v52, v70
	v_rcp_f32_e32 v71, v56
	s_nop 0
	v_fma_f32 v72, -v56, v71, 1.0
	v_fmac_f32_e32 v71, v72, v71
	v_div_scale_f32 v72, vcc, v70, v52, v70
	v_mul_f32_e32 v73, v72, v71
	v_fma_f32 v74, -v56, v73, v72
	v_fmac_f32_e32 v73, v74, v71
	v_fma_f32 v56, -v56, v73, v72
	v_div_fmas_f32 v56, v56, v71, v73
	v_div_fixup_f32 v52, v56, v52, v70
	v_lshlrev_b32_e32 v56, 16, v58
	v_and_b32_e32 v58, 0xffff0000, v58
	v_div_scale_f32 v70, s[2:3], v49, v49, v58
	v_rcp_f32_e32 v71, v70
	s_nop 0
	v_fma_f32 v72, -v70, v71, 1.0
	v_fmac_f32_e32 v71, v72, v71
	v_div_scale_f32 v72, vcc, v58, v49, v58
	v_mul_f32_e32 v73, v72, v71
	v_fma_f32 v74, -v70, v73, v72
	v_fmac_f32_e32 v73, v74, v71
	v_fma_f32 v70, -v70, v73, v72
	v_div_fmas_f32 v70, v70, v71, v73
	v_div_fixup_f32 v49, v70, v49, v58
	v_div_scale_f32 v58, s[2:3], v48, v48, v56
	v_rcp_f32_e32 v70, v58
	s_nop 0
	v_fma_f32 v71, -v58, v70, 1.0
	v_fmac_f32_e32 v70, v71, v70
	v_div_scale_f32 v71, vcc, v56, v48, v56
	v_mul_f32_e32 v72, v71, v70
	v_fma_f32 v73, -v58, v72, v71
	v_fmac_f32_e32 v72, v73, v70
	v_fma_f32 v58, -v58, v72, v71
	v_div_fmas_f32 v58, v58, v70, v72
	v_div_fixup_f32 v48, v58, v48, v56
	v_lshlrev_b32_e32 v56, 16, v57
	v_and_b32_e32 v57, 0xffff0000, v57
	v_div_scale_f32 v58, s[2:3], v55, v55, v57
	v_rcp_f32_e32 v70, v58
	s_nop 0
	v_fma_f32 v71, -v58, v70, 1.0
	v_fmac_f32_e32 v70, v71, v70
	v_div_scale_f32 v71, vcc, v57, v55, v57
	v_mul_f32_e32 v72, v71, v70
	v_fma_f32 v73, -v58, v72, v71
	v_fmac_f32_e32 v72, v73, v70
	v_fma_f32 v58, -v58, v72, v71
	v_div_fmas_f32 v58, v58, v70, v72
	v_div_fixup_f32 v55, v58, v55, v57
	v_div_scale_f32 v57, s[2:3], v54, v54, v56
	v_rcp_f32_e32 v58, v57
	s_nop 0
	v_fma_f32 v70, -v57, v58, 1.0
	v_fmac_f32_e32 v58, v70, v58
	v_div_scale_f32 v70, vcc, v56, v54, v56
	v_mul_f32_e32 v71, v70, v58
	v_fma_f32 v72, -v57, v71, v70
	v_fmac_f32_e32 v71, v72, v58
	v_fma_f32 v57, -v57, v71, v70
	v_div_fmas_f32 v57, v57, v58, v71
	v_div_fixup_f32 v54, v57, v54, v56
	v_and_b32_e32 v57, 0xffff0000, v59
	v_div_scale_f32 v58, s[2:3], v51, v51, v57
	v_lshlrev_b32_e32 v56, 16, v59
	v_rcp_f32_e32 v59, v58
	s_nop 0
	v_fma_f32 v70, -v58, v59, 1.0
	v_fmac_f32_e32 v59, v70, v59
	v_div_scale_f32 v70, vcc, v57, v51, v57
	v_mul_f32_e32 v71, v70, v59
	v_fma_f32 v72, -v58, v71, v70
	v_fmac_f32_e32 v71, v72, v59
	v_fma_f32 v58, -v58, v71, v70
	v_div_fmas_f32 v58, v58, v59, v71
	v_div_fixup_f32 v57, v58, v51, v57
	v_div_scale_f32 v51, s[2:3], v50, v50, v56
	v_rcp_f32_e32 v58, v51
	s_nop 0
	v_fma_f32 v59, -v51, v58, 1.0
	v_fmac_f32_e32 v58, v59, v58
	v_div_scale_f32 v59, vcc, v56, v50, v56
	v_mul_f32_e32 v70, v59, v58
	v_fma_f32 v71, -v51, v70, v59
	v_fmac_f32_e32 v70, v71, v58
	v_fma_f32 v51, -v51, v70, v59
	v_div_fmas_f32 v51, v51, v58, v70
	v_div_fixup_f32 v56, v51, v50, v56
	v_pk_mul_f32 v[50:51], v[52:53], v[52:53]
	v_pk_mul_f32 v[58:59], v[54:55], v[54:55]
	v_add_f32_e32 v50, v50, v62
	v_add_f32_e32 v50, v51, v50
	v_add_f32_e32 v50, v58, v50
	v_pk_mul_f32 v[70:71], v[48:49], v[48:49]
	v_add_f32_e32 v50, v59, v50
	v_add_f32_e32 v50, v70, v50
	v_pk_mul_f32 v[72:73], v[56:57], v[56:57]
	v_add_f32_e32 v50, v71, v50
	v_add_f32_e32 v50, v72, v50
	v_add_f32_e32 v58, v73, v50
	v_cvt_pk_bf16_f32 v50, v52, v53
	v_cvt_pk_bf16_f32 v52, v48, v49
	ds_bpermute_b32 v48, v186, v58
	v_cvt_pk_bf16_f32 v51, v54, v55
	v_cvt_pk_bf16_f32 v53, v56, v57
	global_store_dwordx4 v[60:61], v[50:53], off offset:256
	s_waitcnt lgkmcnt(0)
	v_add_f32_e32 v48, v58, v48
	ds_bpermute_b32 v49, v185, v48
	s_and_saveexec_b64 s[2:3], s[38:39]
	s_cbranch_execz .LBB0_67
	s_waitcnt lgkmcnt(0)
	v_add_f32_e32 v48, v48, v49
	ds_add_f32 v165, v48
.LBB0_67:
	s_or_b64 exec, exec, s[2:3]
	s_waitcnt lgkmcnt(0)
	v_lshl_add_u64 v[48:49], s[18:19], 0, v[150:151]
	v_lshlrev_b64 v[50:51], 10, v[48:49]
	v_lshlrev_b64 v[56:57], 12, v[48:49]
	v_lshl_add_u64 v[48:49], s[4:5], 0, v[50:51]
	v_lshl_add_u64 v[54:55], v[48:49], 0, v[160:161]
	v_mul_f32_e32 v44, 0xbfb8aa3b, v44
	v_mul_f32_e32 v45, 0xbfb8aa3b, v45
	v_exp_f32_e32 v44, v44
	v_exp_f32_e32 v45, v45
	v_mul_f32_e32 v40, 0xbfb8aa3b, v40
	v_mul_f32_e32 v41, 0xbfb8aa3b, v41
	v_exp_f32_e32 v40, v40
	v_pk_add_f32 v[44:45], v[44:45], 1.0 op_sel_hi:[1,0]
	v_exp_f32_e32 v41, v41
	v_mul_f32_e32 v36, 0xbfb8aa3b, v36
	v_mul_f32_e32 v37, 0xbfb8aa3b, v37
	v_exp_f32_e32 v36, v36
	v_pk_add_f32 v[40:41], v[40:41], 1.0 op_sel_hi:[1,0]
	v_exp_f32_e32 v37, v37
	v_mul_f32_e32 v32, 0xbfb8aa3b, v32
	v_mul_f32_e32 v33, 0xbfb8aa3b, v33
	v_exp_f32_e32 v32, v32
	v_pk_add_f32 v[36:37], v[36:37], 1.0 op_sel_hi:[1,0]
	v_exp_f32_e32 v33, v33
	v_mul_f32_e32 v38, 0xbfb8aa3b, v38
	v_mul_f32_e32 v39, 0xbfb8aa3b, v39
	v_exp_f32_e32 v38, v38
	v_pk_add_f32 v[32:33], v[32:33], 1.0 op_sel_hi:[1,0]
	v_exp_f32_e32 v39, v39
	v_mul_f32_e32 v34, 0xbfb8aa3b, v34
	v_mul_f32_e32 v35, 0xbfb8aa3b, v35
	v_exp_f32_e32 v34, v34
	v_pk_add_f32 v[38:39], v[38:39], 1.0 op_sel_hi:[1,0]
	v_exp_f32_e32 v35, v35
	s_waitcnt vmcnt(7)
; __device__ __forceinline__ unsigned pk2(float lo, float hi) { const f32x2 v = {lo, hi}; return __builtin_bit_cast(unsigned, __builtin_convertvector(v, bf16x2_t)); }
; __device__ __forceinline__ void unpack8(u32x4 w, float* f) { f[0] = bflo(w.x); f[1] = bfhi(w.x); f[2] = bflo(w.y); f[3] = bfhi(w.y); f[4] = bflo(w.z); f[5] = bfhi(w.z); f[6] = bflo(w.w); f[7] = bfhi(w.w); }
;     __device__ __forceinline__ void operator()(const f32x4 (&acc)[2][2][4][2], const Unit& u, int wr, int wc, int fr, int fq) const {
;     ...
;                 for (int bj = 0; bj < 2; ++bj) { const int col = col0 + bj * HALF; const u32x4 yw = *(const u32x4*)(YG + row * 512 + col); float y[8], o[8]; unpack8(yw, y);
;                     const f32x4 v0 = acc[ai][bj][m][0], v1 = acc[ai][bj][m][1];
; #pragma unroll
;                     for (int j = 0; j < 4; ++j) { o[j] = y[j] / (1.0f + __expf(-v0[j])); o[4 + j] = y[4 + j] / (1.0f + __expf(-v1[j])); }
; #pragma unroll
;                     for (int j = 0; j < 8; ++j) part += o[j] * o[j];
;                     u32x4 w; w.x = pk2(o[0], o[1]); w.y = pk2(o[2], o[3]); w.z = pk2(o[4], o[5]); w.w = pk2(o[6], o[7]);
;                     *(u32x4*)(YC + row * D + col) = w; }
	v_mov_b32_e32 v48, v228
	v_mov_b32_e32 v49, v229
	v_mov_b32_e32 v50, v230
	v_mov_b32_e32 v51, v231
	v_lshlrev_b32_e32 v52, 16, v48
	v_and_b32_e32 v48, 0xffff0000, v48
	v_div_scale_f32 v53, s[2:3], v45, v45, v48
	v_rcp_f32_e32 v58, v53
	v_pk_add_f32 v[34:35], v[34:35], 1.0 op_sel_hi:[1,0]
	v_fma_f32 v59, -v53, v58, 1.0
	v_fmac_f32_e32 v58, v59, v58
	v_div_scale_f32 v59, vcc, v48, v45, v48
	v_mul_f32_e32 v60, v59, v58
	v_fma_f32 v61, -v53, v60, v59
	v_fmac_f32_e32 v60, v61, v58
	v_fma_f32 v53, -v53, v60, v59
	v_div_fmas_f32 v53, v53, v58, v60
	v_div_fixup_f32 v45, v53, v45, v48
	v_div_scale_f32 v48, s[2:3], v44, v44, v52
	v_rcp_f32_e32 v53, v48
	s_nop 0
	v_fma_f32 v58, -v48, v53, 1.0
	v_fmac_f32_e32 v53, v58, v53
	v_div_scale_f32 v58, vcc, v52, v44, v52
	v_mul_f32_e32 v59, v58, v53
	v_fma_f32 v60, -v48, v59, v58
	v_fmac_f32_e32 v59, v60, v53
	v_fma_f32 v48, -v48, v59, v58
	v_div_fmas_f32 v48, v48, v53, v59
	v_div_fixup_f32 v44, v48, v44, v52
	v_lshlrev_b32_e32 v48, 16, v50
	v_and_b32_e32 v50, 0xffff0000, v50
	v_div_scale_f32 v52, s[2:3], v41, v41, v50
	v_rcp_f32_e32 v53, v52
	s_nop 0
	v_fma_f32 v58, -v52, v53, 1.0
	v_fmac_f32_e32 v53, v58, v53
	v_div_scale_f32 v58, vcc, v50, v41, v50
	v_mul_f32_e32 v59, v58, v53
	v_fma_f32 v60, -v52, v59, v58
	v_fmac_f32_e32 v59, v60, v53
	v_fma_f32 v52, -v52, v59, v58
	v_div_fmas_f32 v52, v52, v53, v59
	v_div_fixup_f32 v59, v52, v41, v50
	v_div_scale_f32 v41, s[2:3], v40, v40, v48
	v_rcp_f32_e32 v50, v41
	s_nop 0
	v_fma_f32 v52, -v41, v50, 1.0
	v_fmac_f32_e32 v50, v52, v50
	v_div_scale_f32 v52, vcc, v48, v40, v48
	v_mul_f32_e32 v53, v52, v50
	v_fma_f32 v58, -v41, v53, v52
	v_fmac_f32_e32 v53, v58, v50
	v_fma_f32 v41, -v41, v53, v52
	v_div_fmas_f32 v41, v41, v50, v53
	v_div_fixup_f32 v58, v41, v40, v48
	v_mul_f32_e32 v41, 0xbfb8aa3b, v42
	v_mul_f32_e32 v40, 0xbfb8aa3b, v46
	v_exp_f32_e32 v42, v41
	v_mul_f32_e32 v41, 0xbfb8aa3b, v47
	v_exp_f32_e32 v40, v40
	v_exp_f32_e32 v41, v41
	v_and_b32_e32 v47, 0xffff0000, v49
	v_lshlrev_b32_e32 v46, 16, v49
	v_pk_add_f32 v[40:41], v[40:41], 1.0 op_sel_hi:[1,0]
	s_nop 0
	v_div_scale_f32 v48, s[2:3], v41, v41, v47
	v_rcp_f32_e32 v49, v48
	s_nop 0
	v_fma_f32 v50, -v48, v49, 1.0
	v_fmac_f32_e32 v49, v50, v49
	v_div_scale_f32 v50, vcc, v47, v41, v47
	v_mul_f32_e32 v52, v50, v49
	v_fma_f32 v53, -v48, v52, v50
	v_fmac_f32_e32 v52, v53, v49
	v_fma_f32 v48, -v48, v52, v50
	v_div_fmas_f32 v48, v48, v49, v52
	v_div_fixup_f32 v61, v48, v41, v47
	v_div_scale_f32 v41, s[2:3], v40, v40, v46
	v_rcp_f32_e32 v47, v41
	v_pk_mul_f32 v[52:53], v[44:45], v[44:45]
	v_fma_f32 v48, -v41, v47, 1.0
	v_fmac_f32_e32 v47, v48, v47
	v_div_scale_f32 v48, vcc, v46, v40, v46
	v_mul_f32_e32 v49, v48, v47
	v_fma_f32 v50, -v41, v49, v48
	v_fmac_f32_e32 v49, v50, v47
	v_fma_f32 v41, -v41, v49, v48
	v_div_fmas_f32 v41, v41, v47, v49
	v_div_fixup_f32 v60, v41, v40, v46
	v_mul_f32_e32 v40, 0xbfb8aa3b, v43
	v_exp_f32_e32 v43, v40
	v_and_b32_e32 v47, 0xffff0000, v51
	v_lshlrev_b32_e32 v46, 16, v51
	v_add_f32_e32 v52, v52, v53
	v_pk_add_f32 v[40:41], v[42:43], 1.0 op_sel_hi:[1,0]
	s_nop 0
	v_div_scale_f32 v42, s[2:3], v41, v41, v47
	v_rcp_f32_e32 v43, v42
	s_nop 0
	v_fma_f32 v48, -v42, v43, 1.0
	v_fmac_f32_e32 v43, v48, v43
	v_div_scale_f32 v48, vcc, v47, v41, v47
	v_mul_f32_e32 v49, v48, v43
	v_fma_f32 v50, -v42, v49, v48
	v_fmac_f32_e32 v49, v50, v43
	v_fma_f32 v42, -v42, v49, v48
	v_div_fmas_f32 v42, v42, v43, v49
	v_div_fixup_f32 v63, v42, v41, v47
	v_div_scale_f32 v41, s[2:3], v40, v40, v46
	v_rcp_f32_e32 v42, v41
	v_pk_mul_f32 v[50:51], v[60:61], v[60:61]
	v_fma_f32 v43, -v41, v42, 1.0
	v_fmac_f32_e32 v42, v43, v42
	v_div_scale_f32 v43, vcc, v46, v40, v46
	v_mul_f32_e32 v47, v43, v42
	v_fma_f32 v48, -v41, v47, v43
	v_fmac_f32_e32 v47, v48, v42
	v_fma_f32 v41, -v41, v47, v43
	v_div_fmas_f32 v41, v41, v42, v47
	v_div_fixup_f32 v62, v41, v40, v46
	v_cvt_pk_bf16_f32 v40, v44, v45
	v_lshl_add_u64 v[44:45], s[94:95], 0, v[56:57]
	v_cvt_pk_bf16_f32 v41, v60, v61
	v_cvt_pk_bf16_f32 v42, v58, v59
	v_cvt_pk_bf16_f32 v43, v62, v63
	v_lshl_add_u64 v[44:45], v[44:45], 0, v[160:161]
	global_store_dwordx4 v[44:45], v[40:43], off
	v_pk_mul_f32 v[48:49], v[58:59], v[58:59]
	v_add_f32_e32 v50, v50, v52
	v_add_f32_e32 v50, v51, v50
	v_add_f32_e32 v48, v48, v50
	v_pk_mul_f32 v[46:47], v[62:63], v[62:63]
	v_add_f32_e32 v48, v49, v48
	v_add_f32_e32 v46, v46, v48
	v_add_f32_e32 v46, v47, v46
	s_waitcnt vmcnt(7)
; __device__ __forceinline__ unsigned pk2(float lo, float hi) { const f32x2 v = {lo, hi}; return __builtin_bit_cast(unsigned, __builtin_convertvector(v, bf16x2_t)); }
; __device__ __forceinline__ void unpack8(u32x4 w, float* f) { f[0] = bflo(w.x); f[1] = bfhi(w.x); f[2] = bflo(w.y); f[3] = bfhi(w.y); f[4] = bflo(w.z); f[5] = bfhi(w.z); f[6] = bflo(w.w); f[7] = bfhi(w.w); }
;     __device__ __forceinline__ void operator()(const f32x4 (&acc)[2][2][4][2], const Unit& u, int wr, int wc, int fr, int fq) const {
;     ...
;             for (int m = 0; m < 4; ++m) { const int rl = wr * 64 + fr + ai * HALF + m * 16; const size_t row = (size_t)u.pm * BM + rl; float part = 0.f;
; #pragma unroll
;                 for (int bj = 0; bj < 2; ++bj) { const int col = col0 + bj * HALF; const u32x4 yw = *(const u32x4*)(YG + row * 512 + col); float y[8], o[8]; unpack8(yw, y);
;                     const f32x4 v0 = acc[ai][bj][m][0], v1 = acc[ai][bj][m][1];
; #pragma unroll
;                     for (int j = 0; j < 4; ++j) { o[j] = y[j] / (1.0f + __expf(-v0[j])); o[4 + j] = y[4 + j] / (1.0f + __expf(-v1[j])); }
; #pragma unroll
;                     for (int j = 0; j < 8; ++j) part += o[j] * o[j];
;                     u32x4 w; w.x = pk2(o[0], o[1]); w.y = pk2(o[2], o[3]); w.z = pk2(o[4], o[5]); w.w = pk2(o[6], o[7]);
;                     *(u32x4*)(YC + row * D + col) = w; }
;                 part += __shfl_xor(part, 16); part += __shfl_xor(part, 32);
;                 if (fq == 0) (void)__hip_atomic_fetch_add(rss + rl, part, __ATOMIC_RELAXED, __HIP_MEMORY_SCOPE_WORKGROUP); }
	v_mov_b32_e32 v40, v232
	v_mov_b32_e32 v41, v233
	v_mov_b32_e32 v42, v234
	v_mov_b32_e32 v43, v235
	v_lshlrev_b32_e32 v54, 16, v40
	v_and_b32_e32 v40, 0xffff0000, v40
	v_div_scale_f32 v55, s[2:3], v37, v37, v40
	v_rcp_f32_e32 v56, v55
	s_nop 0
	v_fma_f32 v57, -v55, v56, 1.0
	v_fmac_f32_e32 v56, v57, v56
	v_div_scale_f32 v57, vcc, v40, v37, v40
	v_mul_f32_e32 v58, v57, v56
	v_fma_f32 v59, -v55, v58, v57
	v_fmac_f32_e32 v58, v59, v56
	v_fma_f32 v55, -v55, v58, v57
	v_div_fmas_f32 v55, v55, v56, v58
	v_div_fixup_f32 v37, v55, v37, v40
	v_div_scale_f32 v40, s[2:3], v36, v36, v54
	v_rcp_f32_e32 v55, v40
	s_nop 0
	v_fma_f32 v56, -v40, v55, 1.0
	v_fmac_f32_e32 v55, v56, v55
	v_div_scale_f32 v56, vcc, v54, v36, v54
	v_mul_f32_e32 v57, v56, v55
	v_fma_f32 v58, -v40, v57, v56
	v_fmac_f32_e32 v57, v58, v55
	v_fma_f32 v40, -v40, v57, v56
	v_div_fmas_f32 v40, v40, v55, v57
	v_div_fixup_f32 v36, v40, v36, v54
	v_lshlrev_b32_e32 v40, 16, v42
	v_and_b32_e32 v42, 0xffff0000, v42
	v_div_scale_f32 v54, s[2:3], v33, v33, v42
	v_rcp_f32_e32 v55, v54
	s_nop 0
	v_fma_f32 v56, -v54, v55, 1.0
	v_fmac_f32_e32 v55, v56, v55
	v_div_scale_f32 v56, vcc, v42, v33, v42
	v_mul_f32_e32 v57, v56, v55
	v_fma_f32 v58, -v54, v57, v56
	v_fmac_f32_e32 v57, v58, v55
	v_fma_f32 v54, -v54, v57, v56
	v_div_fmas_f32 v54, v54, v55, v57
	v_div_fixup_f32 v33, v54, v33, v42
	v_div_scale_f32 v42, s[2:3], v32, v32, v40
	v_rcp_f32_e32 v54, v42
	s_nop 0
	v_fma_f32 v55, -v42, v54, 1.0
	v_fmac_f32_e32 v54, v55, v54
	v_div_scale_f32 v55, vcc, v40, v32, v40
	v_mul_f32_e32 v56, v55, v54
	v_fma_f32 v57, -v42, v56, v55
	v_fmac_f32_e32 v56, v57, v54
	v_fma_f32 v42, -v42, v56, v55
	v_div_fmas_f32 v42, v42, v54, v56
	v_div_fixup_f32 v32, v42, v32, v40
	v_lshlrev_b32_e32 v40, 16, v41
	v_and_b32_e32 v41, 0xffff0000, v41
	v_div_scale_f32 v42, s[2:3], v39, v39, v41
	v_rcp_f32_e32 v54, v42
	s_nop 0
	v_fma_f32 v55, -v42, v54, 1.0
	v_fmac_f32_e32 v54, v55, v54
	v_div_scale_f32 v55, vcc, v41, v39, v41
	v_mul_f32_e32 v56, v55, v54
	v_fma_f32 v57, -v42, v56, v55
	v_fmac_f32_e32 v56, v57, v54
	v_fma_f32 v42, -v42, v56, v55
	v_div_fmas_f32 v42, v42, v54, v56
	v_div_fixup_f32 v39, v42, v39, v41
	v_div_scale_f32 v41, s[2:3], v38, v38, v40
	v_rcp_f32_e32 v42, v41
	s_nop 0
	v_fma_f32 v54, -v41, v42, 1.0
	v_fmac_f32_e32 v42, v54, v42
	v_div_scale_f32 v54, vcc, v40, v38, v40
	v_mul_f32_e32 v55, v54, v42
	v_fma_f32 v56, -v41, v55, v54
	v_fmac_f32_e32 v55, v56, v42
	v_fma_f32 v41, -v41, v55, v54
	v_div_fmas_f32 v41, v41, v42, v55
	v_div_fixup_f32 v38, v41, v38, v40
	v_and_b32_e32 v41, 0xffff0000, v43
	v_div_scale_f32 v42, s[2:3], v35, v35, v41
	v_lshlrev_b32_e32 v40, 16, v43
	v_rcp_f32_e32 v43, v42
	s_nop 0
	v_fma_f32 v54, -v42, v43, 1.0
	v_fmac_f32_e32 v43, v54, v43
	v_div_scale_f32 v54, vcc, v41, v35, v41
	v_mul_f32_e32 v55, v54, v43
	v_fma_f32 v56, -v42, v55, v54
	v_fmac_f32_e32 v55, v56, v43
	v_fma_f32 v42, -v42, v55, v54
	v_div_fmas_f32 v42, v42, v43, v55
	v_div_fixup_f32 v41, v42, v35, v41
	v_div_scale_f32 v35, s[2:3], v34, v34, v40
	v_rcp_f32_e32 v42, v35
	s_nop 0
	v_fma_f32 v43, -v35, v42, 1.0
	v_fmac_f32_e32 v42, v43, v42
	v_div_scale_f32 v43, vcc, v40, v34, v40
	v_mul_f32_e32 v54, v43, v42
	v_fma_f32 v55, -v35, v54, v43
	v_fmac_f32_e32 v54, v55, v42
	v_fma_f32 v35, -v35, v54, v43
	v_div_fmas_f32 v35, v35, v42, v54
	v_div_fixup_f32 v40, v35, v34, v40
	v_pk_mul_f32 v[34:35], v[36:37], v[36:37]
	v_pk_mul_f32 v[42:43], v[38:39], v[38:39]
	v_add_f32_e32 v34, v34, v46
	v_add_f32_e32 v34, v35, v34
	v_add_f32_e32 v34, v42, v34
	v_pk_mul_f32 v[54:55], v[32:33], v[32:33]
	v_add_f32_e32 v34, v43, v34
	v_add_f32_e32 v34, v54, v34
	v_pk_mul_f32 v[56:57], v[40:41], v[40:41]
	v_add_f32_e32 v34, v55, v34
	v_add_f32_e32 v34, v56, v34
	v_add_f32_e32 v42, v57, v34
	v_cvt_pk_bf16_f32 v34, v36, v37
	v_cvt_pk_bf16_f32 v36, v32, v33
	ds_bpermute_b32 v32, v186, v42
	v_cvt_pk_bf16_f32 v35, v38, v39
	v_cvt_pk_bf16_f32 v37, v40, v41
	global_store_dwordx4 v[44:45], v[34:37], off offset:256
	s_waitcnt lgkmcnt(0)
	v_add_f32_e32 v32, v42, v32
	ds_bpermute_b32 v33, v185, v32
	s_and_saveexec_b64 s[2:3], s[38:39]
	s_cbranch_execz .LBB0_69
	s_waitcnt lgkmcnt(0)
	v_add_f32_e32 v32, v32, v33
	ds_add_f32 v180, v32
.LBB0_69:
	s_or_b64 exec, exec, s[2:3]
	s_waitcnt lgkmcnt(0)
	v_lshl_add_u64 v[32:33], s[18:19], 0, v[152:153]
	v_lshlrev_b64 v[34:35], 10, v[32:33]
	v_lshlrev_b64 v[40:41], 12, v[32:33]
	v_lshl_add_u64 v[32:33], s[4:5], 0, v[34:35]
	v_lshl_add_u64 v[38:39], v[32:33], 0, v[160:161]
	v_mul_f32_e32 v28, 0xbfb8aa3b, v28
	v_mul_f32_e32 v29, 0xbfb8aa3b, v29
	v_exp_f32_e32 v28, v28
	v_exp_f32_e32 v29, v29
	v_mul_f32_e32 v24, 0xbfb8aa3b, v24
	v_mul_f32_e32 v25, 0xbfb8aa3b, v25
	v_exp_f32_e32 v24, v24
	v_pk_add_f32 v[28:29], v[28:29], 1.0 op_sel_hi:[1,0]
	v_exp_f32_e32 v25, v25
	v_mul_f32_e32 v20, 0xbfb8aa3b, v20
	v_mul_f32_e32 v21, 0xbfb8aa3b, v21
	v_exp_f32_e32 v20, v20
	v_pk_add_f32 v[24:25], v[24:25], 1.0 op_sel_hi:[1,0]
	v_exp_f32_e32 v21, v21
	v_mul_f32_e32 v16, 0xbfb8aa3b, v16
	v_mul_f32_e32 v17, 0xbfb8aa3b, v17
	v_exp_f32_e32 v16, v16
	v_pk_add_f32 v[20:21], v[20:21], 1.0 op_sel_hi:[1,0]
	v_exp_f32_e32 v17, v17
	v_mul_f32_e32 v22, 0xbfb8aa3b, v22
	v_mul_f32_e32 v23, 0xbfb8aa3b, v23
	v_exp_f32_e32 v22, v22
	v_pk_add_f32 v[16:17], v[16:17], 1.0 op_sel_hi:[1,0]
	v_exp_f32_e32 v23, v23
	v_mul_f32_e32 v18, 0xbfb8aa3b, v18
	v_mul_f32_e32 v19, 0xbfb8aa3b, v19
	v_exp_f32_e32 v18, v18
	v_pk_add_f32 v[22:23], v[22:23], 1.0 op_sel_hi:[1,0]
	v_exp_f32_e32 v19, v19
	s_waitcnt vmcnt(7)
; __device__ __forceinline__ unsigned pk2(float lo, float hi) { const f32x2 v = {lo, hi}; return __builtin_bit_cast(unsigned, __builtin_convertvector(v, bf16x2_t)); }
; __device__ __forceinline__ void unpack8(u32x4 w, float* f) { f[0] = bflo(w.x); f[1] = bfhi(w.x); f[2] = bflo(w.y); f[3] = bfhi(w.y); f[4] = bflo(w.z); f[5] = bfhi(w.z); f[6] = bflo(w.w); f[7] = bfhi(w.w); }
;     __device__ __forceinline__ void operator()(const f32x4 (&acc)[2][2][4][2], const Unit& u, int wr, int wc, int fr, int fq) const {
;     ...
;                 for (int bj = 0; bj < 2; ++bj) { const int col = col0 + bj * HALF; const u32x4 yw = *(const u32x4*)(YG + row * 512 + col); float y[8], o[8]; unpack8(yw, y);
;                     const f32x4 v0 = acc[ai][bj][m][0], v1 = acc[ai][bj][m][1];
; #pragma unroll
;                     for (int j = 0; j < 4; ++j) { o[j] = y[j] / (1.0f + __expf(-v0[j])); o[4 + j] = y[4 + j] / (1.0f + __expf(-v1[j])); }
; #pragma unroll
;                     for (int j = 0; j < 8; ++j) part += o[j] * o[j];
;                     u32x4 w; w.x = pk2(o[0], o[1]); w.y = pk2(o[2], o[3]); w.z = pk2(o[4], o[5]); w.w = pk2(o[6], o[7]);
;                     *(u32x4*)(YC + row * D + col) = w; }
	v_mov_b32_e32 v32, v236
	v_mov_b32_e32 v33, v237
	v_mov_b32_e32 v34, v238
	v_mov_b32_e32 v35, v239
	v_lshlrev_b32_e32 v36, 16, v32
	v_and_b32_e32 v32, 0xffff0000, v32
	v_div_scale_f32 v37, s[2:3], v29, v29, v32
	v_rcp_f32_e32 v42, v37
	v_pk_add_f32 v[18:19], v[18:19], 1.0 op_sel_hi:[1,0]
	v_fma_f32 v43, -v37, v42, 1.0
	v_fmac_f32_e32 v42, v43, v42
	v_div_scale_f32 v43, vcc, v32, v29, v32
	v_mul_f32_e32 v44, v43, v42
	v_fma_f32 v45, -v37, v44, v43
	v_fmac_f32_e32 v44, v45, v42
	v_fma_f32 v37, -v37, v44, v43
	v_div_fmas_f32 v37, v37, v42, v44
	v_div_fixup_f32 v29, v37, v29, v32
	v_div_scale_f32 v32, s[2:3], v28, v28, v36
	v_rcp_f32_e32 v37, v32
	s_nop 0
	v_fma_f32 v42, -v32, v37, 1.0
	v_fmac_f32_e32 v37, v42, v37
	v_div_scale_f32 v42, vcc, v36, v28, v36
	v_mul_f32_e32 v43, v42, v37
	v_fma_f32 v44, -v32, v43, v42
	v_fmac_f32_e32 v43, v44, v37
	v_fma_f32 v32, -v32, v43, v42
	v_div_fmas_f32 v32, v32, v37, v43
	v_div_fixup_f32 v28, v32, v28, v36
	v_lshlrev_b32_e32 v32, 16, v34
	v_and_b32_e32 v34, 0xffff0000, v34
	v_div_scale_f32 v36, s[2:3], v25, v25, v34
	v_rcp_f32_e32 v37, v36
	s_nop 0
	v_fma_f32 v42, -v36, v37, 1.0
	v_fmac_f32_e32 v37, v42, v37
	v_div_scale_f32 v42, vcc, v34, v25, v34
	v_mul_f32_e32 v43, v42, v37
	v_fma_f32 v44, -v36, v43, v42
	v_fmac_f32_e32 v43, v44, v37
	v_fma_f32 v36, -v36, v43, v42
	v_div_fmas_f32 v36, v36, v37, v43
	v_div_fixup_f32 v43, v36, v25, v34
	v_div_scale_f32 v25, s[2:3], v24, v24, v32
	v_rcp_f32_e32 v34, v25
	s_nop 0
	v_fma_f32 v36, -v25, v34, 1.0
	v_fmac_f32_e32 v34, v36, v34
	v_div_scale_f32 v36, vcc, v32, v24, v32
	v_mul_f32_e32 v37, v36, v34
	v_fma_f32 v42, -v25, v37, v36
	v_fmac_f32_e32 v37, v42, v34
	v_fma_f32 v25, -v25, v37, v36
	v_div_fmas_f32 v25, v25, v34, v37
	v_div_fixup_f32 v42, v25, v24, v32
	v_mul_f32_e32 v25, 0xbfb8aa3b, v26
	v_mul_f32_e32 v24, 0xbfb8aa3b, v30
	v_exp_f32_e32 v26, v25
	v_mul_f32_e32 v25, 0xbfb8aa3b, v31
	v_exp_f32_e32 v24, v24
	v_exp_f32_e32 v25, v25
	v_and_b32_e32 v31, 0xffff0000, v33
	v_lshlrev_b32_e32 v30, 16, v33
	v_pk_add_f32 v[24:25], v[24:25], 1.0 op_sel_hi:[1,0]
	s_nop 0
	v_div_scale_f32 v32, s[2:3], v25, v25, v31
	v_rcp_f32_e32 v33, v32
	s_nop 0
	v_fma_f32 v34, -v32, v33, 1.0
	v_fmac_f32_e32 v33, v34, v33
	v_div_scale_f32 v34, vcc, v31, v25, v31
	v_mul_f32_e32 v36, v34, v33
	v_fma_f32 v37, -v32, v36, v34
	v_fmac_f32_e32 v36, v37, v33
	v_fma_f32 v32, -v32, v36, v34
	v_div_fmas_f32 v32, v32, v33, v36
	v_div_fixup_f32 v45, v32, v25, v31
	v_div_scale_f32 v25, s[2:3], v24, v24, v30
	v_rcp_f32_e32 v31, v25
	v_pk_mul_f32 v[36:37], v[28:29], v[28:29]
	v_fma_f32 v32, -v25, v31, 1.0
	v_fmac_f32_e32 v31, v32, v31
	v_div_scale_f32 v32, vcc, v30, v24, v30
	v_mul_f32_e32 v33, v32, v31
	v_fma_f32 v34, -v25, v33, v32
	v_fmac_f32_e32 v33, v34, v31
	v_fma_f32 v25, -v25, v33, v32
	v_div_fmas_f32 v25, v25, v31, v33
	v_div_fixup_f32 v44, v25, v24, v30
	v_mul_f32_e32 v24, 0xbfb8aa3b, v27
	v_exp_f32_e32 v27, v24
	v_and_b32_e32 v31, 0xffff0000, v35
	v_lshlrev_b32_e32 v30, 16, v35
	v_add_f32_e32 v36, v36, v37
	v_pk_add_f32 v[24:25], v[26:27], 1.0 op_sel_hi:[1,0]
	s_nop 0
	v_div_scale_f32 v26, s[2:3], v25, v25, v31
	v_rcp_f32_e32 v27, v26
	s_nop 0
	v_fma_f32 v32, -v26, v27, 1.0
	v_fmac_f32_e32 v27, v32, v27
	v_div_scale_f32 v32, vcc, v31, v25, v31
	v_mul_f32_e32 v33, v32, v27
	v_fma_f32 v34, -v26, v33, v32
	v_fmac_f32_e32 v33, v34, v27
	v_fma_f32 v26, -v26, v33, v32
	v_div_fmas_f32 v26, v26, v27, v33
	v_div_fixup_f32 v47, v26, v25, v31
	v_div_scale_f32 v25, s[2:3], v24, v24, v30
	v_rcp_f32_e32 v26, v25
	v_pk_mul_f32 v[34:35], v[44:45], v[44:45]
	v_fma_f32 v27, -v25, v26, 1.0
	v_fmac_f32_e32 v26, v27, v26
	v_div_scale_f32 v27, vcc, v30, v24, v30
	v_mul_f32_e32 v31, v27, v26
	v_fma_f32 v32, -v25, v31, v27
	v_fmac_f32_e32 v31, v32, v26
	v_fma_f32 v25, -v25, v31, v27
	v_div_fmas_f32 v25, v25, v26, v31
	v_div_fixup_f32 v46, v25, v24, v30
	v_cvt_pk_bf16_f32 v24, v28, v29
	v_lshl_add_u64 v[28:29], s[94:95], 0, v[40:41]
	v_cvt_pk_bf16_f32 v25, v44, v45
	v_cvt_pk_bf16_f32 v26, v42, v43
	v_cvt_pk_bf16_f32 v27, v46, v47
	v_lshl_add_u64 v[28:29], v[28:29], 0, v[160:161]
	global_store_dwordx4 v[28:29], v[24:27], off
	v_pk_mul_f32 v[32:33], v[42:43], v[42:43]
	v_add_f32_e32 v34, v34, v36
	v_add_f32_e32 v34, v35, v34
	v_add_f32_e32 v32, v32, v34
	v_pk_mul_f32 v[30:31], v[46:47], v[46:47]
	v_add_f32_e32 v32, v33, v32
	v_add_f32_e32 v30, v30, v32
	v_add_f32_e32 v30, v31, v30
	s_waitcnt vmcnt(7)
; __device__ __forceinline__ unsigned pk2(float lo, float hi) { const f32x2 v = {lo, hi}; return __builtin_bit_cast(unsigned, __builtin_convertvector(v, bf16x2_t)); }
; __device__ __forceinline__ void unpack8(u32x4 w, float* f) { f[0] = bflo(w.x); f[1] = bfhi(w.x); f[2] = bflo(w.y); f[3] = bfhi(w.y); f[4] = bflo(w.z); f[5] = bfhi(w.z); f[6] = bflo(w.w); f[7] = bfhi(w.w); }
;     __device__ __forceinline__ void operator()(const f32x4 (&acc)[2][2][4][2], const Unit& u, int wr, int wc, int fr, int fq) const {
;     ...
;             for (int m = 0; m < 4; ++m) { const int rl = wr * 64 + fr + ai * HALF + m * 16; const size_t row = (size_t)u.pm * BM + rl; float part = 0.f;
; #pragma unroll
;                 for (int bj = 0; bj < 2; ++bj) { const int col = col0 + bj * HALF; const u32x4 yw = *(const u32x4*)(YG + row * 512 + col); float y[8], o[8]; unpack8(yw, y);
;                     const f32x4 v0 = acc[ai][bj][m][0], v1 = acc[ai][bj][m][1];
; #pragma unroll
;                     for (int j = 0; j < 4; ++j) { o[j] = y[j] / (1.0f + __expf(-v0[j])); o[4 + j] = y[4 + j] / (1.0f + __expf(-v1[j])); }
; #pragma unroll
;                     for (int j = 0; j < 8; ++j) part += o[j] * o[j];
;                     u32x4 w; w.x = pk2(o[0], o[1]); w.y = pk2(o[2], o[3]); w.z = pk2(o[4], o[5]); w.w = pk2(o[6], o[7]);
;                     *(u32x4*)(YC + row * D + col) = w; }
;                 part += __shfl_xor(part, 16); part += __shfl_xor(part, 32);
;                 if (fq == 0) (void)__hip_atomic_fetch_add(rss + rl, part, __ATOMIC_RELAXED, __HIP_MEMORY_SCOPE_WORKGROUP); }
	v_mov_b32_e32 v24, v240
	v_mov_b32_e32 v25, v241
	v_mov_b32_e32 v26, v242
	v_mov_b32_e32 v27, v243
	v_lshlrev_b32_e32 v38, 16, v24
	v_and_b32_e32 v24, 0xffff0000, v24
	v_div_scale_f32 v39, s[2:3], v21, v21, v24
	v_rcp_f32_e32 v40, v39
	s_nop 0
	v_fma_f32 v41, -v39, v40, 1.0
	v_fmac_f32_e32 v40, v41, v40
	v_div_scale_f32 v41, vcc, v24, v21, v24
	v_mul_f32_e32 v42, v41, v40
	v_fma_f32 v43, -v39, v42, v41
	v_fmac_f32_e32 v42, v43, v40
	v_fma_f32 v39, -v39, v42, v41
	v_div_fmas_f32 v39, v39, v40, v42
	v_div_fixup_f32 v21, v39, v21, v24
	v_div_scale_f32 v24, s[2:3], v20, v20, v38
	v_rcp_f32_e32 v39, v24
	s_nop 0
	v_fma_f32 v40, -v24, v39, 1.0
	v_fmac_f32_e32 v39, v40, v39
	v_div_scale_f32 v40, vcc, v38, v20, v38
	v_mul_f32_e32 v41, v40, v39
	v_fma_f32 v42, -v24, v41, v40
	v_fmac_f32_e32 v41, v42, v39
	v_fma_f32 v24, -v24, v41, v40
	v_div_fmas_f32 v24, v24, v39, v41
	v_div_fixup_f32 v20, v24, v20, v38
	v_lshlrev_b32_e32 v24, 16, v26
	v_and_b32_e32 v26, 0xffff0000, v26
	v_div_scale_f32 v38, s[2:3], v17, v17, v26
	v_rcp_f32_e32 v39, v38
	s_nop 0
	v_fma_f32 v40, -v38, v39, 1.0
	v_fmac_f32_e32 v39, v40, v39
	v_div_scale_f32 v40, vcc, v26, v17, v26
	v_mul_f32_e32 v41, v40, v39
	v_fma_f32 v42, -v38, v41, v40
	v_fmac_f32_e32 v41, v42, v39
	v_fma_f32 v38, -v38, v41, v40
	v_div_fmas_f32 v38, v38, v39, v41
	v_div_fixup_f32 v17, v38, v17, v26
	v_div_scale_f32 v26, s[2:3], v16, v16, v24
	v_rcp_f32_e32 v38, v26
	s_nop 0
	v_fma_f32 v39, -v26, v38, 1.0
	v_fmac_f32_e32 v38, v39, v38
	v_div_scale_f32 v39, vcc, v24, v16, v24
	v_mul_f32_e32 v40, v39, v38
	v_fma_f32 v41, -v26, v40, v39
	v_fmac_f32_e32 v40, v41, v38
	v_fma_f32 v26, -v26, v40, v39
	v_div_fmas_f32 v26, v26, v38, v40
	v_div_fixup_f32 v16, v26, v16, v24
	v_lshlrev_b32_e32 v24, 16, v25
	v_and_b32_e32 v25, 0xffff0000, v25
	v_div_scale_f32 v26, s[2:3], v23, v23, v25
	v_rcp_f32_e32 v38, v26
	s_nop 0
	v_fma_f32 v39, -v26, v38, 1.0
	v_fmac_f32_e32 v38, v39, v38
	v_div_scale_f32 v39, vcc, v25, v23, v25
	v_mul_f32_e32 v40, v39, v38
	v_fma_f32 v41, -v26, v40, v39
	v_fmac_f32_e32 v40, v41, v38
	v_fma_f32 v26, -v26, v40, v39
	v_div_fmas_f32 v26, v26, v38, v40
	v_div_fixup_f32 v23, v26, v23, v25
	v_div_scale_f32 v25, s[2:3], v22, v22, v24
	v_rcp_f32_e32 v26, v25
	s_nop 0
	v_fma_f32 v38, -v25, v26, 1.0
	v_fmac_f32_e32 v26, v38, v26
	v_div_scale_f32 v38, vcc, v24, v22, v24
	v_mul_f32_e32 v39, v38, v26
	v_fma_f32 v40, -v25, v39, v38
	v_fmac_f32_e32 v39, v40, v26
	v_fma_f32 v25, -v25, v39, v38
	v_div_fmas_f32 v25, v25, v26, v39
	v_div_fixup_f32 v22, v25, v22, v24
	v_and_b32_e32 v25, 0xffff0000, v27
	v_div_scale_f32 v26, s[2:3], v19, v19, v25
	v_lshlrev_b32_e32 v24, 16, v27
	v_rcp_f32_e32 v27, v26
	s_nop 0
	v_fma_f32 v38, -v26, v27, 1.0
	v_fmac_f32_e32 v27, v38, v27
	v_div_scale_f32 v38, vcc, v25, v19, v25
	v_mul_f32_e32 v39, v38, v27
	v_fma_f32 v40, -v26, v39, v38
	v_fmac_f32_e32 v39, v40, v27
	v_fma_f32 v26, -v26, v39, v38
	v_div_fmas_f32 v26, v26, v27, v39
	v_div_fixup_f32 v25, v26, v19, v25
	v_div_scale_f32 v19, s[2:3], v18, v18, v24
	v_rcp_f32_e32 v26, v19
	s_nop 0
	v_fma_f32 v27, -v19, v26, 1.0
	v_fmac_f32_e32 v26, v27, v26
	v_div_scale_f32 v27, vcc, v24, v18, v24
	v_mul_f32_e32 v38, v27, v26
	v_fma_f32 v39, -v19, v38, v27
	v_fmac_f32_e32 v38, v39, v26
	v_fma_f32 v19, -v19, v38, v27
	v_div_fmas_f32 v19, v19, v26, v38
	v_div_fixup_f32 v24, v19, v18, v24
	v_pk_mul_f32 v[18:19], v[20:21], v[20:21]
	v_pk_mul_f32 v[26:27], v[22:23], v[22:23]
	v_add_f32_e32 v18, v18, v30
	v_add_f32_e32 v18, v19, v18
	v_add_f32_e32 v18, v26, v18
	v_pk_mul_f32 v[38:39], v[16:17], v[16:17]
	v_add_f32_e32 v18, v27, v18
	v_add_f32_e32 v18, v38, v18
	v_pk_mul_f32 v[40:41], v[24:25], v[24:25]
	v_add_f32_e32 v18, v39, v18
	v_add_f32_e32 v18, v40, v18
	v_add_f32_e32 v26, v41, v18
	v_cvt_pk_bf16_f32 v18, v20, v21
	v_cvt_pk_bf16_f32 v20, v16, v17
	ds_bpermute_b32 v16, v186, v26
	v_cvt_pk_bf16_f32 v19, v22, v23
	v_cvt_pk_bf16_f32 v21, v24, v25
	global_store_dwordx4 v[28:29], v[18:21], off offset:256
	s_waitcnt lgkmcnt(0)
	v_add_f32_e32 v16, v26, v16
	ds_bpermute_b32 v17, v185, v16
	s_and_saveexec_b64 s[2:3], s[38:39]
	s_cbranch_execz .LBB0_71
	s_waitcnt lgkmcnt(0)
	v_add_f32_e32 v16, v16, v17
	ds_add_f32 v181, v16
.LBB0_71:
	s_or_b64 exec, exec, s[2:3]
	s_waitcnt lgkmcnt(0)
	v_lshl_add_u64 v[16:17], s[18:19], 0, v[154:155]
	v_lshlrev_b64 v[18:19], 10, v[16:17]
	v_lshlrev_b64 v[24:25], 12, v[16:17]
	v_lshl_add_u64 v[16:17], s[4:5], 0, v[18:19]
	v_lshl_add_u64 v[22:23], v[16:17], 0, v[160:161]
	v_mul_f32_e32 v12, 0xbfb8aa3b, v12
	v_mul_f32_e32 v13, 0xbfb8aa3b, v13
	v_exp_f32_e32 v12, v12
	v_exp_f32_e32 v13, v13
	v_mul_f32_e32 v8, 0xbfb8aa3b, v8
	v_mul_f32_e32 v9, 0xbfb8aa3b, v9
	v_exp_f32_e32 v8, v8
	v_pk_add_f32 v[12:13], v[12:13], 1.0 op_sel_hi:[1,0]
	v_exp_f32_e32 v9, v9
	v_mul_f32_e32 v4, 0xbfb8aa3b, v4
	v_mul_f32_e32 v5, 0xbfb8aa3b, v5
	v_exp_f32_e32 v4, v4
	v_pk_add_f32 v[8:9], v[8:9], 1.0 op_sel_hi:[1,0]
	v_exp_f32_e32 v5, v5
	v_mul_f32_e32 v0, 0xbfb8aa3b, v0
	v_mul_f32_e32 v1, 0xbfb8aa3b, v1
	v_exp_f32_e32 v0, v0
	v_pk_add_f32 v[4:5], v[4:5], 1.0 op_sel_hi:[1,0]
	v_exp_f32_e32 v1, v1
	v_mul_f32_e32 v6, 0xbfb8aa3b, v6
	v_mul_f32_e32 v7, 0xbfb8aa3b, v7
	v_exp_f32_e32 v6, v6
	v_pk_add_f32 v[0:1], v[0:1], 1.0 op_sel_hi:[1,0]
	v_exp_f32_e32 v7, v7
	v_mul_f32_e32 v2, 0xbfb8aa3b, v2
	v_mul_f32_e32 v3, 0xbfb8aa3b, v3
	v_exp_f32_e32 v2, v2
	v_pk_add_f32 v[6:7], v[6:7], 1.0 op_sel_hi:[1,0]
	v_exp_f32_e32 v3, v3
	s_waitcnt vmcnt(7)
; __device__ __forceinline__ unsigned pk2(float lo, float hi) { const f32x2 v = {lo, hi}; return __builtin_bit_cast(unsigned, __builtin_convertvector(v, bf16x2_t)); }
; __device__ __forceinline__ void unpack8(u32x4 w, float* f) { f[0] = bflo(w.x); f[1] = bfhi(w.x); f[2] = bflo(w.y); f[3] = bfhi(w.y); f[4] = bflo(w.z); f[5] = bfhi(w.z); f[6] = bflo(w.w); f[7] = bfhi(w.w); }
;     __device__ __forceinline__ void operator()(const f32x4 (&acc)[2][2][4][2], const Unit& u, int wr, int wc, int fr, int fq) const {
;     ...
;                 for (int bj = 0; bj < 2; ++bj) { const int col = col0 + bj * HALF; const u32x4 yw = *(const u32x4*)(YG + row * 512 + col); float y[8], o[8]; unpack8(yw, y);
;                     const f32x4 v0 = acc[ai][bj][m][0], v1 = acc[ai][bj][m][1];
; #pragma unroll
;                     for (int j = 0; j < 4; ++j) { o[j] = y[j] / (1.0f + __expf(-v0[j])); o[4 + j] = y[4 + j] / (1.0f + __expf(-v1[j])); }
; #pragma unroll
;                     for (int j = 0; j < 8; ++j) part += o[j] * o[j];
;                     u32x4 w; w.x = pk2(o[0], o[1]); w.y = pk2(o[2], o[3]); w.z = pk2(o[4], o[5]); w.w = pk2(o[6], o[7]);
;                     *(u32x4*)(YC + row * D + col) = w; }
	v_mov_b32_e32 v16, v244
	v_mov_b32_e32 v17, v245
	v_mov_b32_e32 v18, v246
	v_mov_b32_e32 v19, v247
	v_lshlrev_b32_e32 v20, 16, v16
	v_and_b32_e32 v16, 0xffff0000, v16
	v_div_scale_f32 v21, s[2:3], v13, v13, v16
	v_rcp_f32_e32 v26, v21
	v_pk_add_f32 v[2:3], v[2:3], 1.0 op_sel_hi:[1,0]
	v_fma_f32 v27, -v21, v26, 1.0
	v_fmac_f32_e32 v26, v27, v26
	v_div_scale_f32 v27, vcc, v16, v13, v16
	v_mul_f32_e32 v28, v27, v26
	v_fma_f32 v29, -v21, v28, v27
	v_fmac_f32_e32 v28, v29, v26
	v_fma_f32 v21, -v21, v28, v27
	v_div_fmas_f32 v21, v21, v26, v28
	v_div_fixup_f32 v13, v21, v13, v16
	v_div_scale_f32 v16, s[2:3], v12, v12, v20
	v_rcp_f32_e32 v21, v16
	s_nop 0
	v_fma_f32 v26, -v16, v21, 1.0
	v_fmac_f32_e32 v21, v26, v21
	v_div_scale_f32 v26, vcc, v20, v12, v20
	v_mul_f32_e32 v27, v26, v21
	v_fma_f32 v28, -v16, v27, v26
	v_fmac_f32_e32 v27, v28, v21
	v_fma_f32 v16, -v16, v27, v26
	v_div_fmas_f32 v16, v16, v21, v27
	v_div_fixup_f32 v12, v16, v12, v20
	v_lshlrev_b32_e32 v16, 16, v18
	v_and_b32_e32 v18, 0xffff0000, v18
	v_div_scale_f32 v20, s[2:3], v9, v9, v18
	v_rcp_f32_e32 v21, v20
	s_nop 0
	v_fma_f32 v26, -v20, v21, 1.0
	v_fmac_f32_e32 v21, v26, v21
	v_div_scale_f32 v26, vcc, v18, v9, v18
	v_mul_f32_e32 v27, v26, v21
	v_fma_f32 v28, -v20, v27, v26
	v_fmac_f32_e32 v27, v28, v21
	v_fma_f32 v20, -v20, v27, v26
	v_div_fmas_f32 v20, v20, v21, v27
	v_div_fixup_f32 v27, v20, v9, v18
	v_div_scale_f32 v9, s[2:3], v8, v8, v16
	v_rcp_f32_e32 v18, v9
	s_nop 0
	v_fma_f32 v20, -v9, v18, 1.0
	v_fmac_f32_e32 v18, v20, v18
	v_div_scale_f32 v20, vcc, v16, v8, v16
	v_mul_f32_e32 v21, v20, v18
	v_fma_f32 v26, -v9, v21, v20
	v_fmac_f32_e32 v21, v26, v18
	v_fma_f32 v9, -v9, v21, v20
	v_div_fmas_f32 v9, v9, v18, v21
	v_div_fixup_f32 v26, v9, v8, v16
	v_mul_f32_e32 v9, 0xbfb8aa3b, v10
	v_mul_f32_e32 v8, 0xbfb8aa3b, v14
	v_exp_f32_e32 v10, v9
	v_mul_f32_e32 v9, 0xbfb8aa3b, v15
	v_exp_f32_e32 v8, v8
	v_exp_f32_e32 v9, v9
	v_and_b32_e32 v15, 0xffff0000, v17
	v_lshlrev_b32_e32 v14, 16, v17
	v_pk_add_f32 v[8:9], v[8:9], 1.0 op_sel_hi:[1,0]
	s_nop 0
	v_div_scale_f32 v16, s[2:3], v9, v9, v15
	v_rcp_f32_e32 v17, v16
	s_nop 0
	v_fma_f32 v18, -v16, v17, 1.0
	v_fmac_f32_e32 v17, v18, v17
	v_div_scale_f32 v18, vcc, v15, v9, v15
	v_mul_f32_e32 v20, v18, v17
	v_fma_f32 v21, -v16, v20, v18
	v_fmac_f32_e32 v20, v21, v17
	v_fma_f32 v16, -v16, v20, v18
	v_div_fmas_f32 v16, v16, v17, v20
	v_div_fixup_f32 v29, v16, v9, v15
	v_div_scale_f32 v9, s[2:3], v8, v8, v14
	v_rcp_f32_e32 v15, v9
	v_pk_mul_f32 v[20:21], v[12:13], v[12:13]
	v_fma_f32 v16, -v9, v15, 1.0
	v_fmac_f32_e32 v15, v16, v15
	v_div_scale_f32 v16, vcc, v14, v8, v14
	v_mul_f32_e32 v17, v16, v15
	v_fma_f32 v18, -v9, v17, v16
	v_fmac_f32_e32 v17, v18, v15
	v_fma_f32 v9, -v9, v17, v16
	v_div_fmas_f32 v9, v9, v15, v17
	v_div_fixup_f32 v28, v9, v8, v14
	v_mul_f32_e32 v8, 0xbfb8aa3b, v11
	v_exp_f32_e32 v11, v8
	v_and_b32_e32 v15, 0xffff0000, v19
	v_lshlrev_b32_e32 v14, 16, v19
	v_add_f32_e32 v20, v20, v21
	v_pk_add_f32 v[8:9], v[10:11], 1.0 op_sel_hi:[1,0]
	s_nop 0
	v_div_scale_f32 v10, s[2:3], v9, v9, v15
	v_rcp_f32_e32 v11, v10
	s_nop 0
	v_fma_f32 v16, -v10, v11, 1.0
	v_fmac_f32_e32 v11, v16, v11
	v_div_scale_f32 v16, vcc, v15, v9, v15
	v_mul_f32_e32 v17, v16, v11
	v_fma_f32 v18, -v10, v17, v16
	v_fmac_f32_e32 v17, v18, v11
	v_fma_f32 v10, -v10, v17, v16
	v_div_fmas_f32 v10, v10, v11, v17
	v_div_fixup_f32 v31, v10, v9, v15
	v_div_scale_f32 v9, s[2:3], v8, v8, v14
	v_rcp_f32_e32 v10, v9
	v_pk_mul_f32 v[18:19], v[28:29], v[28:29]
	v_fma_f32 v11, -v9, v10, 1.0
	v_fmac_f32_e32 v10, v11, v10
	v_div_scale_f32 v11, vcc, v14, v8, v14
	v_mul_f32_e32 v15, v11, v10
	v_fma_f32 v16, -v9, v15, v11
	v_fmac_f32_e32 v15, v16, v10
	v_fma_f32 v9, -v9, v15, v11
	v_div_fmas_f32 v9, v9, v10, v15
	v_div_fixup_f32 v30, v9, v8, v14
	v_cvt_pk_bf16_f32 v8, v12, v13
	v_lshl_add_u64 v[12:13], s[94:95], 0, v[24:25]
	v_cvt_pk_bf16_f32 v9, v28, v29
	v_cvt_pk_bf16_f32 v10, v26, v27
	v_cvt_pk_bf16_f32 v11, v30, v31
	v_lshl_add_u64 v[12:13], v[12:13], 0, v[160:161]
	global_store_dwordx4 v[12:13], v[8:11], off
	v_pk_mul_f32 v[16:17], v[26:27], v[26:27]
	v_add_f32_e32 v18, v18, v20
	v_add_f32_e32 v18, v19, v18
	v_add_f32_e32 v16, v16, v18
	v_pk_mul_f32 v[14:15], v[30:31], v[30:31]
	v_add_f32_e32 v16, v17, v16
	v_add_f32_e32 v14, v14, v16
	v_add_f32_e32 v14, v15, v14
	s_waitcnt vmcnt(7)
; __device__ __forceinline__ unsigned pk2(float lo, float hi) { const f32x2 v = {lo, hi}; return __builtin_bit_cast(unsigned, __builtin_convertvector(v, bf16x2_t)); }
; __device__ __forceinline__ void unpack8(u32x4 w, float* f) { f[0] = bflo(w.x); f[1] = bfhi(w.x); f[2] = bflo(w.y); f[3] = bfhi(w.y); f[4] = bflo(w.z); f[5] = bfhi(w.z); f[6] = bflo(w.w); f[7] = bfhi(w.w); }
;     __device__ __forceinline__ void operator()(const f32x4 (&acc)[2][2][4][2], const Unit& u, int wr, int wc, int fr, int fq) const {
;     ...
;                 for (int bj = 0; bj < 2; ++bj) { const int col = col0 + bj * HALF; const u32x4 yw = *(const u32x4*)(YG + row * 512 + col); float y[8], o[8]; unpack8(yw, y);
;                     const f32x4 v0 = acc[ai][bj][m][0], v1 = acc[ai][bj][m][1];
; #pragma unroll
;                     for (int j = 0; j < 4; ++j) { o[j] = y[j] / (1.0f + __expf(-v0[j])); o[4 + j] = y[4 + j] / (1.0f + __expf(-v1[j])); }
; #pragma unroll
;                     for (int j = 0; j < 8; ++j) part += o[j] * o[j];
;                     u32x4 w; w.x = pk2(o[0], o[1]); w.y = pk2(o[2], o[3]); w.z = pk2(o[4], o[5]); w.w = pk2(o[6], o[7]);
;                     *(u32x4*)(YC + row * D + col) = w; }
;                 part += __shfl_xor(part, 16); part += __shfl_xor(part, 32);
;                 if (fq == 0) (void)__hip_atomic_fetch_add(rss + rl, part, __ATOMIC_RELAXED, __HIP_MEMORY_SCOPE_WORKGROUP); }
	v_mov_b32_e32 v8, v248
	v_mov_b32_e32 v9, v249
	v_mov_b32_e32 v10, v250
	v_mov_b32_e32 v11, v251
	v_lshlrev_b32_e32 v22, 16, v8
	v_and_b32_e32 v8, 0xffff0000, v8
	v_div_scale_f32 v23, s[2:3], v5, v5, v8
	v_rcp_f32_e32 v24, v23
	s_nop 0
	v_fma_f32 v25, -v23, v24, 1.0
	v_fmac_f32_e32 v24, v25, v24
	v_div_scale_f32 v25, vcc, v8, v5, v8
	v_mul_f32_e32 v26, v25, v24
	v_fma_f32 v27, -v23, v26, v25
	v_fmac_f32_e32 v26, v27, v24
	v_fma_f32 v23, -v23, v26, v25
	v_div_fmas_f32 v23, v23, v24, v26
	v_div_fixup_f32 v5, v23, v5, v8
	v_div_scale_f32 v8, s[2:3], v4, v4, v22
	v_rcp_f32_e32 v23, v8
	s_nop 0
	v_fma_f32 v24, -v8, v23, 1.0
	v_fmac_f32_e32 v23, v24, v23
	v_div_scale_f32 v24, vcc, v22, v4, v22
	v_mul_f32_e32 v25, v24, v23
	v_fma_f32 v26, -v8, v25, v24
	v_fmac_f32_e32 v25, v26, v23
	v_fma_f32 v8, -v8, v25, v24
	v_div_fmas_f32 v8, v8, v23, v25
	v_div_fixup_f32 v4, v8, v4, v22
	v_lshlrev_b32_e32 v8, 16, v10
	v_and_b32_e32 v10, 0xffff0000, v10
	v_div_scale_f32 v22, s[2:3], v1, v1, v10
	v_rcp_f32_e32 v23, v22
	s_nop 0
	v_fma_f32 v24, -v22, v23, 1.0
	v_fmac_f32_e32 v23, v24, v23
	v_div_scale_f32 v24, vcc, v10, v1, v10
	v_mul_f32_e32 v25, v24, v23
	v_fma_f32 v26, -v22, v25, v24
	v_fmac_f32_e32 v25, v26, v23
	v_fma_f32 v22, -v22, v25, v24
	v_div_fmas_f32 v22, v22, v23, v25
	v_div_fixup_f32 v1, v22, v1, v10
	v_div_scale_f32 v10, s[2:3], v0, v0, v8
	v_rcp_f32_e32 v22, v10
	s_nop 0
	v_fma_f32 v23, -v10, v22, 1.0
	v_fmac_f32_e32 v22, v23, v22
	v_div_scale_f32 v23, vcc, v8, v0, v8
	v_mul_f32_e32 v24, v23, v22
	v_fma_f32 v25, -v10, v24, v23
	v_fmac_f32_e32 v24, v25, v22
	v_fma_f32 v10, -v10, v24, v23
	v_div_fmas_f32 v10, v10, v22, v24
	v_div_fixup_f32 v0, v10, v0, v8
	v_lshlrev_b32_e32 v8, 16, v9
	v_and_b32_e32 v9, 0xffff0000, v9
	v_div_scale_f32 v10, s[2:3], v7, v7, v9
	v_rcp_f32_e32 v22, v10
	s_nop 0
	v_fma_f32 v23, -v10, v22, 1.0
	v_fmac_f32_e32 v22, v23, v22
	v_div_scale_f32 v23, vcc, v9, v7, v9
	v_mul_f32_e32 v24, v23, v22
	v_fma_f32 v25, -v10, v24, v23
	v_fmac_f32_e32 v24, v25, v22
	v_fma_f32 v10, -v10, v24, v23
	v_div_fmas_f32 v10, v10, v22, v24
	v_div_fixup_f32 v7, v10, v7, v9
	v_div_scale_f32 v9, s[2:3], v6, v6, v8
	v_rcp_f32_e32 v10, v9
	s_nop 0
	v_fma_f32 v22, -v9, v10, 1.0
	v_fmac_f32_e32 v10, v22, v10
	v_div_scale_f32 v22, vcc, v8, v6, v8
	v_mul_f32_e32 v23, v22, v10
	v_fma_f32 v24, -v9, v23, v22
	v_fmac_f32_e32 v23, v24, v10
	v_fma_f32 v9, -v9, v23, v22
	v_div_fmas_f32 v9, v9, v10, v23
	v_div_fixup_f32 v6, v9, v6, v8
	v_and_b32_e32 v9, 0xffff0000, v11
	v_div_scale_f32 v10, s[2:3], v3, v3, v9
	v_lshlrev_b32_e32 v8, 16, v11
	v_rcp_f32_e32 v11, v10
	s_nop 0
	v_fma_f32 v22, -v10, v11, 1.0
	v_fmac_f32_e32 v11, v22, v11
	v_div_scale_f32 v22, vcc, v9, v3, v9
	v_mul_f32_e32 v23, v22, v11
	v_fma_f32 v24, -v10, v23, v22
	v_fmac_f32_e32 v23, v24, v11
	v_fma_f32 v10, -v10, v23, v22
	v_div_fmas_f32 v10, v10, v11, v23
	v_div_fixup_f32 v9, v10, v3, v9
	v_div_scale_f32 v3, s[2:3], v2, v2, v8
	v_rcp_f32_e32 v10, v3
	s_nop 0
	v_fma_f32 v11, -v3, v10, 1.0
	v_fmac_f32_e32 v10, v11, v10
	v_div_scale_f32 v11, vcc, v8, v2, v8
	v_mul_f32_e32 v22, v11, v10
	v_fma_f32 v23, -v3, v22, v11
	v_fmac_f32_e32 v22, v23, v10
	v_fma_f32 v3, -v3, v22, v11
	v_div_fmas_f32 v3, v3, v10, v22
	v_div_fixup_f32 v8, v3, v2, v8
	v_pk_mul_f32 v[2:3], v[4:5], v[4:5]
	v_pk_mul_f32 v[10:11], v[6:7], v[6:7]
	v_add_f32_e32 v2, v2, v14
	v_add_f32_e32 v2, v3, v2
	v_add_f32_e32 v2, v10, v2
	v_pk_mul_f32 v[22:23], v[0:1], v[0:1]
	v_add_f32_e32 v2, v11, v2
	v_add_f32_e32 v2, v22, v2
	v_pk_mul_f32 v[24:25], v[8:9], v[8:9]
	v_add_f32_e32 v2, v23, v2
	v_add_f32_e32 v2, v24, v2
	v_add_f32_e32 v10, v25, v2
	v_cvt_pk_bf16_f32 v2, v4, v5
	v_cvt_pk_bf16_f32 v4, v0, v1
	ds_bpermute_b32 v0, v186, v10
	v_cvt_pk_bf16_f32 v3, v6, v7
	v_cvt_pk_bf16_f32 v5, v8, v9
	global_store_dwordx4 v[12:13], v[2:5], off offset:256
	s_waitcnt lgkmcnt(0)
	v_add_f32_e32 v0, v10, v0
	ds_bpermute_b32 v1, v185, v0
	s_and_saveexec_b64 s[2:3], s[38:39]
	s_cbranch_execz .LBB0_73
	s_waitcnt lgkmcnt(0)
	v_add_f32_e32 v0, v0, v1
	ds_add_f32 v182, v0

; __device__ __forceinline__ void unpack8(u32x4 w, float* f) { f[0] = bflo(w.x); f[1] = bfhi(w.x); f[2] = bflo(w.y); f[3] = bfhi(w.y); f[4] = bflo(w.z); f[5] = bfhi(w.z); f[6] = bflo(w.w); f[7] = bfhi(w.w); }
; __device__ __forceinline__ const unsigned char* xrow(const XBuf& b, int row) { return (row < b.split ? b.p0 : b.p1) + (size_t)row * (b.f32 ? 8192 : 4096); }
; __device__ __forceinline__ void xload8(const XBuf& b, int row, int col, float* v) {
;     const unsigned char* r = xrow(b, row);
;     if (b.f32) { const f32x4 a0 = *(const f32x4*)(r + (size_t)col * 4), a1 = *(const f32x4*)(r + (size_t)col * 4 + 16);
; #pragma unroll
;         for (int j = 0; j < 4; ++j) { v[j] = a0[j]; v[4 + j] = a1[j]; } }
;     else unpack8(*(const u32x4*)(r + (size_t)col * 2), v);
;     __device__ __forceinline__ void operator()(const f32x4 (&acc)[2][2][4][2], const Unit& u, int wr, int wc, int fr, int fq) const {
;     ...
;         for (int ai = 0; ai < 2; ++ai) {
;             const int bi = batch_of(row0 + ai * HALF);
;             f32x4 gv[2][2];
; #pragma unroll
;             for (int bj = 0; bj < 2; ++bj)
; #pragma unroll
;                 for (int n = 0; n < 2; ++n) gv[bj][n] = *(const f32x4*)(gate + (size_t)bi * NMOD + col0 + bj * HALF + n * 4);
; #pragma unroll
;             for (int m = 0; m < 4; ++m) { const int row = row0 + ai * HALF + m * 16;
;                 float xv[2][8];
; #pragma unroll
;                 for (int bj = 0; bj < 2; ++bj) xload8(xin, row, col0 + bj * HALF, xv[bj]);
.LBB0_554:
	v_lshl_add_u32 v202, s38, 8, v176
	v_add_u32_e32 v129, 0xffff8000, v202
	v_lshrrev_b32_e32 v129, 6, v129
	v_ashrrev_i32_e32 v128, 14, v202
	v_add_u32_e32 v129, 2, v129
	v_cmp_gt_i32_e32 vcc, s81, v202
	v_lshl_or_b32 v198, s36, 8, v177
	v_ashrrev_i32_e32 v199, 31, v198
	v_cndmask_b32_e32 v130, v129, v128, vcc
	v_mov_b64_e32 v[128:129], s[10:11]
	v_mad_i64_i32 v[128:129], s[2:3], v130, s84, v[128:129]
	v_lshl_add_u64 v[132:133], v[198:199], 2, v[128:129]
	global_load_dwordx4 v[136:139], v[132:133], off offset:16
	global_load_dwordx4 v[140:143], v[132:133], off
	global_load_dwordx4 v[128:131], v[132:133], off offset:528
	s_nop 0
	global_load_dwordx4 v[132:135], v[132:133], off offset:512
	v_mov_b32_e32 v144, s48
	v_mov_b32_e32 v145, s46
	v_cmp_gt_i32_e32 vcc, s50, v202
	v_mov_b32_e32 v146, s47
	v_ashrrev_i32_e32 v203, 31, v202
	v_cndmask_b32_e32 v145, v144, v145, vcc
	v_mov_b32_e32 v144, s49
	v_cndmask_b32_e32 v144, v144, v146, vcc
	v_lshlrev_b64 v[146:147], s66, v[202:203]
	v_lshl_add_u64 v[204:205], v[144:145], 0, v[146:147]
	s_mov_b64 s[2:3], -1
	s_and_b64 vcc, exec, s[6:7]
	s_cbranch_vccz .LBB0_556
	s_lshl_b32 s96, 16, s66
	s_mov_b32 s97, 0
	v_lshl_add_u64 v[208:209], v[198:199], 1, v[204:205]
	global_load_dwordx4 v[220:223], v[208:209], off
	global_load_dwordx4 v[224:227], v[208:209], off offset:256
	v_lshl_add_u64 v[208:209], v[208:209], 0, s[96:97]
	global_load_dwordx4 v[228:231], v[208:209], off
	global_load_dwordx4 v[232:235], v[208:209], off offset:256
	v_lshl_add_u64 v[208:209], v[208:209], 0, s[96:97]
	global_load_dwordx4 v[236:239], v[208:209], off
	global_load_dwordx4 v[240:243], v[208:209], off offset:256
	v_lshl_add_u64 v[208:209], v[208:209], 0, s[96:97]
	global_load_dwordx4 v[244:247], v[208:209], off
	global_load_dwordx4 v[248:251], v[208:209], off offset:256
	s_mov_b64 s[2:3], 0
	s_waitcnt vmcnt(6)
	v_lshlrev_b32_e32 v144, 16, v220
	v_and_b32_e32 v145, 0xffff0000, v220
	v_lshlrev_b32_e32 v146, 16, v221
	v_and_b32_e32 v147, 0xffff0000, v221
	v_lshlrev_b32_e32 v148, 16, v222
	v_and_b32_e32 v149, 0xffff0000, v222
	v_lshlrev_b32_e32 v150, 16, v223
	v_and_b32_e32 v151, 0xffff0000, v223

; __device__ __forceinline__ void unpack8(u32x4 w, float* f) { f[0] = bflo(w.x); f[1] = bfhi(w.x); f[2] = bflo(w.y); f[3] = bfhi(w.y); f[4] = bflo(w.z); f[5] = bfhi(w.z); f[6] = bflo(w.w); f[7] = bfhi(w.w); }
; __device__ __forceinline__ const unsigned char* xrow(const XBuf& b, int row) { return (row < b.split ? b.p0 : b.p1) + (size_t)row * (b.f32 ? 8192 : 4096); }
; __device__ __forceinline__ void xload8(const XBuf& b, int row, int col, float* v) {
;     const unsigned char* r = xrow(b, row);
;     if (b.f32) { const f32x4 a0 = *(const f32x4*)(r + (size_t)col * 4), a1 = *(const f32x4*)(r + (size_t)col * 4 + 16);
; #pragma unroll
;         for (int j = 0; j < 4; ++j) { v[j] = a0[j]; v[4 + j] = a1[j]; } }
;     else unpack8(*(const u32x4*)(r + (size_t)col * 2), v);
;     __device__ __forceinline__ void operator()(const f32x4 (&acc)[2][2][4][2], const Unit& u, int wr, int wc, int fr, int fq) const {
;     ...
;                 float xv[2][8];
; #pragma unroll
;                 for (int bj = 0; bj < 2; ++bj) xload8(xin, row, col0 + bj * HALF, xv[bj]);
.LBB0_558:
	v_or_b32_e32 v200, 0x80, v198
	v_ashrrev_i32_e32 v201, 31, v200
	s_mov_b64 s[2:3], -1
	s_and_b64 vcc, exec, s[6:7]
	s_cbranch_vccz .LBB0_560
	s_mov_b64 s[2:3], 0
	s_waitcnt vmcnt(6)
	v_lshlrev_b32_e32 v152, 16, v224
	v_and_b32_e32 v153, 0xffff0000, v224
	v_lshlrev_b32_e32 v154, 16, v225
	v_and_b32_e32 v155, 0xffff0000, v225
	v_lshlrev_b32_e32 v156, 16, v226
	v_and_b32_e32 v157, 0xffff0000, v226
	v_lshlrev_b32_e32 v158, 16, v227
	v_and_b32_e32 v159, 0xffff0000, v227

; __device__ __forceinline__ unsigned pk2(float lo, float hi) { const f32x2 v = {lo, hi}; return __builtin_bit_cast(unsigned, __builtin_convertvector(v, bf16x2_t)); }
; __device__ __forceinline__ const unsigned char* xrow(const XBuf& b, int row) { return (row < b.split ? b.p0 : b.p1) + (size_t)row * (b.f32 ? 8192 : 4096); }
; __device__ __forceinline__ void xstore8(const XBuf& b, int row, int col, const float* v) {
;     unsigned char* r = (unsigned char*)xrow(b, row);
;     if (b.f32) { *(f32x4*)(r + (size_t)col * 4) = (f32x4){v[0], v[1], v[2], v[3]}; *(f32x4*)(r + (size_t)col * 4 + 16) = (f32x4){v[4], v[5], v[6], v[7]}; }
;     else { u32x4 w; w.x = pk2(v[0], v[1]); w.y = pk2(v[2], v[3]); w.z = pk2(v[4], v[5]); w.w = pk2(v[6], v[7]); *(u32x4*)(r + (size_t)col * 2) = w; }
;     __device__ __forceinline__ void operator()(const f32x4 (&acc)[2][2][4][2], const Unit& u, int wr, int wc, int fr, int fq) const {
;     ...
;                 for (int bj = 0; bj < 2; ++bj) { float o[8];
; #pragma unroll
;                     for (int j = 0; j < 4; ++j) { o[j] = xv[bj][j] + gv[bj][0][j] * acc[ai][bj][m][0][j]; o[4 + j] = xv[bj][4 + j] + gv[bj][1][j] * acc[ai][bj][m][1][j]; }
;                     xstore8(xout, row, col0 + bj * HALF, o); }
.LBB0_562:
	s_cmp_lg_u64 s[6:7], 0
	s_cbranch_scc1 .Lepi_res_j0
	s_waitcnt vmcnt(0)
.Lepi_res_j0:
	v_pk_fma_f32 v[124:125], v[124:125], v[140:141], v[144:145]
	v_mov_b32_e32 v144, s53
	v_mov_b32_e32 v145, s51
	v_cmp_gt_i32_e32 vcc, s54, v202
	v_pk_fma_f32 v[126:127], v[126:127], v[142:143], v[146:147]
	v_mov_b32_e32 v146, s52
	v_cndmask_b32_e32 v145, v144, v145, vcc
	v_mov_b32_e32 v144, s33
	v_cndmask_b32_e32 v144, v144, v146, vcc
	v_lshlrev_b64 v[146:147], s67, v[202:203]
	v_lshl_add_u64 v[144:145], v[144:145], 0, v[146:147]
	v_cndmask_b32_e64 v146, 0, 1, s[8:9]
	v_pk_fma_f32 v[120:121], v[120:121], v[136:137], v[148:149]
	v_pk_fma_f32 v[122:123], v[122:123], v[138:139], v[150:151]
	v_cmp_ne_u32_e64 s[4:5], 1, v146
	s_andn2_b64 vcc, exec, s[8:9]
	s_mov_b64 s[2:3], -1
	s_cbranch_vccnz .LBB0_564
	v_lshl_add_u64 v[146:147], v[198:199], 2, v[144:145]
	s_mov_b64 s[2:3], 0
	global_store_dwordx4 v[146:147], v[124:127], off
	global_store_dwordx4 v[146:147], v[120:123], off offset:16

; __device__ __forceinline__ void unpack8(u32x4 w, float* f) { f[0] = bflo(w.x); f[1] = bfhi(w.x); f[2] = bflo(w.y); f[3] = bfhi(w.y); f[4] = bflo(w.z); f[5] = bfhi(w.z); f[6] = bflo(w.w); f[7] = bfhi(w.w); }
; __device__ __forceinline__ const unsigned char* xrow(const XBuf& b, int row) { return (row < b.split ? b.p0 : b.p1) + (size_t)row * (b.f32 ? 8192 : 4096); }
; __device__ __forceinline__ void xload8(const XBuf& b, int row, int col, float* v) {
;     const unsigned char* r = xrow(b, row);
;     if (b.f32) { const f32x4 a0 = *(const f32x4*)(r + (size_t)col * 4), a1 = *(const f32x4*)(r + (size_t)col * 4 + 16);
; #pragma unroll
;         for (int j = 0; j < 4; ++j) { v[j] = a0[j]; v[4 + j] = a1[j]; } }
;     else unpack8(*(const u32x4*)(r + (size_t)col * 2), v);
;     __device__ __forceinline__ void operator()(const f32x4 (&acc)[2][2][4][2], const Unit& u, int wr, int wc, int fr, int fq) const {
;     ...
;             for (int m = 0; m < 4; ++m) { const int row = row0 + ai * HALF + m * 16;
;                 float xv[2][8];
; #pragma unroll
;                 for (int bj = 0; bj < 2; ++bj) xload8(xin, row, col0 + bj * HALF, xv[bj]);
.LBB0_570:
	v_or_b32_e32 v144, 16, v202
	v_mov_b32_e32 v112, s48
	v_mov_b32_e32 v113, s46
	v_cmp_gt_i32_e32 vcc, s50, v144
	v_mov_b32_e32 v114, s47
	v_ashrrev_i32_e32 v145, 31, v144
	v_cndmask_b32_e32 v113, v112, v113, vcc
	v_mov_b32_e32 v112, s49
	v_cndmask_b32_e32 v112, v112, v114, vcc
	v_lshlrev_b64 v[114:115], s66, v[144:145]
	v_lshl_add_u64 v[146:147], v[112:113], 0, v[114:115]
	s_mov_b64 s[2:3], -1
	s_and_b64 vcc, exec, s[6:7]
	s_cbranch_vccz .LBB0_572
	s_waitcnt vmcnt(6)
	v_lshlrev_b32_e32 v112, 16, v228
	v_and_b32_e32 v113, 0xffff0000, v228
	v_lshlrev_b32_e32 v114, 16, v229
	v_and_b32_e32 v115, 0xffff0000, v229
	v_lshlrev_b32_e32 v116, 16, v230
	v_and_b32_e32 v117, 0xffff0000, v230
	v_lshlrev_b32_e32 v118, 16, v231
	v_and_b32_e32 v119, 0xffff0000, v231
	s_cbranch_execnz .LBB0_574
	s_branch .LBB0_573

; __device__ __forceinline__ void unpack8(u32x4 w, float* f) { f[0] = bflo(w.x); f[1] = bfhi(w.x); f[2] = bflo(w.y); f[3] = bfhi(w.y); f[4] = bflo(w.z); f[5] = bfhi(w.z); f[6] = bflo(w.w); f[7] = bfhi(w.w); }
; __device__ __forceinline__ const unsigned char* xrow(const XBuf& b, int row) { return (row < b.split ? b.p0 : b.p1) + (size_t)row * (b.f32 ? 8192 : 4096); }
; __device__ __forceinline__ void xload8(const XBuf& b, int row, int col, float* v) {
;     const unsigned char* r = xrow(b, row);
;     if (b.f32) { const f32x4 a0 = *(const f32x4*)(r + (size_t)col * 4), a1 = *(const f32x4*)(r + (size_t)col * 4 + 16);
; #pragma unroll
;         for (int j = 0; j < 4; ++j) { v[j] = a0[j]; v[4 + j] = a1[j]; } }
;     else unpack8(*(const u32x4*)(r + (size_t)col * 2), v);
;     __device__ __forceinline__ void operator()(const f32x4 (&acc)[2][2][4][2], const Unit& u, int wr, int wc, int fr, int fq) const {
;     ...
;                 float xv[2][8];
; #pragma unroll
;                 for (int bj = 0; bj < 2; ++bj) xload8(xin, row, col0 + bj * HALF, xv[bj]);
.LBB0_574:
	s_mov_b64 s[2:3], -1
	s_and_b64 vcc, exec, s[6:7]
	s_cbranch_vccz .LBB0_576
	s_waitcnt vmcnt(6)
	v_lshlrev_b32_e32 v120, 16, v232
	v_and_b32_e32 v121, 0xffff0000, v232
	v_lshlrev_b32_e32 v122, 16, v233
	v_and_b32_e32 v123, 0xffff0000, v233
	v_lshlrev_b32_e32 v124, 16, v234
	v_and_b32_e32 v125, 0xffff0000, v234
	v_lshlrev_b32_e32 v126, 16, v235
	v_and_b32_e32 v127, 0xffff0000, v235
	s_cbranch_execz .LBB0_577
	s_branch .LBB0_578

; __device__ __forceinline__ unsigned pk2(float lo, float hi) { const f32x2 v = {lo, hi}; return __builtin_bit_cast(unsigned, __builtin_convertvector(v, bf16x2_t)); }
; __device__ __forceinline__ const unsigned char* xrow(const XBuf& b, int row) { return (row < b.split ? b.p0 : b.p1) + (size_t)row * (b.f32 ? 8192 : 4096); }
; __device__ __forceinline__ void xstore8(const XBuf& b, int row, int col, const float* v) {
;     unsigned char* r = (unsigned char*)xrow(b, row);
;     if (b.f32) { *(f32x4*)(r + (size_t)col * 4) = (f32x4){v[0], v[1], v[2], v[3]}; *(f32x4*)(r + (size_t)col * 4 + 16) = (f32x4){v[4], v[5], v[6], v[7]}; }
;     else { u32x4 w; w.x = pk2(v[0], v[1]); w.y = pk2(v[2], v[3]); w.z = pk2(v[4], v[5]); w.w = pk2(v[6], v[7]); *(u32x4*)(r + (size_t)col * 2) = w; }
;     __device__ __forceinline__ void operator()(const f32x4 (&acc)[2][2][4][2], const Unit& u, int wr, int wc, int fr, int fq) const {
;     ...
;                 for (int bj = 0; bj < 2; ++bj) { float o[8];
; #pragma unroll
;                     for (int j = 0; j < 4; ++j) { o[j] = xv[bj][j] + gv[bj][0][j] * acc[ai][bj][m][0][j]; o[4 + j] = xv[bj][4 + j] + gv[bj][1][j] * acc[ai][bj][m][1][j]; }
;                     xstore8(xout, row, col0 + bj * HALF, o); }
.Lepi_res_j1:
	v_pk_fma_f32 v[108:109], v[108:109], v[140:141], v[112:113]
	v_mov_b32_e32 v112, s53
	v_mov_b32_e32 v113, s51
	v_cmp_gt_i32_e32 vcc, s54, v144
	v_pk_fma_f32 v[110:111], v[110:111], v[142:143], v[114:115]
	v_mov_b32_e32 v114, s52
	v_cndmask_b32_e32 v113, v112, v113, vcc
	v_mov_b32_e32 v112, s33
	v_cndmask_b32_e32 v112, v112, v114, vcc
	v_lshlrev_b64 v[114:115], s67, v[144:145]
	v_pk_fma_f32 v[104:105], v[104:105], v[136:137], v[116:117]
	v_pk_fma_f32 v[106:107], v[106:107], v[138:139], v[118:119]
	v_lshl_add_u64 v[112:113], v[112:113], 0, v[114:115]
	s_and_b64 vcc, exec, s[4:5]
	s_mov_b64 s[2:3], -1
	s_cbranch_vccnz .LBB0_580
	v_lshl_add_u64 v[114:115], v[198:199], 2, v[112:113]
	s_mov_b64 s[2:3], 0
	global_store_dwordx4 v[114:115], v[108:111], off
	global_store_dwordx4 v[114:115], v[104:107], off offset:16

; __device__ __forceinline__ void unpack8(u32x4 w, float* f) { f[0] = bflo(w.x); f[1] = bfhi(w.x); f[2] = bflo(w.y); f[3] = bfhi(w.y); f[4] = bflo(w.z); f[5] = bfhi(w.z); f[6] = bflo(w.w); f[7] = bfhi(w.w); }
; __device__ __forceinline__ const unsigned char* xrow(const XBuf& b, int row) { return (row < b.split ? b.p0 : b.p1) + (size_t)row * (b.f32 ? 8192 : 4096); }
; __device__ __forceinline__ void xload8(const XBuf& b, int row, int col, float* v) {
;     const unsigned char* r = xrow(b, row);
;     if (b.f32) { const f32x4 a0 = *(const f32x4*)(r + (size_t)col * 4), a1 = *(const f32x4*)(r + (size_t)col * 4 + 16);
; #pragma unroll
;         for (int j = 0; j < 4; ++j) { v[j] = a0[j]; v[4 + j] = a1[j]; } }
;     else unpack8(*(const u32x4*)(r + (size_t)col * 2), v);
;     __device__ __forceinline__ void operator()(const f32x4 (&acc)[2][2][4][2], const Unit& u, int wr, int wc, int fr, int fq) const {
;     ...
;             for (int m = 0; m < 4; ++m) { const int row = row0 + ai * HALF + m * 16;
;                 float xv[2][8];
; #pragma unroll
;                 for (int bj = 0; bj < 2; ++bj) xload8(xin, row, col0 + bj * HALF, xv[bj]);
.LBB0_586:
	v_or_b32_e32 v112, 32, v202
	v_mov_b32_e32 v96, s48
	v_mov_b32_e32 v97, s46
	v_cmp_gt_i32_e32 vcc, s50, v112
	v_mov_b32_e32 v98, s47
	v_ashrrev_i32_e32 v113, 31, v112
	v_cndmask_b32_e32 v97, v96, v97, vcc
	v_mov_b32_e32 v96, s49
	v_cndmask_b32_e32 v96, v96, v98, vcc
	v_lshlrev_b64 v[98:99], s66, v[112:113]
	v_lshl_add_u64 v[114:115], v[96:97], 0, v[98:99]
	s_mov_b64 s[2:3], -1
	s_and_b64 vcc, exec, s[6:7]
	s_cbranch_vccz .LBB0_588
	s_waitcnt vmcnt(6)
	v_lshlrev_b32_e32 v96, 16, v236
	v_and_b32_e32 v97, 0xffff0000, v236
	v_lshlrev_b32_e32 v98, 16, v237
	v_and_b32_e32 v99, 0xffff0000, v237
	v_lshlrev_b32_e32 v100, 16, v238
	v_and_b32_e32 v101, 0xffff0000, v238
	v_lshlrev_b32_e32 v102, 16, v239
	v_and_b32_e32 v103, 0xffff0000, v239
	s_cbranch_execnz .LBB0_590
	s_branch .LBB0_589

; __device__ __forceinline__ void unpack8(u32x4 w, float* f) { f[0] = bflo(w.x); f[1] = bfhi(w.x); f[2] = bflo(w.y); f[3] = bfhi(w.y); f[4] = bflo(w.z); f[5] = bfhi(w.z); f[6] = bflo(w.w); f[7] = bfhi(w.w); }
; __device__ __forceinline__ const unsigned char* xrow(const XBuf& b, int row) { return (row < b.split ? b.p0 : b.p1) + (size_t)row * (b.f32 ? 8192 : 4096); }
; __device__ __forceinline__ void xload8(const XBuf& b, int row, int col, float* v) {
;     const unsigned char* r = xrow(b, row);
;     if (b.f32) { const f32x4 a0 = *(const f32x4*)(r + (size_t)col * 4), a1 = *(const f32x4*)(r + (size_t)col * 4 + 16);
; #pragma unroll
;         for (int j = 0; j < 4; ++j) { v[j] = a0[j]; v[4 + j] = a1[j]; } }
;     else unpack8(*(const u32x4*)(r + (size_t)col * 2), v);
;     __device__ __forceinline__ void operator()(const f32x4 (&acc)[2][2][4][2], const Unit& u, int wr, int wc, int fr, int fq) const {
;     ...
;                 float xv[2][8];
; #pragma unroll
;                 for (int bj = 0; bj < 2; ++bj) xload8(xin, row, col0 + bj * HALF, xv[bj]);
.LBB0_590:
	s_mov_b64 s[2:3], -1
	s_and_b64 vcc, exec, s[6:7]
	s_cbranch_vccz .LBB0_592
	s_waitcnt vmcnt(6)
	v_lshlrev_b32_e32 v104, 16, v240
	v_and_b32_e32 v105, 0xffff0000, v240
	v_lshlrev_b32_e32 v106, 16, v241
	v_and_b32_e32 v107, 0xffff0000, v241
	v_lshlrev_b32_e32 v108, 16, v242
	v_and_b32_e32 v109, 0xffff0000, v242
	v_lshlrev_b32_e32 v110, 16, v243
	v_and_b32_e32 v111, 0xffff0000, v243
	s_cbranch_execz .LBB0_593
	s_branch .LBB0_594

; __device__ __forceinline__ unsigned pk2(float lo, float hi) { const f32x2 v = {lo, hi}; return __builtin_bit_cast(unsigned, __builtin_convertvector(v, bf16x2_t)); }
; __device__ __forceinline__ const unsigned char* xrow(const XBuf& b, int row) { return (row < b.split ? b.p0 : b.p1) + (size_t)row * (b.f32 ? 8192 : 4096); }
; __device__ __forceinline__ void xstore8(const XBuf& b, int row, int col, const float* v) {
;     unsigned char* r = (unsigned char*)xrow(b, row);
;     if (b.f32) { *(f32x4*)(r + (size_t)col * 4) = (f32x4){v[0], v[1], v[2], v[3]}; *(f32x4*)(r + (size_t)col * 4 + 16) = (f32x4){v[4], v[5], v[6], v[7]}; }
;     else { u32x4 w; w.x = pk2(v[0], v[1]); w.y = pk2(v[2], v[3]); w.z = pk2(v[4], v[5]); w.w = pk2(v[6], v[7]); *(u32x4*)(r + (size_t)col * 2) = w; }
;     __device__ __forceinline__ void operator()(const f32x4 (&acc)[2][2][4][2], const Unit& u, int wr, int wc, int fr, int fq) const {
;     ...
;                 for (int bj = 0; bj < 2; ++bj) { float o[8];
; #pragma unroll
;                     for (int j = 0; j < 4; ++j) { o[j] = xv[bj][j] + gv[bj][0][j] * acc[ai][bj][m][0][j]; o[4 + j] = xv[bj][4 + j] + gv[bj][1][j] * acc[ai][bj][m][1][j]; }
;                     xstore8(xout, row, col0 + bj * HALF, o); }
.Lepi_res_j2:
	v_pk_fma_f32 v[92:93], v[92:93], v[140:141], v[96:97]
	v_mov_b32_e32 v96, s53
	v_mov_b32_e32 v97, s51
	v_cmp_gt_i32_e32 vcc, s54, v112
	v_pk_fma_f32 v[94:95], v[94:95], v[142:143], v[98:99]
	v_mov_b32_e32 v98, s52
	v_cndmask_b32_e32 v97, v96, v97, vcc
	v_mov_b32_e32 v96, s33
	v_cndmask_b32_e32 v96, v96, v98, vcc
	v_lshlrev_b64 v[98:99], s67, v[112:113]
	v_pk_fma_f32 v[88:89], v[88:89], v[136:137], v[100:101]
	v_pk_fma_f32 v[90:91], v[90:91], v[138:139], v[102:103]
	v_lshl_add_u64 v[96:97], v[96:97], 0, v[98:99]
	s_and_b64 vcc, exec, s[4:5]
	s_mov_b64 s[2:3], -1
	s_cbranch_vccnz .LBB0_596
	v_lshl_add_u64 v[98:99], v[198:199], 2, v[96:97]
	s_mov_b64 s[2:3], 0
	global_store_dwordx4 v[98:99], v[92:95], off
	global_store_dwordx4 v[98:99], v[88:91], off offset:16

; __device__ __forceinline__ void unpack8(u32x4 w, float* f) { f[0] = bflo(w.x); f[1] = bfhi(w.x); f[2] = bflo(w.y); f[3] = bfhi(w.y); f[4] = bflo(w.z); f[5] = bfhi(w.z); f[6] = bflo(w.w); f[7] = bfhi(w.w); }
; __device__ __forceinline__ const unsigned char* xrow(const XBuf& b, int row) { return (row < b.split ? b.p0 : b.p1) + (size_t)row * (b.f32 ? 8192 : 4096); }
; __device__ __forceinline__ void xload8(const XBuf& b, int row, int col, float* v) {
;     const unsigned char* r = xrow(b, row);
;     if (b.f32) { const f32x4 a0 = *(const f32x4*)(r + (size_t)col * 4), a1 = *(const f32x4*)(r + (size_t)col * 4 + 16);
; #pragma unroll
;         for (int j = 0; j < 4; ++j) { v[j] = a0[j]; v[4 + j] = a1[j]; } }
;     else unpack8(*(const u32x4*)(r + (size_t)col * 2), v);
;     __device__ __forceinline__ void operator()(const f32x4 (&acc)[2][2][4][2], const Unit& u, int wr, int wc, int fr, int fq) const {
;     ...
;             for (int m = 0; m < 4; ++m) { const int row = row0 + ai * HALF + m * 16;
;                 float xv[2][8];
; #pragma unroll
;                 for (int bj = 0; bj < 2; ++bj) xload8(xin, row, col0 + bj * HALF, xv[bj]);
.LBB0_602:
	v_or_b32_e32 v96, 48, v202
	v_mov_b32_e32 v80, s48
	v_mov_b32_e32 v81, s46
	v_cmp_gt_i32_e32 vcc, s50, v96
	v_mov_b32_e32 v82, s47
	v_ashrrev_i32_e32 v97, 31, v96
	v_cndmask_b32_e32 v81, v80, v81, vcc
	v_mov_b32_e32 v80, s49
	v_cndmask_b32_e32 v80, v80, v82, vcc
	v_lshlrev_b64 v[82:83], s66, v[96:97]
	v_lshl_add_u64 v[98:99], v[80:81], 0, v[82:83]
	s_mov_b64 s[2:3], -1
	s_and_b64 vcc, exec, s[6:7]
	s_cbranch_vccz .LBB0_604
	s_waitcnt vmcnt(6)
	v_lshlrev_b32_e32 v80, 16, v244
	v_and_b32_e32 v81, 0xffff0000, v244
	v_lshlrev_b32_e32 v82, 16, v245
	v_and_b32_e32 v83, 0xffff0000, v245
	v_lshlrev_b32_e32 v84, 16, v246
	v_and_b32_e32 v85, 0xffff0000, v246
	v_lshlrev_b32_e32 v86, 16, v247
	v_and_b32_e32 v87, 0xffff0000, v247
	s_cbranch_execnz .LBB0_606
	s_branch .LBB0_605

; __device__ __forceinline__ void unpack8(u32x4 w, float* f) { f[0] = bflo(w.x); f[1] = bfhi(w.x); f[2] = bflo(w.y); f[3] = bfhi(w.y); f[4] = bflo(w.z); f[5] = bfhi(w.z); f[6] = bflo(w.w); f[7] = bfhi(w.w); }
; __device__ __forceinline__ const unsigned char* xrow(const XBuf& b, int row) { return (row < b.split ? b.p0 : b.p1) + (size_t)row * (b.f32 ? 8192 : 4096); }
; __device__ __forceinline__ void xload8(const XBuf& b, int row, int col, float* v) {
;     const unsigned char* r = xrow(b, row);
;     if (b.f32) { const f32x4 a0 = *(const f32x4*)(r + (size_t)col * 4), a1 = *(const f32x4*)(r + (size_t)col * 4 + 16);
; #pragma unroll
;         for (int j = 0; j < 4; ++j) { v[j] = a0[j]; v[4 + j] = a1[j]; } }
;     else unpack8(*(const u32x4*)(r + (size_t)col * 2), v);
;     __device__ __forceinline__ void operator()(const f32x4 (&acc)[2][2][4][2], const Unit& u, int wr, int wc, int fr, int fq) const {
;     ...
;                 float xv[2][8];
; #pragma unroll
;                 for (int bj = 0; bj < 2; ++bj) xload8(xin, row, col0 + bj * HALF, xv[bj]);
.LBB0_606:
	s_mov_b64 s[2:3], -1
	s_and_b64 vcc, exec, s[6:7]
	s_cbranch_vccz .LBB0_608
	s_waitcnt vmcnt(6)
	v_lshlrev_b32_e32 v88, 16, v248
	v_and_b32_e32 v89, 0xffff0000, v248
	v_lshlrev_b32_e32 v90, 16, v249
	v_and_b32_e32 v91, 0xffff0000, v249
	v_lshlrev_b32_e32 v92, 16, v250
	v_and_b32_e32 v93, 0xffff0000, v250
	v_lshlrev_b32_e32 v94, 16, v251
	v_and_b32_e32 v95, 0xffff0000, v251
	s_cbranch_execz .LBB0_609
	s_branch .LBB0_610

; __device__ __forceinline__ unsigned pk2(float lo, float hi) { const f32x2 v = {lo, hi}; return __builtin_bit_cast(unsigned, __builtin_convertvector(v, bf16x2_t)); }
; __device__ __forceinline__ const unsigned char* xrow(const XBuf& b, int row) { return (row < b.split ? b.p0 : b.p1) + (size_t)row * (b.f32 ? 8192 : 4096); }
; __device__ __forceinline__ void xstore8(const XBuf& b, int row, int col, const float* v) {
;     unsigned char* r = (unsigned char*)xrow(b, row);
;     if (b.f32) { *(f32x4*)(r + (size_t)col * 4) = (f32x4){v[0], v[1], v[2], v[3]}; *(f32x4*)(r + (size_t)col * 4 + 16) = (f32x4){v[4], v[5], v[6], v[7]}; }
;     else { u32x4 w; w.x = pk2(v[0], v[1]); w.y = pk2(v[2], v[3]); w.z = pk2(v[4], v[5]); w.w = pk2(v[6], v[7]); *(u32x4*)(r + (size_t)col * 2) = w; }
;     __device__ __forceinline__ void operator()(const f32x4 (&acc)[2][2][4][2], const Unit& u, int wr, int wc, int fr, int fq) const {
;     ...
;                 for (int bj = 0; bj < 2; ++bj) { float o[8];
; #pragma unroll
;                     for (int j = 0; j < 4; ++j) { o[j] = xv[bj][j] + gv[bj][0][j] * acc[ai][bj][m][0][j]; o[4 + j] = xv[bj][4 + j] + gv[bj][1][j] * acc[ai][bj][m][1][j]; }
;                     xstore8(xout, row, col0 + bj * HALF, o); }
.Lepi_res_j3:
	v_pk_fma_f32 v[76:77], v[76:77], v[140:141], v[80:81]
	v_mov_b32_e32 v80, s53
	v_mov_b32_e32 v81, s51
	v_cmp_gt_i32_e32 vcc, s54, v96
	v_pk_fma_f32 v[78:79], v[78:79], v[142:143], v[82:83]
	v_mov_b32_e32 v82, s52
	v_cndmask_b32_e32 v81, v80, v81, vcc
	v_mov_b32_e32 v80, s33
	v_cndmask_b32_e32 v80, v80, v82, vcc
	v_lshlrev_b64 v[82:83], s67, v[96:97]
	v_pk_fma_f32 v[72:73], v[72:73], v[136:137], v[84:85]
	v_pk_fma_f32 v[74:75], v[74:75], v[138:139], v[86:87]
	v_lshl_add_u64 v[80:81], v[80:81], 0, v[82:83]
	s_and_b64 vcc, exec, s[4:5]
	s_mov_b64 s[2:3], -1
	s_cbranch_vccnz .LBB0_612
	v_lshl_add_u64 v[82:83], v[198:199], 2, v[80:81]
	s_mov_b64 s[2:3], 0
	global_store_dwordx4 v[82:83], v[76:79], off
	global_store_dwordx4 v[82:83], v[72:75], off offset:16

; __device__ __forceinline__ void unpack8(u32x4 w, float* f) { f[0] = bflo(w.x); f[1] = bfhi(w.x); f[2] = bflo(w.y); f[3] = bfhi(w.y); f[4] = bflo(w.z); f[5] = bfhi(w.z); f[6] = bflo(w.w); f[7] = bfhi(w.w); }
; __device__ __forceinline__ const unsigned char* xrow(const XBuf& b, int row) { return (row < b.split ? b.p0 : b.p1) + (size_t)row * (b.f32 ? 8192 : 4096); }
; __device__ __forceinline__ void xload8(const XBuf& b, int row, int col, float* v) {
;     const unsigned char* r = xrow(b, row);
;     if (b.f32) { const f32x4 a0 = *(const f32x4*)(r + (size_t)col * 4), a1 = *(const f32x4*)(r + (size_t)col * 4 + 16);
; #pragma unroll
;         for (int j = 0; j < 4; ++j) { v[j] = a0[j]; v[4 + j] = a1[j]; } }
;     else unpack8(*(const u32x4*)(r + (size_t)col * 2), v);
;     __device__ __forceinline__ void operator()(const f32x4 (&acc)[2][2][4][2], const Unit& u, int wr, int wc, int fr, int fq) const {
;     ...
;         for (int ai = 0; ai < 2; ++ai) {
;             const int bi = batch_of(row0 + ai * HALF);
;             f32x4 gv[2][2];
; #pragma unroll
;             for (int bj = 0; bj < 2; ++bj)
; #pragma unroll
;                 for (int n = 0; n < 2; ++n) gv[bj][n] = *(const f32x4*)(gate + (size_t)bi * NMOD + col0 + bj * HALF + n * 4);
; #pragma unroll
;             for (int m = 0; m < 4; ++m) { const int row = row0 + ai * HALF + m * 16;
;                 float xv[2][8];
; #pragma unroll
;                 for (int bj = 0; bj < 2; ++bj) xload8(xin, row, col0 + bj * HALF, xv[bj]);
.LBB0_618:
	v_add_u32_e32 v65, 0xffff8080, v202
	v_add_u32_e32 v96, 0x80, v202
	v_lshrrev_b32_e32 v65, 6, v65
	s_movk_i32 s2, 0x7f80
	v_ashrrev_i32_e32 v64, 14, v96
	v_add_u32_e32 v65, 2, v65
	v_cmp_gt_i32_e32 vcc, s2, v202
	v_mov_b32_e32 v80, s48
	v_mov_b32_e32 v81, s46
	v_cndmask_b32_e32 v66, v65, v64, vcc
	v_mov_b64_e32 v[64:65], s[10:11]
	v_mad_i64_i32 v[64:65], s[2:3], v66, s84, v[64:65]
	v_lshl_add_u64 v[68:69], v[198:199], 2, v[64:65]
	global_load_dwordx4 v[72:75], v[68:69], off offset:16
	global_load_dwordx4 v[76:79], v[68:69], off
	global_load_dwordx4 v[64:67], v[68:69], off offset:528
	s_nop 0
	global_load_dwordx4 v[68:71], v[68:69], off offset:512
	v_cmp_gt_i32_e32 vcc, s50, v96
	v_mov_b32_e32 v82, s47
	v_ashrrev_i32_e32 v97, 31, v96
	v_cndmask_b32_e32 v81, v80, v81, vcc
	v_mov_b32_e32 v80, s49
	v_cndmask_b32_e32 v80, v80, v82, vcc
	v_lshlrev_b64 v[82:83], s66, v[96:97]
	v_lshl_add_u64 v[98:99], v[80:81], 0, v[82:83]
	s_mov_b64 s[2:3], -1
	s_and_b64 vcc, exec, s[6:7]
	s_cbranch_vccz .LBB0_620
	s_lshl_b32 s96, 16, s66
	s_mov_b32 s97, 0
	v_lshl_add_u64 v[208:209], v[198:199], 1, v[98:99]
	global_load_dwordx4 v[220:223], v[208:209], off
	global_load_dwordx4 v[224:227], v[208:209], off offset:256
	v_lshl_add_u64 v[208:209], v[208:209], 0, s[96:97]
	global_load_dwordx4 v[228:231], v[208:209], off
	global_load_dwordx4 v[232:235], v[208:209], off offset:256
	v_lshl_add_u64 v[208:209], v[208:209], 0, s[96:97]
	global_load_dwordx4 v[236:239], v[208:209], off
	global_load_dwordx4 v[240:243], v[208:209], off offset:256
	v_lshl_add_u64 v[208:209], v[208:209], 0, s[96:97]
	global_load_dwordx4 v[244:247], v[208:209], off
	global_load_dwordx4 v[248:251], v[208:209], off offset:256
	s_waitcnt vmcnt(6)
	v_lshlrev_b32_e32 v80, 16, v220
	v_and_b32_e32 v81, 0xffff0000, v220
	v_lshlrev_b32_e32 v82, 16, v221
	v_and_b32_e32 v83, 0xffff0000, v221
	v_lshlrev_b32_e32 v84, 16, v222
	v_and_b32_e32 v85, 0xffff0000, v222
	v_lshlrev_b32_e32 v86, 16, v223
	v_and_b32_e32 v87, 0xffff0000, v223
	s_cbranch_execnz .LBB0_622
	s_branch .LBB0_621

; __device__ __forceinline__ void unpack8(u32x4 w, float* f) { f[0] = bflo(w.x); f[1] = bfhi(w.x); f[2] = bflo(w.y); f[3] = bfhi(w.y); f[4] = bflo(w.z); f[5] = bfhi(w.z); f[6] = bflo(w.w); f[7] = bfhi(w.w); }
; __device__ __forceinline__ const unsigned char* xrow(const XBuf& b, int row) { return (row < b.split ? b.p0 : b.p1) + (size_t)row * (b.f32 ? 8192 : 4096); }
; __device__ __forceinline__ void xload8(const XBuf& b, int row, int col, float* v) {
;     const unsigned char* r = xrow(b, row);
;     if (b.f32) { const f32x4 a0 = *(const f32x4*)(r + (size_t)col * 4), a1 = *(const f32x4*)(r + (size_t)col * 4 + 16);
; #pragma unroll
;         for (int j = 0; j < 4; ++j) { v[j] = a0[j]; v[4 + j] = a1[j]; } }
;     else unpack8(*(const u32x4*)(r + (size_t)col * 2), v);
;     __device__ __forceinline__ void operator()(const f32x4 (&acc)[2][2][4][2], const Unit& u, int wr, int wc, int fr, int fq) const {
;     ...
;                 float xv[2][8];
; #pragma unroll
;                 for (int bj = 0; bj < 2; ++bj) xload8(xin, row, col0 + bj * HALF, xv[bj]);
.LBB0_622:
	s_mov_b64 s[2:3], -1
	s_and_b64 vcc, exec, s[6:7]
	s_cbranch_vccz .LBB0_624
	s_waitcnt vmcnt(6)
	v_lshlrev_b32_e32 v88, 16, v224
	v_and_b32_e32 v89, 0xffff0000, v224
	v_lshlrev_b32_e32 v90, 16, v225
	v_and_b32_e32 v91, 0xffff0000, v225
	v_lshlrev_b32_e32 v92, 16, v226
	v_and_b32_e32 v93, 0xffff0000, v226
	v_lshlrev_b32_e32 v94, 16, v227
	v_and_b32_e32 v95, 0xffff0000, v227
	s_cbranch_execz .LBB0_625
	s_branch .LBB0_626

; __device__ __forceinline__ unsigned pk2(float lo, float hi) { const f32x2 v = {lo, hi}; return __builtin_bit_cast(unsigned, __builtin_convertvector(v, bf16x2_t)); }
; __device__ __forceinline__ const unsigned char* xrow(const XBuf& b, int row) { return (row < b.split ? b.p0 : b.p1) + (size_t)row * (b.f32 ? 8192 : 4096); }
; __device__ __forceinline__ void xstore8(const XBuf& b, int row, int col, const float* v) {
;     unsigned char* r = (unsigned char*)xrow(b, row);
;     if (b.f32) { *(f32x4*)(r + (size_t)col * 4) = (f32x4){v[0], v[1], v[2], v[3]}; *(f32x4*)(r + (size_t)col * 4 + 16) = (f32x4){v[4], v[5], v[6], v[7]}; }
;     else { u32x4 w; w.x = pk2(v[0], v[1]); w.y = pk2(v[2], v[3]); w.z = pk2(v[4], v[5]); w.w = pk2(v[6], v[7]); *(u32x4*)(r + (size_t)col * 2) = w; }
;     __device__ __forceinline__ void operator()(const f32x4 (&acc)[2][2][4][2], const Unit& u, int wr, int wc, int fr, int fq) const {
;     ...
;                 for (int bj = 0; bj < 2; ++bj) { float o[8];
; #pragma unroll
;                     for (int j = 0; j < 4; ++j) { o[j] = xv[bj][j] + gv[bj][0][j] * acc[ai][bj][m][0][j]; o[4 + j] = xv[bj][4 + j] + gv[bj][1][j] * acc[ai][bj][m][1][j]; }
;                     xstore8(xout, row, col0 + bj * HALF, o); }
.Lepi_res_j4:
	v_pk_fma_f32 v[60:61], v[60:61], v[76:77], v[80:81]
	v_mov_b32_e32 v80, s53
	v_mov_b32_e32 v81, s51
	v_cmp_gt_i32_e32 vcc, s54, v96
	v_pk_fma_f32 v[62:63], v[62:63], v[78:79], v[82:83]
	v_mov_b32_e32 v82, s52
	v_cndmask_b32_e32 v81, v80, v81, vcc
	v_mov_b32_e32 v80, s33
	v_cndmask_b32_e32 v80, v80, v82, vcc
	v_lshlrev_b64 v[82:83], s67, v[96:97]
	v_pk_fma_f32 v[56:57], v[56:57], v[72:73], v[84:85]
	v_pk_fma_f32 v[58:59], v[58:59], v[74:75], v[86:87]
	v_lshl_add_u64 v[80:81], v[80:81], 0, v[82:83]
	s_and_b64 vcc, exec, s[4:5]
	s_mov_b64 s[2:3], -1
	s_cbranch_vccnz .LBB0_628
	v_lshl_add_u64 v[82:83], v[198:199], 2, v[80:81]
	s_mov_b64 s[2:3], 0
	global_store_dwordx4 v[82:83], v[60:63], off
	global_store_dwordx4 v[82:83], v[56:59], off offset:16

; __device__ __forceinline__ void unpack8(u32x4 w, float* f) { f[0] = bflo(w.x); f[1] = bfhi(w.x); f[2] = bflo(w.y); f[3] = bfhi(w.y); f[4] = bflo(w.z); f[5] = bfhi(w.z); f[6] = bflo(w.w); f[7] = bfhi(w.w); }
; __device__ __forceinline__ const unsigned char* xrow(const XBuf& b, int row) { return (row < b.split ? b.p0 : b.p1) + (size_t)row * (b.f32 ? 8192 : 4096); }
; __device__ __forceinline__ void xload8(const XBuf& b, int row, int col, float* v) {
;     const unsigned char* r = xrow(b, row);
;     if (b.f32) { const f32x4 a0 = *(const f32x4*)(r + (size_t)col * 4), a1 = *(const f32x4*)(r + (size_t)col * 4 + 16);
; #pragma unroll
;         for (int j = 0; j < 4; ++j) { v[j] = a0[j]; v[4 + j] = a1[j]; } }
;     else unpack8(*(const u32x4*)(r + (size_t)col * 2), v);
;     __device__ __forceinline__ void operator()(const f32x4 (&acc)[2][2][4][2], const Unit& u, int wr, int wc, int fr, int fq) const {
;     ...
;             for (int m = 0; m < 4; ++m) { const int row = row0 + ai * HALF + m * 16;
;                 float xv[2][8];
; #pragma unroll
;                 for (int bj = 0; bj < 2; ++bj) xload8(xin, row, col0 + bj * HALF, xv[bj]);
.LBB0_634:
	v_add_u32_e32 v80, 0x90, v202
	v_mov_b32_e32 v48, s48
	v_mov_b32_e32 v49, s46
	v_cmp_gt_i32_e32 vcc, s50, v80
	v_mov_b32_e32 v50, s47
	v_ashrrev_i32_e32 v81, 31, v80
	v_cndmask_b32_e32 v49, v48, v49, vcc
	v_mov_b32_e32 v48, s49
	v_cndmask_b32_e32 v48, v48, v50, vcc
	v_lshlrev_b64 v[50:51], s66, v[80:81]
	v_lshl_add_u64 v[82:83], v[48:49], 0, v[50:51]
	s_mov_b64 s[2:3], -1
	s_and_b64 vcc, exec, s[6:7]
	s_cbranch_vccz .LBB0_636
	s_waitcnt vmcnt(6)
	v_lshlrev_b32_e32 v48, 16, v228
	v_and_b32_e32 v49, 0xffff0000, v228
	v_lshlrev_b32_e32 v50, 16, v229
	v_and_b32_e32 v51, 0xffff0000, v229
	v_lshlrev_b32_e32 v52, 16, v230
	v_and_b32_e32 v53, 0xffff0000, v230
	v_lshlrev_b32_e32 v54, 16, v231
	v_and_b32_e32 v55, 0xffff0000, v231
	s_cbranch_execnz .LBB0_638
	s_branch .LBB0_637

; __device__ __forceinline__ void unpack8(u32x4 w, float* f) { f[0] = bflo(w.x); f[1] = bfhi(w.x); f[2] = bflo(w.y); f[3] = bfhi(w.y); f[4] = bflo(w.z); f[5] = bfhi(w.z); f[6] = bflo(w.w); f[7] = bfhi(w.w); }
; __device__ __forceinline__ const unsigned char* xrow(const XBuf& b, int row) { return (row < b.split ? b.p0 : b.p1) + (size_t)row * (b.f32 ? 8192 : 4096); }
; __device__ __forceinline__ void xload8(const XBuf& b, int row, int col, float* v) {
;     const unsigned char* r = xrow(b, row);
;     if (b.f32) { const f32x4 a0 = *(const f32x4*)(r + (size_t)col * 4), a1 = *(const f32x4*)(r + (size_t)col * 4 + 16);
; #pragma unroll
;         for (int j = 0; j < 4; ++j) { v[j] = a0[j]; v[4 + j] = a1[j]; } }
;     else unpack8(*(const u32x4*)(r + (size_t)col * 2), v);
;     __device__ __forceinline__ void operator()(const f32x4 (&acc)[2][2][4][2], const Unit& u, int wr, int wc, int fr, int fq) const {
;     ...
;                 float xv[2][8];
; #pragma unroll
;                 for (int bj = 0; bj < 2; ++bj) xload8(xin, row, col0 + bj * HALF, xv[bj]);
.LBB0_638:
	s_mov_b64 s[2:3], -1
	s_and_b64 vcc, exec, s[6:7]
	s_cbranch_vccz .LBB0_640
	s_waitcnt vmcnt(6)
	v_lshlrev_b32_e32 v56, 16, v232
	v_and_b32_e32 v57, 0xffff0000, v232
	v_lshlrev_b32_e32 v58, 16, v233
	v_and_b32_e32 v59, 0xffff0000, v233
	v_lshlrev_b32_e32 v60, 16, v234
	v_and_b32_e32 v61, 0xffff0000, v234
	v_lshlrev_b32_e32 v62, 16, v235
	v_and_b32_e32 v63, 0xffff0000, v235
	s_cbranch_execz .LBB0_641
	s_branch .LBB0_642

; __device__ __forceinline__ unsigned pk2(float lo, float hi) { const f32x2 v = {lo, hi}; return __builtin_bit_cast(unsigned, __builtin_convertvector(v, bf16x2_t)); }
; __device__ __forceinline__ const unsigned char* xrow(const XBuf& b, int row) { return (row < b.split ? b.p0 : b.p1) + (size_t)row * (b.f32 ? 8192 : 4096); }
; __device__ __forceinline__ void xstore8(const XBuf& b, int row, int col, const float* v) {
;     unsigned char* r = (unsigned char*)xrow(b, row);
;     if (b.f32) { *(f32x4*)(r + (size_t)col * 4) = (f32x4){v[0], v[1], v[2], v[3]}; *(f32x4*)(r + (size_t)col * 4 + 16) = (f32x4){v[4], v[5], v[6], v[7]}; }
;     else { u32x4 w; w.x = pk2(v[0], v[1]); w.y = pk2(v[2], v[3]); w.z = pk2(v[4], v[5]); w.w = pk2(v[6], v[7]); *(u32x4*)(r + (size_t)col * 2) = w; }
;     __device__ __forceinline__ void operator()(const f32x4 (&acc)[2][2][4][2], const Unit& u, int wr, int wc, int fr, int fq) const {
;     ...
;                 for (int bj = 0; bj < 2; ++bj) { float o[8];
; #pragma unroll
;                     for (int j = 0; j < 4; ++j) { o[j] = xv[bj][j] + gv[bj][0][j] * acc[ai][bj][m][0][j]; o[4 + j] = xv[bj][4 + j] + gv[bj][1][j] * acc[ai][bj][m][1][j]; }
;                     xstore8(xout, row, col0 + bj * HALF, o); }
.Lepi_res_j5:
	v_pk_fma_f32 v[44:45], v[44:45], v[76:77], v[48:49]
	v_mov_b32_e32 v48, s53
	v_mov_b32_e32 v49, s51
	v_cmp_gt_i32_e32 vcc, s54, v80
	v_pk_fma_f32 v[46:47], v[46:47], v[78:79], v[50:51]
	v_mov_b32_e32 v50, s52
	v_cndmask_b32_e32 v49, v48, v49, vcc
	v_mov_b32_e32 v48, s33
	v_cndmask_b32_e32 v48, v48, v50, vcc
	v_lshlrev_b64 v[50:51], s67, v[80:81]
	v_pk_fma_f32 v[40:41], v[40:41], v[72:73], v[52:53]
	v_pk_fma_f32 v[42:43], v[42:43], v[74:75], v[54:55]
	v_lshl_add_u64 v[48:49], v[48:49], 0, v[50:51]
	s_and_b64 vcc, exec, s[4:5]
	s_mov_b64 s[2:3], -1
	s_cbranch_vccnz .LBB0_644
	v_lshl_add_u64 v[50:51], v[198:199], 2, v[48:49]
	s_mov_b64 s[2:3], 0
	global_store_dwordx4 v[50:51], v[44:47], off
	global_store_dwordx4 v[50:51], v[40:43], off offset:16

; __device__ __forceinline__ void unpack8(u32x4 w, float* f) { f[0] = bflo(w.x); f[1] = bfhi(w.x); f[2] = bflo(w.y); f[3] = bfhi(w.y); f[4] = bflo(w.z); f[5] = bfhi(w.z); f[6] = bflo(w.w); f[7] = bfhi(w.w); }
; __device__ __forceinline__ const unsigned char* xrow(const XBuf& b, int row) { return (row < b.split ? b.p0 : b.p1) + (size_t)row * (b.f32 ? 8192 : 4096); }
; __device__ __forceinline__ void xload8(const XBuf& b, int row, int col, float* v) {
;     const unsigned char* r = xrow(b, row);
;     if (b.f32) { const f32x4 a0 = *(const f32x4*)(r + (size_t)col * 4), a1 = *(const f32x4*)(r + (size_t)col * 4 + 16);
; #pragma unroll
;         for (int j = 0; j < 4; ++j) { v[j] = a0[j]; v[4 + j] = a1[j]; } }
;     else unpack8(*(const u32x4*)(r + (size_t)col * 2), v);
;     __device__ __forceinline__ void operator()(const f32x4 (&acc)[2][2][4][2], const Unit& u, int wr, int wc, int fr, int fq) const {
;     ...
;             for (int m = 0; m < 4; ++m) { const int row = row0 + ai * HALF + m * 16;
;                 float xv[2][8];
; #pragma unroll
;                 for (int bj = 0; bj < 2; ++bj) xload8(xin, row, col0 + bj * HALF, xv[bj]);
.LBB0_650:
	v_add_u32_e32 v48, 0xa0, v202
	v_mov_b32_e32 v32, s48
	v_mov_b32_e32 v33, s46
	v_cmp_gt_i32_e32 vcc, s50, v48
	v_mov_b32_e32 v34, s47
	v_ashrrev_i32_e32 v49, 31, v48
	v_cndmask_b32_e32 v33, v32, v33, vcc
	v_mov_b32_e32 v32, s49
	v_cndmask_b32_e32 v32, v32, v34, vcc
	v_lshlrev_b64 v[34:35], s66, v[48:49]
	v_lshl_add_u64 v[50:51], v[32:33], 0, v[34:35]
	s_mov_b64 s[2:3], -1
	s_and_b64 vcc, exec, s[6:7]
	s_cbranch_vccz .LBB0_652
	s_waitcnt vmcnt(6)
	v_lshlrev_b32_e32 v32, 16, v236
	v_and_b32_e32 v33, 0xffff0000, v236
	v_lshlrev_b32_e32 v34, 16, v237
	v_and_b32_e32 v35, 0xffff0000, v237
	v_lshlrev_b32_e32 v36, 16, v238
	v_and_b32_e32 v37, 0xffff0000, v238
	v_lshlrev_b32_e32 v38, 16, v239
	v_and_b32_e32 v39, 0xffff0000, v239
	s_cbranch_execnz .LBB0_654
	s_branch .LBB0_653

; __device__ __forceinline__ void unpack8(u32x4 w, float* f) { f[0] = bflo(w.x); f[1] = bfhi(w.x); f[2] = bflo(w.y); f[3] = bfhi(w.y); f[4] = bflo(w.z); f[5] = bfhi(w.z); f[6] = bflo(w.w); f[7] = bfhi(w.w); }
; __device__ __forceinline__ const unsigned char* xrow(const XBuf& b, int row) { return (row < b.split ? b.p0 : b.p1) + (size_t)row * (b.f32 ? 8192 : 4096); }
; __device__ __forceinline__ void xload8(const XBuf& b, int row, int col, float* v) {
;     const unsigned char* r = xrow(b, row);
;     if (b.f32) { const f32x4 a0 = *(const f32x4*)(r + (size_t)col * 4), a1 = *(const f32x4*)(r + (size_t)col * 4 + 16);
; #pragma unroll
;         for (int j = 0; j < 4; ++j) { v[j] = a0[j]; v[4 + j] = a1[j]; } }
;     else unpack8(*(const u32x4*)(r + (size_t)col * 2), v);
;     __device__ __forceinline__ void operator()(const f32x4 (&acc)[2][2][4][2], const Unit& u, int wr, int wc, int fr, int fq) const {
;     ...
;                 float xv[2][8];
; #pragma unroll
;                 for (int bj = 0; bj < 2; ++bj) xload8(xin, row, col0 + bj * HALF, xv[bj]);
.LBB0_654:
	s_mov_b64 s[2:3], -1
	s_and_b64 vcc, exec, s[6:7]
	s_cbranch_vccz .LBB0_656
	s_waitcnt vmcnt(6)
	v_lshlrev_b32_e32 v40, 16, v240
	v_and_b32_e32 v41, 0xffff0000, v240
	v_lshlrev_b32_e32 v42, 16, v241
	v_and_b32_e32 v43, 0xffff0000, v241
	v_lshlrev_b32_e32 v44, 16, v242
	v_and_b32_e32 v45, 0xffff0000, v242
	v_lshlrev_b32_e32 v46, 16, v243
	v_and_b32_e32 v47, 0xffff0000, v243
	s_cbranch_execz .LBB0_657
	s_branch .LBB0_658

; __device__ __forceinline__ unsigned pk2(float lo, float hi) { const f32x2 v = {lo, hi}; return __builtin_bit_cast(unsigned, __builtin_convertvector(v, bf16x2_t)); }
; __device__ __forceinline__ const unsigned char* xrow(const XBuf& b, int row) { return (row < b.split ? b.p0 : b.p1) + (size_t)row * (b.f32 ? 8192 : 4096); }
; __device__ __forceinline__ void xstore8(const XBuf& b, int row, int col, const float* v) {
;     unsigned char* r = (unsigned char*)xrow(b, row);
;     if (b.f32) { *(f32x4*)(r + (size_t)col * 4) = (f32x4){v[0], v[1], v[2], v[3]}; *(f32x4*)(r + (size_t)col * 4 + 16) = (f32x4){v[4], v[5], v[6], v[7]}; }
;     else { u32x4 w; w.x = pk2(v[0], v[1]); w.y = pk2(v[2], v[3]); w.z = pk2(v[4], v[5]); w.w = pk2(v[6], v[7]); *(u32x4*)(r + (size_t)col * 2) = w; }
;     __device__ __forceinline__ void operator()(const f32x4 (&acc)[2][2][4][2], const Unit& u, int wr, int wc, int fr, int fq) const {
;     ...
;                 for (int bj = 0; bj < 2; ++bj) { float o[8];
; #pragma unroll
;                     for (int j = 0; j < 4; ++j) { o[j] = xv[bj][j] + gv[bj][0][j] * acc[ai][bj][m][0][j]; o[4 + j] = xv[bj][4 + j] + gv[bj][1][j] * acc[ai][bj][m][1][j]; }
;                     xstore8(xout, row, col0 + bj * HALF, o); }
.Lepi_res_j6:
	v_pk_fma_f32 v[28:29], v[28:29], v[76:77], v[32:33]
	v_mov_b32_e32 v32, s53
	v_mov_b32_e32 v33, s51
	v_cmp_gt_i32_e32 vcc, s54, v48
	v_pk_fma_f32 v[30:31], v[30:31], v[78:79], v[34:35]
	v_mov_b32_e32 v34, s52
	v_cndmask_b32_e32 v33, v32, v33, vcc
	v_mov_b32_e32 v32, s33
	v_cndmask_b32_e32 v32, v32, v34, vcc
	v_lshlrev_b64 v[34:35], s67, v[48:49]
	v_pk_fma_f32 v[24:25], v[24:25], v[72:73], v[36:37]
	v_pk_fma_f32 v[26:27], v[26:27], v[74:75], v[38:39]
	v_lshl_add_u64 v[32:33], v[32:33], 0, v[34:35]
	s_and_b64 vcc, exec, s[4:5]
	s_mov_b64 s[2:3], -1
	s_cbranch_vccnz .LBB0_660
	v_lshl_add_u64 v[34:35], v[198:199], 2, v[32:33]
	s_mov_b64 s[2:3], 0
	global_store_dwordx4 v[34:35], v[28:31], off
	global_store_dwordx4 v[34:35], v[24:27], off offset:16

; __device__ __forceinline__ void unpack8(u32x4 w, float* f) { f[0] = bflo(w.x); f[1] = bfhi(w.x); f[2] = bflo(w.y); f[3] = bfhi(w.y); f[4] = bflo(w.z); f[5] = bfhi(w.z); f[6] = bflo(w.w); f[7] = bfhi(w.w); }
; __device__ __forceinline__ const unsigned char* xrow(const XBuf& b, int row) { return (row < b.split ? b.p0 : b.p1) + (size_t)row * (b.f32 ? 8192 : 4096); }
; __device__ __forceinline__ void xload8(const XBuf& b, int row, int col, float* v) {
;     const unsigned char* r = xrow(b, row);
;     if (b.f32) { const f32x4 a0 = *(const f32x4*)(r + (size_t)col * 4), a1 = *(const f32x4*)(r + (size_t)col * 4 + 16);
; #pragma unroll
;         for (int j = 0; j < 4; ++j) { v[j] = a0[j]; v[4 + j] = a1[j]; } }
;     else unpack8(*(const u32x4*)(r + (size_t)col * 2), v);
;     __device__ __forceinline__ void operator()(const f32x4 (&acc)[2][2][4][2], const Unit& u, int wr, int wc, int fr, int fq) const {
;     ...
;             for (int m = 0; m < 4; ++m) { const int row = row0 + ai * HALF + m * 16;
;                 float xv[2][8];
; #pragma unroll
;                 for (int bj = 0; bj < 2; ++bj) xload8(xin, row, col0 + bj * HALF, xv[bj]);
.LBB0_666:
	v_add_u32_e32 v32, 0xb0, v202
	v_mov_b32_e32 v16, s48
	v_mov_b32_e32 v17, s46
	v_cmp_gt_i32_e32 vcc, s50, v32
	v_mov_b32_e32 v18, s47
	v_ashrrev_i32_e32 v33, 31, v32
	v_cndmask_b32_e32 v17, v16, v17, vcc
	v_mov_b32_e32 v16, s49
	v_cndmask_b32_e32 v16, v16, v18, vcc
	v_lshlrev_b64 v[18:19], s66, v[32:33]
	v_lshl_add_u64 v[34:35], v[16:17], 0, v[18:19]
	s_mov_b64 s[2:3], -1
	s_and_b64 vcc, exec, s[6:7]
	s_cbranch_vccz .LBB0_668
	s_waitcnt vmcnt(6)
	v_lshlrev_b32_e32 v16, 16, v244
	v_and_b32_e32 v17, 0xffff0000, v244
	v_lshlrev_b32_e32 v18, 16, v245
	v_and_b32_e32 v19, 0xffff0000, v245
	v_lshlrev_b32_e32 v20, 16, v246
	v_and_b32_e32 v21, 0xffff0000, v246
	v_lshlrev_b32_e32 v22, 16, v247
	v_and_b32_e32 v23, 0xffff0000, v247
	s_cbranch_execnz .LBB0_670
	s_branch .LBB0_669

; __device__ __forceinline__ void unpack8(u32x4 w, float* f) { f[0] = bflo(w.x); f[1] = bfhi(w.x); f[2] = bflo(w.y); f[3] = bfhi(w.y); f[4] = bflo(w.z); f[5] = bfhi(w.z); f[6] = bflo(w.w); f[7] = bfhi(w.w); }
; __device__ __forceinline__ const unsigned char* xrow(const XBuf& b, int row) { return (row < b.split ? b.p0 : b.p1) + (size_t)row * (b.f32 ? 8192 : 4096); }
; __device__ __forceinline__ void xload8(const XBuf& b, int row, int col, float* v) {
;     const unsigned char* r = xrow(b, row);
;     if (b.f32) { const f32x4 a0 = *(const f32x4*)(r + (size_t)col * 4), a1 = *(const f32x4*)(r + (size_t)col * 4 + 16);
; #pragma unroll
;         for (int j = 0; j < 4; ++j) { v[j] = a0[j]; v[4 + j] = a1[j]; } }
;     else unpack8(*(const u32x4*)(r + (size_t)col * 2), v);
;     __device__ __forceinline__ void operator()(const f32x4 (&acc)[2][2][4][2], const Unit& u, int wr, int wc, int fr, int fq) const {
;     ...
;                 float xv[2][8];
; #pragma unroll
;                 for (int bj = 0; bj < 2; ++bj) xload8(xin, row, col0 + bj * HALF, xv[bj]);
.LBB0_670:
	s_mov_b64 s[2:3], -1
	s_and_b64 vcc, exec, s[6:7]
	s_cbranch_vccz .LBB0_672
	s_waitcnt vmcnt(6)
	v_lshlrev_b32_e32 v24, 16, v248
	v_and_b32_e32 v25, 0xffff0000, v248
	v_lshlrev_b32_e32 v26, 16, v249
	v_and_b32_e32 v27, 0xffff0000, v249
	v_lshlrev_b32_e32 v28, 16, v250
	v_and_b32_e32 v29, 0xffff0000, v250
	v_lshlrev_b32_e32 v30, 16, v251
	v_and_b32_e32 v31, 0xffff0000, v251
	s_cbranch_execz .LBB0_673
	s_branch .LBB0_674

; __device__ __forceinline__ unsigned pk2(float lo, float hi) { const f32x2 v = {lo, hi}; return __builtin_bit_cast(unsigned, __builtin_convertvector(v, bf16x2_t)); }
; __device__ __forceinline__ const unsigned char* xrow(const XBuf& b, int row) { return (row < b.split ? b.p0 : b.p1) + (size_t)row * (b.f32 ? 8192 : 4096); }
; __device__ __forceinline__ void xstore8(const XBuf& b, int row, int col, const float* v) {
;     unsigned char* r = (unsigned char*)xrow(b, row);
;     if (b.f32) { *(f32x4*)(r + (size_t)col * 4) = (f32x4){v[0], v[1], v[2], v[3]}; *(f32x4*)(r + (size_t)col * 4 + 16) = (f32x4){v[4], v[5], v[6], v[7]}; }
;     else { u32x4 w; w.x = pk2(v[0], v[1]); w.y = pk2(v[2], v[3]); w.z = pk2(v[4], v[5]); w.w = pk2(v[6], v[7]); *(u32x4*)(r + (size_t)col * 2) = w; }
;     __device__ __forceinline__ void operator()(const f32x4 (&acc)[2][2][4][2], const Unit& u, int wr, int wc, int fr, int fq) const {
;     ...
;                 for (int bj = 0; bj < 2; ++bj) { float o[8];
; #pragma unroll
;                     for (int j = 0; j < 4; ++j) { o[j] = xv[bj][j] + gv[bj][0][j] * acc[ai][bj][m][0][j]; o[4 + j] = xv[bj][4 + j] + gv[bj][1][j] * acc[ai][bj][m][1][j]; }
;                     xstore8(xout, row, col0 + bj * HALF, o); }
.Lepi_res_j7:
	v_pk_fma_f32 v[12:13], v[12:13], v[76:77], v[16:17]
	v_mov_b32_e32 v16, s53
	v_mov_b32_e32 v17, s51
	v_cmp_gt_i32_e32 vcc, s54, v32
	v_pk_fma_f32 v[14:15], v[14:15], v[78:79], v[18:19]
	v_mov_b32_e32 v18, s52
	v_cndmask_b32_e32 v17, v16, v17, vcc
	v_mov_b32_e32 v16, s33
	v_cndmask_b32_e32 v16, v16, v18, vcc
	v_lshlrev_b64 v[18:19], s67, v[32:33]
	v_pk_fma_f32 v[8:9], v[8:9], v[72:73], v[20:21]
	v_pk_fma_f32 v[10:11], v[10:11], v[74:75], v[22:23]
	v_lshl_add_u64 v[16:17], v[16:17], 0, v[18:19]
	s_and_b64 vcc, exec, s[4:5]
	s_mov_b64 s[2:3], -1
	s_cbranch_vccnz .LBB0_676
	v_lshl_add_u64 v[18:19], v[198:199], 2, v[16:17]
	s_mov_b64 s[2:3], 0
	global_store_dwordx4 v[18:19], v[12:15], off
	global_store_dwordx4 v[18:19], v[8:11], off offset:16
